# w2 unit: compress-bias rows read from an LDS copy (ds_read) instead of global loads that drained the H-row prefetch; vm/lgkm waits of the unit recomputed from register dependences; tasks B and C H row
# speedup vs baseline: 1.0019x; 1.0019x over previous
; #define LAS __attribute__((address_space(3)))
; DI bf16x8 pack8(f32x4 a, f32x4 b) { u32x4 p; p.x = pk2(a.x, a.y); p.y = pk2(a.z, a.w); p.z = pk2(b.x, b.y); p.w = pk2(b.z, b.w); return __builtin_bit_cast(bf16x8, p); }
; DI void w2_compute(const Args& a, LAS unsigned char* lds, int task, int lane, const u32x4 (&x0)[8], const u32x4 (&x1)[8]) {
;     ...
;     const float* cb = (const float*)(ws + WS_CBIAS) + kind * 256 + 8 * fq;
;     bf16x8 af[8];
; #pragma unroll
;     for (int ks = 0; ks < 8; ++ks) { const f32x4 c0 = *(const f32x4*)(cb + 32 * ks), c1 = *(const f32x4*)(cb + 32 * ks + 4);
;         f32x4 g0, g1;
;         g0.x = gelu_tanh(bf2f(x0[ks].x & 0xffffu) + bf2f(x1[ks].x & 0xffffu) + c0.x); g0.y = gelu_tanh(bf2f(x0[ks].x >> 16) + bf2f(x1[ks].x >> 16) + c0.y);
;         g0.z = gelu_tanh(bf2f(x0[ks].y & 0xffffu) + bf2f(x1[ks].y & 0xffffu) + c0.z); g0.w = gelu_tanh(bf2f(x0[ks].y >> 16) + bf2f(x1[ks].y >> 16) + c0.w);
;         g1.x = gelu_tanh(bf2f(x0[ks].z & 0xffffu) + bf2f(x1[ks].z & 0xffffu) + c1.x); g1.y = gelu_tanh(bf2f(x0[ks].z >> 16) + bf2f(x1[ks].z >> 16) + c1.y);
;         g1.z = gelu_tanh(bf2f(x0[ks].w & 0xffffu) + bf2f(x1[ks].w & 0xffffu) + c1.z); g1.w = gelu_tanh(bf2f(x0[ks].w >> 16) + bf2f(x1[ks].w >> 16) + c1.w);
;         af[ks] = pack8(g0, g1); }
;     const LAS unsigned char* wl = lds + W2_LDS + kind * 32768;
;     f32x4 acc[4];
; #pragma unroll
;     for (int nt = 0; nt < 4; ++nt) { acc[nt] = (f32x4){0.f, 0.f, 0.f, 0.f};
; #pragma unroll
;         for (int ks = 0; ks < 8; ++ks) { const bf16x8 wfr = *(const LAS bf16x8*)(wl + w2off(16 * (fr >> 2) + 4 * nt + (fr & 3), 4 * ks + fq)); acc[nt] = __builtin_amdgcn_mfma_f32_16x16x32_bf16(wfr, af[ks], acc[nt], 0, 0, 0); } }
; DI void w2_unit(const Args& a, LAS unsigned char* lds, int v, int wave, int lane) {
;     const int tid = wave * 64 + lane;
;     w2_stage(a, lds, tid);
;     const int t0 = 32 * v + 4 * wave;
.LBB0_1355:
	s_andn2_b64 vcc, exec, s[4:5]
	s_cbranch_vccnz .LBB0_1385
	v_and_b32_e32 v3, 3, v0
	v_lshlrev_b32_e32 v4, 2, v0
	v_and_or_b32 v3, v4, 48, v3
	v_bitop3_b32 v4, v3, v60, 19 bitop3:0x6c
	v_lshlrev_b32_e32 v115, 4, v4
	v_bitop3_b32 v4, v3, v63, 19 bitop3:0x6c
	v_lshlrev_b32_e32 v116, 4, v4
	v_bitop3_b32 v4, v3, v62, 19 bitop3:0x6c
	v_lshlrev_b32_e32 v117, 4, v4
	v_bitop3_b32 v4, v3, v61, 19 bitop3:0x6c
	v_lshlrev_b32_e32 v118, 4, v4
	v_bitop3_b32 v4, v3, v59, 19 bitop3:0x6c
	v_lshlrev_b32_e32 v119, 4, v4
	v_bitop3_b32 v4, v3, v58, 19 bitop3:0x6c
	v_lshlrev_b32_e32 v120, 4, v4
	v_bitop3_b32 v4, v3, v57, 19 bitop3:0x6c
	v_lshlrev_b32_e32 v121, 4, v4
	v_bitop3_b32 v4, v3, v64, 19 bitop3:0x6c
	v_lshlrev_b32_e32 v122, 4, v4
	v_or_b32_e32 v4, 4, v3
	v_bitop3_b32 v5, v4, v60, 23 bitop3:0x6c
	v_lshlrev_b32_e32 v124, 4, v5
	v_bitop3_b32 v5, v4, v63, 23 bitop3:0x6c
	v_lshlrev_b32_e32 v125, 4, v5
	v_bitop3_b32 v5, v4, v62, 23 bitop3:0x6c
	v_lshlrev_b32_e32 v126, 4, v5
	v_bitop3_b32 v5, v4, v61, 23 bitop3:0x6c
	v_lshlrev_b32_e32 v127, 4, v5
	v_bitop3_b32 v5, v4, v59, 23 bitop3:0x6c
	v_lshlrev_b32_e32 v128, 4, v5
	v_bitop3_b32 v5, v4, v58, 23 bitop3:0x6c
	v_lshlrev_b32_e32 v123, 9, v4
	v_lshlrev_b32_e32 v129, 4, v5
	v_bitop3_b32 v5, v4, v57, 23 bitop3:0x6c
	v_bitop3_b32 v4, v4, v64, 23 bitop3:0x6c
	v_lshlrev_b32_e32 v131, 4, v4
	v_or_b32_e32 v4, 8, v3
	v_lshlrev_b32_e32 v130, 4, v5
	v_bitop3_b32 v5, v4, v60, 27 bitop3:0x6c
	v_lshlrev_b32_e32 v133, 4, v5
	v_bitop3_b32 v5, v4, v63, 27 bitop3:0x6c
	v_lshlrev_b32_e32 v134, 4, v5
	v_bitop3_b32 v5, v4, v62, 27 bitop3:0x6c
	v_lshlrev_b32_e32 v135, 4, v5
	v_bitop3_b32 v5, v4, v61, 27 bitop3:0x6c
	v_lshlrev_b32_e32 v136, 4, v5
	v_bitop3_b32 v5, v4, v59, 27 bitop3:0x6c
	v_lshlrev_b32_e32 v137, 4, v5
	v_bitop3_b32 v5, v4, v58, 27 bitop3:0x6c
	v_lshlrev_b32_e32 v114, 9, v3
	v_lshlrev_b32_e32 v132, 9, v4
	v_lshlrev_b32_e32 v138, 4, v5
	v_bitop3_b32 v5, v4, v57, 27 bitop3:0x6c
	v_bitop3_b32 v4, v4, v64, 27 bitop3:0x6c
	v_or_b32_e32 v3, 12, v3
	v_lshlrev_b32_e32 v140, 4, v4
	v_bitop3_b32 v4, v3, v60, 31 bitop3:0x6c
	v_lshlrev_b32_e32 v142, 4, v4
	v_bitop3_b32 v4, v3, v63, 31 bitop3:0x6c
	v_lshlrev_b32_e32 v143, 4, v4
	v_bitop3_b32 v4, v3, v62, 31 bitop3:0x6c
	v_lshlrev_b32_e32 v144, 4, v4
	v_bitop3_b32 v4, v3, v61, 31 bitop3:0x6c
	v_lshlrev_b32_e32 v145, 4, v4
	v_bitop3_b32 v4, v3, v59, 31 bitop3:0x6c
	v_and_b32_e32 v2, 24, v159
	v_lshlrev_b32_e32 v146, 4, v4
	v_bitop3_b32 v4, v3, v58, 31 bitop3:0x6c
	v_mov_b32_e32 v103, 0
	v_lshlrev_b32_e32 v141, 9, v3
	v_lshlrev_b32_e32 v147, 4, v4
	v_bitop3_b32 v4, v3, v57, 31 bitop3:0x6c
	v_bitop3_b32 v3, v3, v64, 31 bitop3:0x6c
	v_lshlrev_b32_e32 v102, 1, v2
	s_add_u32 s28, s94, 0x232dc800
	v_lshlrev_b32_e32 v139, 4, v5
	v_lshlrev_b32_e32 v148, 4, v4
	v_lshlrev_b32_e32 v149, 4, v3
	v_and_b32_e32 v3, 48, v0
	v_lshl_add_u64 v[4:5], s[94:95], 0, v[102:103]
	s_mov_b64 s[4:5], 0x1f2dc800
	v_lshlrev_b32_e32 v102, 2, v56
	s_addc_u32 s29, s95, 0
	s_andn2_b32 s49, s49, 63
	v_lshl_add_u64 v[104:105], v[4:5], 0, s[4:5]
	v_lshl_add_u64 v[106:107], s[16:17], 0, v[102:103]
	v_mov_b32_e32 v186, v102
	v_lshlrev_b32_e32 v187, 2, v0
	global_load_dword v188, v187, s[16:17]
	s_waitcnt vmcnt(0)
	ds_write_b32 v187, v188 offset:32768
	s_waitcnt lgkmcnt(0)
	s_barrier
	v_lshlrev_b32_e32 v102, 1, v3
	v_or_b32_e32 v150, s49, v158
	s_movk_i32 s4, 0x1000
	v_lshlrev_b32_e32 v3, 3, v158
	v_cmp_ne_u32_e32 vcc, 15, v1
	v_lshl_add_u64 v[108:109], s[40:41], 0, v[102:103]
	v_cmp_gt_i32_e64 s[4:5], s4, v150
	v_cmp_eq_u32_e64 s[6:7], 0, v150
	s_lshl_b32 s30, s50, 2
	v_lshl_or_b32 v151, s50, 9, v3
	s_add_i32 s31, 0, 0x220c0
	s_add_i32 s34, 0, 0x10000
	s_movk_i32 s35, 0xdff
	v_mov_b32_e32 v152, 1
	v_mov_b32_e32 v153, 0xc0135761
	v_lshlrev_b32_e32 v110, 1, v2
	s_add_i32 s36, 0, 0x22040
	s_branch .LBB0_1359

; #define LAS __attribute__((address_space(3)))
; DI bf16x8 pack8(f32x4 a, f32x4 b) { u32x4 p; p.x = pk2(a.x, a.y); p.y = pk2(a.z, a.w); p.z = pk2(b.x, b.y); p.w = pk2(b.z, b.w); return __builtin_bit_cast(bf16x8, p); }
; DI void w2_load(const Args& a, int task, int lane, u32x4 (&x0)[8], u32x4 (&x1)[8]) {
;     ...
;     const int kind = task / (AROWS_S / 16), pr0 = (task % (AROWS_S / 16)) * 16;
;     const bf16_t* h0 = (const bf16_t*)(a.ws + WS_GH) + ((size_t)kind * AROWS_S + pr0 + fr) * 256 + 8 * fq;
;     const bool bnd = (task & 3) == 3 && fr == 15;
;     const int hb = ((pr0 + 16) >> 6) < 1023 ? ((pr0 + 16) >> 6) : 1023;
;     const bf16_t* h1 = (const bf16_t*)(a.ws + WS_GH) + (size_t)2 * AROWS_S * 256 + ((size_t)kind * 1024 + hb) * 256 + 8 * fq;
; #pragma unroll
;     for (int ks = 0; ks < 8; ++ks) { x0[ks] = *(const u32x4*)(h0 + 32 * ks); x1[ks] = bnd ? *(const u32x4*)(h1 + 32 * ks) : (u32x4){0u, 0u, 0u, 0u}; }
; }
; DI void w2_compute(const Args& a, LAS unsigned char* lds, int task, int lane, const u32x4 (&x0)[8], const u32x4 (&x1)[8]) {
;     unsigned char* ws = a.ws;
;     const int fr = lane & 15, fq = lane >> 4;
;     const int kind = task / (AROWS_S / 16), row0 = AROWS_P + (task % (AROWS_S / 16)) * 16;
;     const float* cb = (const float*)(ws + WS_CBIAS) + kind * 256 + 8 * fq;
;     bf16x8 af[8];
; #pragma unroll
;     for (int ks = 0; ks < 8; ++ks) { const f32x4 c0 = *(const f32x4*)(cb + 32 * ks), c1 = *(const f32x4*)(cb + 32 * ks + 4);
;         f32x4 g0, g1;
;         g0.x = gelu_tanh(bf2f(x0[ks].x & 0xffffu) + bf2f(x1[ks].x & 0xffffu) + c0.x); g0.y = gelu_tanh(bf2f(x0[ks].x >> 16) + bf2f(x1[ks].x >> 16) + c0.y);
;         g0.z = gelu_tanh(bf2f(x0[ks].y & 0xffffu) + bf2f(x1[ks].y & 0xffffu) + c0.z); g0.w = gelu_tanh(bf2f(x0[ks].y >> 16) + bf2f(x1[ks].y >> 16) + c0.w);
;         g1.x = gelu_tanh(bf2f(x0[ks].z & 0xffffu) + bf2f(x1[ks].z & 0xffffu) + c1.x); g1.y = gelu_tanh(bf2f(x0[ks].z >> 16) + bf2f(x1[ks].z >> 16) + c1.y);
;         g1.z = gelu_tanh(bf2f(x0[ks].w & 0xffffu) + bf2f(x1[ks].w & 0xffffu) + c1.z); g1.w = gelu_tanh(bf2f(x0[ks].w >> 16) + bf2f(x1[ks].w >> 16) + c1.w);
;         af[ks] = pack8(g0, g1); }
.LBB0_1366:
	s_waitcnt vmcnt(0) lgkmcnt(0)
	s_add_i32 s8, s38, 0xfffffe60
	s_ashr_i32 s9, s8, 31
	s_lshr_b32 s9, s9, 24
	s_add_i32 s9, s8, s9
	s_and_b32 s9, s9, 0x7ffff00
	s_sub_i32 s8, s8, s9
	s_lshl_b32 s12, s8, 5
	s_add_i32 s12, s12, s30
	s_ashr_i32 s8, s12, 31
	s_lshr_b32 s13, s8, 20
	s_add_i32 s8, s12, s13
	s_ashr_i32 s10, s8, 12
	s_and_b32 s8, s8, 0xffff000
	s_sub_i32 s8, s12, s8
	s_lshl_b32 s17, s8, 4
	s_ashr_i32 s11, s10, 31
	s_lshl_b64 s[8:9], s[10:11], 16
	s_ashr_i32 s11, s17, 31
	s_add_u32 s8, s8, s17
	s_addc_u32 s9, s9, s11
	v_mov_b32_e32 v3, s9
	v_or_b32_e32 v2, s8, v1
	v_lshlrev_b64 v[2:3], 9, v[2:3]
	v_lshl_add_u64 v[2:3], v[104:105], 0, v[2:3]
	global_load_dwordx4 v[6:9], v[2:3], off
	global_load_dwordx4 v[14:17], v[2:3], off offset:64
	s_or_b32 s9, s12, 1
	s_add_i32 s11, s9, s13
	s_ashr_i32 s8, s11, 12
	s_and_b32 s11, s11, 0xffff000
	s_sub_i32 s9, s9, s11
	s_lshl_b32 s16, s9, 4
	s_ashr_i32 s9, s8, 31
	s_lshl_b64 s[38:39], s[8:9], 16
	s_ashr_i32 s11, s16, 31
	s_add_u32 s9, s38, s16
	s_addc_u32 s11, s39, s11
	s_lshl_b32 s38, s10, 8
	s_ashr_i32 s39, s38, 31
	v_lshl_add_u64 v[38:39], s[38:39], 2, v[106:107]
	v_lshl_add_u32 v189, s38, 2, v186
	ds_read_b128 v[40:43], v189 offset:32768
	ds_read_b128 v[44:47], v189 offset:32784
	ds_read_b128 v[48:51], v189 offset:32896
	ds_read_b128 v[52:55], v189 offset:32912
	global_load_dwordx4 v[22:25], v[2:3], off offset:128
	global_load_dwordx4 v[30:33], v[2:3], off offset:192
	global_load_dwordx4 v[26:29], v[2:3], off offset:256
	global_load_dwordx4 v[18:21], v[2:3], off offset:320
	global_load_dwordx4 v[10:13], v[2:3], off offset:384
	s_nop 0
	global_load_dwordx4 v[2:5], v[2:3], off offset:448
	v_mov_b32_e32 v191, s11
	v_or_b32_e32 v190, s9, v1
	v_lshlrev_b64 v[190:191], 9, v[190:191]
	v_lshl_add_u64 v[190:191], v[104:105], 0, v[190:191]
	global_load_dwordx4 v[192:195], v[190:191], off
	global_load_dwordx4 v[196:199], v[190:191], off offset:64
	global_load_dwordx4 v[200:203], v[190:191], off offset:128
	global_load_dwordx4 v[204:207], v[190:191], off offset:192
	global_load_dwordx4 v[208:211], v[190:191], off offset:256
	global_load_dwordx4 v[212:215], v[190:191], off offset:320
	global_load_dwordx4 v[220:223], v[190:191], off offset:384
	global_load_dwordx4 v[224:227], v[190:191], off offset:448
	s_nop 0
	ds_read_b128 v[34:37], v189 offset:33040
	ds_read_b128 v[56:59], v189 offset:33024
	s_lshl_b32 s37, s10, 15
	s_add_i32 s37, s34, s37
	s_addk_i32 s17, 0x800
	s_waitcnt vmcnt(15)
	v_lshlrev_b32_e32 v60, 16, v6
	v_and_b32_e32 v61, 0xffff0000, v6
	v_lshlrev_b32_e32 v6, 16, v7
	v_and_b32_e32 v7, 0xffff0000, v7
	v_lshlrev_b32_e32 v62, 16, v8
	v_and_b32_e32 v63, 0xffff0000, v8
	v_pk_add_f32 v[60:61], v[60:61], 0 op_sel_hi:[1,0]
	v_lshlrev_b32_e32 v8, 16, v9
	v_and_b32_e32 v9, 0xffff0000, v9
	v_pk_add_f32 v[6:7], v[6:7], 0 op_sel_hi:[1,0]
	v_pk_add_f32 v[62:63], v[62:63], 0 op_sel_hi:[1,0]
	s_waitcnt lgkmcnt(5)
	v_pk_add_f32 v[40:41], v[60:61], v[40:41]
	v_pk_add_f32 v[8:9], v[8:9], 0 op_sel_hi:[1,0]
	v_pk_add_f32 v[6:7], v[6:7], v[42:43]
	s_waitcnt lgkmcnt(4)
	v_pk_add_f32 v[42:43], v[62:63], v[44:45]
	v_pk_mul_f32 v[44:45], v[40:41], v[40:41]
	s_waitcnt vmcnt(14)
	v_lshlrev_b32_e32 v64, 16, v14
	v_and_b32_e32 v65, 0xffff0000, v14
	v_pk_add_f32 v[8:9], v[8:9], v[46:47]
	v_pk_mul_f32 v[46:47], v[6:7], v[6:7]
	v_fmamk_f32 v14, v44, 0xbdd2d3e7, v153
	v_fmamk_f32 v44, v45, 0xbdd2d3e7, v153
	v_pk_mul_f32 v[60:61], v[42:43], v[42:43]
	v_fmamk_f32 v45, v46, 0xbdd2d3e7, v153
	v_fmamk_f32 v46, v47, 0xbdd2d3e7, v153
	v_mul_f32_e32 v14, v40, v14
	v_mul_f32_e32 v44, v41, v44
	v_pk_mul_f32 v[62:63], v[8:9], v[8:9]
	v_fmamk_f32 v47, v60, 0xbdd2d3e7, v153
	v_fmamk_f32 v60, v61, 0xbdd2d3e7, v153
	v_mul_f32_e32 v45, v6, v45
	v_mul_f32_e32 v46, v7, v46
	v_exp_f32_e32 v14, v14
	v_exp_f32_e32 v44, v44
	v_fmamk_f32 v61, v62, 0xbdd2d3e7, v153
	v_fmamk_f32 v62, v63, 0xbdd2d3e7, v153
	v_mul_f32_e32 v47, v42, v47
	v_mul_f32_e32 v60, v43, v60
	v_exp_f32_e32 v45, v45
	v_exp_f32_e32 v46, v46
	v_mul_f32_e32 v61, v8, v61
	v_mul_f32_e32 v62, v9, v62
	v_exp_f32_e32 v47, v47
	v_exp_f32_e32 v60, v60
	v_exp_f32_e32 v61, v61
	v_exp_f32_e32 v62, v62
	v_add_f32_e32 v14, 1.0, v14
	v_add_f32_e32 v63, 1.0, v44
	v_add_f32_e32 v66, 1.0, v45
	v_add_f32_e32 v67, 1.0, v46
	v_rcp_f32_e32 v44, v14
	v_rcp_f32_e32 v45, v63
	v_add_f32_e32 v68, 1.0, v47
	v_add_f32_e32 v69, 1.0, v60
	v_rcp_f32_e32 v46, v66
	v_rcp_f32_e32 v47, v67
	v_add_f32_e32 v70, 1.0, v61
	v_add_f32_e32 v71, 1.0, v62
	v_rcp_f32_e32 v60, v68
	v_rcp_f32_e32 v61, v69
	v_rcp_f32_e32 v62, v70
	v_rcp_f32_e32 v63, v71
	v_pk_mul_f32 v[40:41], v[40:41], v[44:45]
	v_pk_mul_f32 v[44:45], v[6:7], v[46:47]
	v_cvt_pk_bf16_f32 v6, v40, v41
	v_pk_add_f32 v[40:41], v[64:65], 0 op_sel_hi:[1,0]
	v_pk_mul_f32 v[42:43], v[42:43], v[60:61]
	s_waitcnt lgkmcnt(3)
	v_pk_add_f32 v[40:41], v[40:41], v[48:49]
	v_pk_mul_f32 v[46:47], v[8:9], v[62:63]
	v_cvt_pk_bf16_f32 v8, v42, v43
	v_pk_mul_f32 v[42:43], v[40:41], v[40:41]
	v_cvt_pk_bf16_f32 v7, v44, v45
	v_fmamk_f32 v9, v42, 0xbdd2d3e7, v153
	v_mul_f32_e32 v9, v40, v9
	v_exp_f32_e32 v14, v9
	v_fmamk_f32 v9, v43, 0xbdd2d3e7, v153
	v_mul_f32_e32 v9, v41, v9
	v_exp_f32_e32 v43, v9
	v_add_f32_e32 v14, 1.0, v14
	v_rcp_f32_e32 v42, v14
	v_cvt_pk_bf16_f32 v9, v46, v47
	v_add_f32_e32 v14, 1.0, v43
	v_rcp_f32_e32 v43, v14
	v_lshlrev_b32_e32 v14, 16, v15
	v_and_b32_e32 v15, 0xffff0000, v15
	v_pk_add_f32 v[14:15], v[14:15], 0 op_sel_hi:[1,0]
	v_pk_mul_f32 v[48:49], v[40:41], v[42:43]
	v_pk_add_f32 v[14:15], v[14:15], v[50:51]
	v_and_b32_e32 v41, 0xffff0000, v16
	v_pk_mul_f32 v[44:45], v[14:15], v[14:15]
	s_nop 0
	v_fmamk_f32 v44, v44, 0xbdd2d3e7, v153
	v_mul_f32_e32 v44, v14, v44
	v_exp_f32_e32 v44, v44
	v_fmamk_f32 v45, v45, 0xbdd2d3e7, v153
	v_mul_f32_e32 v45, v15, v45
	v_exp_f32_e32 v45, v45
	v_add_f32_e32 v40, 1.0, v44
	v_rcp_f32_e32 v50, v40
	v_lshlrev_b32_e32 v40, 16, v16
	v_pk_add_f32 v[40:41], v[40:41], 0 op_sel_hi:[1,0]
	v_add_f32_e32 v42, 1.0, v45
	s_waitcnt lgkmcnt(2)
; DI bf16x8 pack8(f32x4 a, f32x4 b) { u32x4 p; p.x = pk2(a.x, a.y); p.y = pk2(a.z, a.w); p.z = pk2(b.x, b.y); p.w = pk2(b.z, b.w); return __builtin_bit_cast(bf16x8, p); }
; DI void w2_compute(const Args& a, LAS unsigned char* lds, int task, int lane, const u32x4 (&x0)[8], const u32x4 (&x1)[8]) {
;     ...
;     for (int ks = 0; ks < 8; ++ks) { const f32x4 c0 = *(const f32x4*)(cb + 32 * ks), c1 = *(const f32x4*)(cb + 32 * ks + 4);
;         f32x4 g0, g1;
;         g0.x = gelu_tanh(bf2f(x0[ks].x & 0xffffu) + bf2f(x1[ks].x & 0xffffu) + c0.x); g0.y = gelu_tanh(bf2f(x0[ks].x >> 16) + bf2f(x1[ks].x >> 16) + c0.y);
;         g0.z = gelu_tanh(bf2f(x0[ks].y & 0xffffu) + bf2f(x1[ks].y & 0xffffu) + c0.z); g0.w = gelu_tanh(bf2f(x0[ks].y >> 16) + bf2f(x1[ks].y >> 16) + c0.w);
;         g1.x = gelu_tanh(bf2f(x0[ks].z & 0xffffu) + bf2f(x1[ks].z & 0xffffu) + c1.x); g1.y = gelu_tanh(bf2f(x0[ks].z >> 16) + bf2f(x1[ks].z >> 16) + c1.y);
;         g1.z = gelu_tanh(bf2f(x0[ks].w & 0xffffu) + bf2f(x1[ks].w & 0xffffu) + c1.z); g1.w = gelu_tanh(bf2f(x0[ks].w >> 16) + bf2f(x1[ks].w >> 16) + c1.w);
;         af[ks] = pack8(g0, g1); }
	v_pk_add_f32 v[52:53], v[40:41], v[52:53]
	v_rcp_f32_e32 v51, v42
	v_pk_mul_f32 v[40:41], v[52:53], v[52:53]
	v_pk_mul_f32 v[50:51], v[14:15], v[50:51]
	v_fmamk_f32 v16, v40, 0xbdd2d3e7, v153
	v_fmamk_f32 v40, v41, 0xbdd2d3e7, v153
	v_mul_f32_e32 v40, v53, v40
	v_exp_f32_e32 v40, v40
	v_and_b32_e32 v41, 0xffff0000, v17
	v_mul_f32_e32 v16, v52, v16
	v_exp_f32_e32 v16, v16
	v_add_f32_e32 v42, 1.0, v40
	v_lshlrev_b32_e32 v40, 16, v17
	v_pk_add_f32 v[40:41], v[40:41], 0 op_sel_hi:[1,0]
	v_add_f32_e32 v16, 1.0, v16
	v_pk_add_f32 v[54:55], v[40:41], v[54:55]
	v_rcp_f32_e32 v16, v16
	v_pk_mul_f32 v[40:41], v[54:55], v[54:55]
	v_cvt_pk_bf16_f32 v14, v48, v49
	v_fmamk_f32 v17, v40, 0xbdd2d3e7, v153
	v_mul_f32_e32 v17, v54, v17
	v_exp_f32_e32 v40, v17
	v_fmamk_f32 v17, v41, 0xbdd2d3e7, v153
	v_mul_f32_e32 v17, v55, v17
	v_exp_f32_e32 v41, v17
	v_add_f32_e32 v40, 1.0, v40
	v_rcp_f32_e32 v60, v40
	v_rcp_f32_e32 v17, v42
	v_add_f32_e32 v40, 1.0, v41
	v_rcp_f32_e32 v61, v40
	ds_read_b128 v[40:43], v189 offset:33168
	ds_read_b128 v[44:47], v189 offset:33152
	s_waitcnt vmcnt(13)
	v_lshlrev_b32_e32 v48, 16, v22
	v_and_b32_e32 v49, 0xffff0000, v22
	v_pk_add_f32 v[48:49], v[48:49], 0 op_sel_hi:[1,0]
	v_pk_mul_f32 v[16:17], v[52:53], v[16:17]
	s_waitcnt lgkmcnt(2)
	v_pk_add_f32 v[48:49], v[48:49], v[56:57]
	v_cvt_pk_bf16_f32 v15, v50, v51
	v_pk_mul_f32 v[50:51], v[48:49], v[48:49]
	v_cvt_pk_bf16_f32 v16, v16, v17
	v_fmamk_f32 v17, v50, 0xbdd2d3e7, v153
	v_mul_f32_e32 v17, v48, v17
	v_exp_f32_e32 v22, v17
	v_fmamk_f32 v17, v51, 0xbdd2d3e7, v153
	v_mul_f32_e32 v17, v49, v17
	v_exp_f32_e32 v51, v17
	v_add_f32_e32 v22, 1.0, v22
	v_rcp_f32_e32 v50, v22
	v_pk_mul_f32 v[52:53], v[54:55], v[60:61]
	v_add_f32_e32 v22, 1.0, v51
	v_rcp_f32_e32 v51, v22
	v_lshlrev_b32_e32 v22, 16, v23
	v_and_b32_e32 v23, 0xffff0000, v23
	v_pk_add_f32 v[22:23], v[22:23], 0 op_sel_hi:[1,0]
	v_cvt_pk_bf16_f32 v17, v52, v53
	v_pk_add_f32 v[22:23], v[22:23], v[58:59]
	s_nop 0
	v_pk_mul_f32 v[52:53], v[22:23], v[22:23]
	s_nop 0
	v_fmamk_f32 v52, v52, 0xbdd2d3e7, v153
	v_mul_f32_e32 v52, v22, v52
	v_exp_f32_e32 v54, v52
	v_fmamk_f32 v52, v53, 0xbdd2d3e7, v153
	v_mul_f32_e32 v52, v23, v52
	v_exp_f32_e32 v55, v52
	v_pk_mul_f32 v[52:53], v[48:49], v[50:51]
	v_add_f32_e32 v48, 1.0, v54
	v_rcp_f32_e32 v54, v48
	v_lshlrev_b32_e32 v48, 16, v24
	v_and_b32_e32 v49, 0xffff0000, v24
	v_pk_add_f32 v[48:49], v[48:49], 0 op_sel_hi:[1,0]
	v_add_f32_e32 v50, 1.0, v55
	v_pk_add_f32 v[56:57], v[48:49], v[34:35]
	v_rcp_f32_e32 v55, v50
	v_pk_mul_f32 v[34:35], v[56:57], v[56:57]
	v_pk_mul_f32 v[54:55], v[22:23], v[54:55]
	v_fmamk_f32 v24, v34, 0xbdd2d3e7, v153
	v_fmamk_f32 v34, v35, 0xbdd2d3e7, v153
	v_mul_f32_e32 v34, v57, v34
	v_exp_f32_e32 v34, v34
	v_and_b32_e32 v35, 0xffff0000, v25
	v_mul_f32_e32 v24, v56, v24
	v_exp_f32_e32 v24, v24
	v_add_f32_e32 v48, 1.0, v34
	v_lshlrev_b32_e32 v34, 16, v25
	v_pk_add_f32 v[34:35], v[34:35], 0 op_sel_hi:[1,0]
	v_add_f32_e32 v24, 1.0, v24
	v_pk_add_f32 v[58:59], v[34:35], v[36:37]
	v_rcp_f32_e32 v24, v24
	v_pk_mul_f32 v[34:35], v[58:59], v[58:59]
	v_cvt_pk_bf16_f32 v22, v52, v53
	v_fmamk_f32 v25, v34, 0xbdd2d3e7, v153
	v_mul_f32_e32 v25, v58, v25
	v_exp_f32_e32 v34, v25
	v_fmamk_f32 v25, v35, 0xbdd2d3e7, v153
	v_mul_f32_e32 v25, v59, v25
	v_exp_f32_e32 v35, v25
	v_add_f32_e32 v34, 1.0, v34
	v_rcp_f32_e32 v25, v48
	v_rcp_f32_e32 v60, v34
	v_add_f32_e32 v34, 1.0, v35
	v_rcp_f32_e32 v61, v34
	ds_read_b128 v[34:37], v189 offset:33296
	ds_read_b128 v[48:51], v189 offset:33280
	s_waitcnt vmcnt(12)
	v_lshlrev_b32_e32 v52, 16, v30
	v_and_b32_e32 v53, 0xffff0000, v30
	v_pk_add_f32 v[52:53], v[52:53], 0 op_sel_hi:[1,0]
	v_pk_mul_f32 v[24:25], v[56:57], v[24:25]
	v_cvt_pk_bf16_f32 v23, v54, v55
	v_cvt_pk_bf16_f32 v24, v24, v25
	s_waitcnt lgkmcnt(2)
	v_pk_add_f32 v[44:45], v[52:53], v[44:45]
	v_pk_mul_f32 v[56:57], v[58:59], v[60:61]
	v_pk_mul_f32 v[52:53], v[44:45], v[44:45]
	s_nop 0
	v_fmamk_f32 v25, v52, 0xbdd2d3e7, v153
	v_mul_f32_e32 v25, v44, v25
	v_exp_f32_e32 v30, v25
	v_fmamk_f32 v25, v53, 0xbdd2d3e7, v153
	v_mul_f32_e32 v25, v45, v25
	v_exp_f32_e32 v53, v25
	v_add_f32_e32 v30, 1.0, v30
	v_rcp_f32_e32 v52, v30
	v_cvt_pk_bf16_f32 v25, v56, v57
	v_add_f32_e32 v30, 1.0, v53
	v_rcp_f32_e32 v53, v30
	v_lshlrev_b32_e32 v30, 16, v31
	v_and_b32_e32 v31, 0xffff0000, v31
	v_pk_add_f32 v[30:31], v[30:31], 0 op_sel_hi:[1,0]
	v_pk_mul_f32 v[52:53], v[44:45], v[52:53]
	v_pk_add_f32 v[30:31], v[30:31], v[46:47]
	v_and_b32_e32 v45, 0xffff0000, v32
	v_pk_mul_f32 v[46:47], v[30:31], v[30:31]
	s_nop 0
	v_fmamk_f32 v46, v46, 0xbdd2d3e7, v153
	v_mul_f32_e32 v46, v30, v46
	v_exp_f32_e32 v46, v46
	v_fmamk_f32 v47, v47, 0xbdd2d3e7, v153
	v_mul_f32_e32 v47, v31, v47
	v_exp_f32_e32 v47, v47
	v_add_f32_e32 v44, 1.0, v46
	v_rcp_f32_e32 v54, v44
	v_lshlrev_b32_e32 v44, 16, v32
	v_pk_add_f32 v[44:45], v[44:45], 0 op_sel_hi:[1,0]
	v_add_f32_e32 v46, 1.0, v47
	v_pk_add_f32 v[56:57], v[44:45], v[40:41]
	v_rcp_f32_e32 v55, v46
	v_pk_mul_f32 v[40:41], v[56:57], v[56:57]
	v_pk_mul_f32 v[54:55], v[30:31], v[54:55]
	v_fmamk_f32 v32, v40, 0xbdd2d3e7, v153
	v_fmamk_f32 v40, v41, 0xbdd2d3e7, v153
	v_mul_f32_e32 v40, v57, v40
	v_exp_f32_e32 v40, v40
	v_and_b32_e32 v41, 0xffff0000, v33
	v_mul_f32_e32 v32, v56, v32
	v_exp_f32_e32 v32, v32
	v_add_f32_e32 v44, 1.0, v40
	v_lshlrev_b32_e32 v40, 16, v33
	v_pk_add_f32 v[40:41], v[40:41], 0 op_sel_hi:[1,0]
	v_add_f32_e32 v32, 1.0, v32
	v_pk_add_f32 v[58:59], v[40:41], v[42:43]
	v_rcp_f32_e32 v32, v32
	v_pk_mul_f32 v[40:41], v[58:59], v[58:59]
	v_cvt_pk_bf16_f32 v30, v52, v53
	v_fmamk_f32 v33, v40, 0xbdd2d3e7, v153
	v_mul_f32_e32 v33, v58, v33
	v_exp_f32_e32 v40, v33
	v_fmamk_f32 v33, v41, 0xbdd2d3e7, v153
	v_mul_f32_e32 v33, v59, v33
	v_exp_f32_e32 v41, v33
	v_add_f32_e32 v40, 1.0, v40
	v_rcp_f32_e32 v60, v40
	v_rcp_f32_e32 v33, v44
	v_add_f32_e32 v40, 1.0, v41
	v_rcp_f32_e32 v61, v40
	ds_read_b128 v[40:43], v189 offset:33424
	ds_read_b128 v[44:47], v189 offset:33408
	s_waitcnt vmcnt(11)
; DI bf16x8 pack8(f32x4 a, f32x4 b) { u32x4 p; p.x = pk2(a.x, a.y); p.y = pk2(a.z, a.w); p.z = pk2(b.x, b.y); p.w = pk2(b.z, b.w); return __builtin_bit_cast(bf16x8, p); }
; DI void w2_compute(const Args& a, LAS unsigned char* lds, int task, int lane, const u32x4 (&x0)[8], const u32x4 (&x1)[8]) {
;     ...
;     for (int ks = 0; ks < 8; ++ks) { const f32x4 c0 = *(const f32x4*)(cb + 32 * ks), c1 = *(const f32x4*)(cb + 32 * ks + 4);
;         f32x4 g0, g1;
;         g0.x = gelu_tanh(bf2f(x0[ks].x & 0xffffu) + bf2f(x1[ks].x & 0xffffu) + c0.x); g0.y = gelu_tanh(bf2f(x0[ks].x >> 16) + bf2f(x1[ks].x >> 16) + c0.y);
;         g0.z = gelu_tanh(bf2f(x0[ks].y & 0xffffu) + bf2f(x1[ks].y & 0xffffu) + c0.z); g0.w = gelu_tanh(bf2f(x0[ks].y >> 16) + bf2f(x1[ks].y >> 16) + c0.w);
;         g1.x = gelu_tanh(bf2f(x0[ks].z & 0xffffu) + bf2f(x1[ks].z & 0xffffu) + c1.x); g1.y = gelu_tanh(bf2f(x0[ks].z >> 16) + bf2f(x1[ks].z >> 16) + c1.y);
;         g1.z = gelu_tanh(bf2f(x0[ks].w & 0xffffu) + bf2f(x1[ks].w & 0xffffu) + c1.z); g1.w = gelu_tanh(bf2f(x0[ks].w >> 16) + bf2f(x1[ks].w >> 16) + c1.w);
;         af[ks] = pack8(g0, g1); }
	v_lshlrev_b32_e32 v52, 16, v26
	v_and_b32_e32 v53, 0xffff0000, v26
	v_pk_add_f32 v[52:53], v[52:53], 0 op_sel_hi:[1,0]
	v_pk_mul_f32 v[32:33], v[56:57], v[32:33]
	v_cvt_pk_bf16_f32 v31, v54, v55
	v_cvt_pk_bf16_f32 v32, v32, v33
	s_waitcnt lgkmcnt(2)
	v_pk_add_f32 v[48:49], v[52:53], v[48:49]
	v_pk_mul_f32 v[56:57], v[58:59], v[60:61]
	v_pk_mul_f32 v[52:53], v[48:49], v[48:49]
	s_nop 0
	v_fmamk_f32 v26, v52, 0xbdd2d3e7, v153
	v_mul_f32_e32 v26, v48, v26
	v_fmamk_f32 v33, v53, 0xbdd2d3e7, v153
	v_exp_f32_e32 v26, v26
	v_mul_f32_e32 v33, v49, v33
	v_exp_f32_e32 v53, v33
	v_cvt_pk_bf16_f32 v33, v56, v57
	v_add_f32_e32 v26, 1.0, v26
	v_rcp_f32_e32 v52, v26
	v_add_f32_e32 v26, 1.0, v53
	v_rcp_f32_e32 v53, v26
	v_lshlrev_b32_e32 v26, 16, v27
	v_and_b32_e32 v27, 0xffff0000, v27
	v_pk_add_f32 v[26:27], v[26:27], 0 op_sel_hi:[1,0]
	v_pk_mul_f32 v[52:53], v[48:49], v[52:53]
	v_pk_add_f32 v[26:27], v[26:27], v[50:51]
	v_and_b32_e32 v49, 0xffff0000, v28
	v_pk_mul_f32 v[50:51], v[26:27], v[26:27]
	s_nop 0
	v_fmamk_f32 v50, v50, 0xbdd2d3e7, v153
	v_mul_f32_e32 v50, v26, v50
	v_exp_f32_e32 v50, v50
	v_fmamk_f32 v51, v51, 0xbdd2d3e7, v153
	v_mul_f32_e32 v51, v27, v51
	v_exp_f32_e32 v51, v51
	v_add_f32_e32 v48, 1.0, v50
	v_rcp_f32_e32 v54, v48
	v_lshlrev_b32_e32 v48, 16, v28
	v_pk_add_f32 v[48:49], v[48:49], 0 op_sel_hi:[1,0]
	v_add_f32_e32 v50, 1.0, v51
	v_pk_add_f32 v[56:57], v[48:49], v[34:35]
	v_rcp_f32_e32 v55, v50
	v_pk_mul_f32 v[34:35], v[56:57], v[56:57]
	v_pk_mul_f32 v[54:55], v[26:27], v[54:55]
	v_fmamk_f32 v28, v34, 0xbdd2d3e7, v153
	v_fmamk_f32 v34, v35, 0xbdd2d3e7, v153
	v_mul_f32_e32 v34, v57, v34
	v_exp_f32_e32 v34, v34
	v_and_b32_e32 v35, 0xffff0000, v29
	v_mul_f32_e32 v28, v56, v28
	v_exp_f32_e32 v28, v28
	v_add_f32_e32 v48, 1.0, v34
	v_lshlrev_b32_e32 v34, 16, v29
	v_pk_add_f32 v[34:35], v[34:35], 0 op_sel_hi:[1,0]
	v_add_f32_e32 v28, 1.0, v28
	v_pk_add_f32 v[58:59], v[34:35], v[36:37]
	v_rcp_f32_e32 v28, v28
	v_pk_mul_f32 v[34:35], v[58:59], v[58:59]
	v_cvt_pk_bf16_f32 v26, v52, v53
	v_fmamk_f32 v29, v34, 0xbdd2d3e7, v153
	v_mul_f32_e32 v29, v58, v29
	v_exp_f32_e32 v34, v29
	v_fmamk_f32 v29, v35, 0xbdd2d3e7, v153
	v_mul_f32_e32 v29, v59, v29
	v_exp_f32_e32 v35, v29
	v_add_f32_e32 v34, 1.0, v34
	v_rcp_f32_e32 v60, v34
	v_rcp_f32_e32 v29, v48
	v_add_f32_e32 v34, 1.0, v35
	v_rcp_f32_e32 v61, v34
	ds_read_b128 v[34:37], v189 offset:33552
	ds_read_b128 v[48:51], v189 offset:33536
	s_waitcnt vmcnt(10)
	v_lshlrev_b32_e32 v52, 16, v18
	v_and_b32_e32 v53, 0xffff0000, v18
	v_pk_add_f32 v[52:53], v[52:53], 0 op_sel_hi:[1,0]
	v_pk_mul_f32 v[28:29], v[56:57], v[28:29]
	v_pk_mul_f32 v[56:57], v[58:59], v[60:61]
	v_cvt_pk_bf16_f32 v28, v28, v29
	s_waitcnt lgkmcnt(2)
	v_pk_add_f32 v[52:53], v[52:53], v[44:45]
	v_cvt_pk_bf16_f32 v27, v54, v55
	v_pk_mul_f32 v[44:45], v[52:53], v[52:53]
	s_nop 0
	v_fmamk_f32 v29, v45, 0xbdd2d3e7, v153
	v_mul_f32_e32 v29, v53, v29
	v_fmamk_f32 v18, v44, 0xbdd2d3e7, v153
	v_exp_f32_e32 v44, v29
	v_cvt_pk_bf16_f32 v29, v56, v57
	v_and_b32_e32 v45, 0xffff0000, v19
	v_mul_f32_e32 v18, v52, v18
	v_add_f32_e32 v56, 1.0, v44
	v_lshlrev_b32_e32 v44, 16, v19
	v_pk_add_f32 v[44:45], v[44:45], 0 op_sel_hi:[1,0]
	v_exp_f32_e32 v18, v18
	v_pk_add_f32 v[54:55], v[44:45], v[46:47]
	v_add_f32_e32 v18, 1.0, v18
	v_pk_mul_f32 v[44:45], v[54:55], v[54:55]
	v_rcp_f32_e32 v18, v18
	v_fmamk_f32 v19, v44, 0xbdd2d3e7, v153
	v_mul_f32_e32 v19, v54, v19
	v_exp_f32_e32 v44, v19
	v_fmamk_f32 v19, v45, 0xbdd2d3e7, v153
	v_mul_f32_e32 v19, v55, v19
	v_exp_f32_e32 v45, v19
	v_add_f32_e32 v44, 1.0, v44
	v_rcp_f32_e32 v19, v56
	v_rcp_f32_e32 v56, v44
	v_add_f32_e32 v46, 1.0, v45
	v_lshlrev_b32_e32 v44, 16, v20
	v_and_b32_e32 v45, 0xffff0000, v20
	v_pk_add_f32 v[44:45], v[44:45], 0 op_sel_hi:[1,0]
	v_rcp_f32_e32 v57, v46
	v_pk_add_f32 v[58:59], v[44:45], v[40:41]
	v_pk_mul_f32 v[18:19], v[52:53], v[18:19]
	v_pk_mul_f32 v[40:41], v[58:59], v[58:59]
	v_cvt_pk_bf16_f32 v18, v18, v19
	v_fmamk_f32 v20, v40, 0xbdd2d3e7, v153
	v_fmamk_f32 v40, v41, 0xbdd2d3e7, v153
	v_mul_f32_e32 v40, v59, v40
	v_exp_f32_e32 v40, v40
	v_and_b32_e32 v41, 0xffff0000, v21
	v_mul_f32_e32 v20, v58, v20
	v_exp_f32_e32 v20, v20
	v_add_f32_e32 v44, 1.0, v40
	v_lshlrev_b32_e32 v40, 16, v21
	v_pk_add_f32 v[40:41], v[40:41], 0 op_sel_hi:[1,0]
	v_add_f32_e32 v20, 1.0, v20
	v_pk_add_f32 v[60:61], v[40:41], v[42:43]
	v_rcp_f32_e32 v20, v20
	v_pk_mul_f32 v[40:41], v[60:61], v[60:61]
	s_nop 0
	v_fmamk_f32 v21, v40, 0xbdd2d3e7, v153
	v_mul_f32_e32 v21, v60, v21
	v_exp_f32_e32 v40, v21
	v_fmamk_f32 v21, v41, 0xbdd2d3e7, v153
	v_mul_f32_e32 v21, v61, v21
	v_exp_f32_e32 v41, v21
	v_add_f32_e32 v40, 1.0, v40
	v_rcp_f32_e32 v21, v44
	v_rcp_f32_e32 v62, v40
	v_add_f32_e32 v63, 1.0, v41
	ds_read_b128 v[40:43], v189 offset:33680
	ds_read_b128 v[44:47], v189 offset:33664
	v_pk_mul_f32 v[38:39], v[54:55], v[56:57]
	v_pk_mul_f32 v[20:21], v[58:59], v[20:21]
	v_cvt_pk_bf16_f32 v19, v38, v39
	s_waitcnt vmcnt(9)
	v_lshlrev_b32_e32 v38, 16, v10
	v_and_b32_e32 v39, 0xffff0000, v10
	v_pk_add_f32 v[38:39], v[38:39], 0 op_sel_hi:[1,0]
	v_cvt_pk_bf16_f32 v20, v20, v21
	v_rcp_f32_e32 v63, v63
	s_waitcnt lgkmcnt(2)
; #define LAS __attribute__((address_space(3)))
; DI bf16x8 pack8(f32x4 a, f32x4 b) { u32x4 p; p.x = pk2(a.x, a.y); p.y = pk2(a.z, a.w); p.z = pk2(b.x, b.y); p.w = pk2(b.z, b.w); return __builtin_bit_cast(bf16x8, p); }
; DI void w2_compute(const Args& a, LAS unsigned char* lds, int task, int lane, const u32x4 (&x0)[8], const u32x4 (&x1)[8]) {
;     ...
;     for (int ks = 0; ks < 8; ++ks) { const f32x4 c0 = *(const f32x4*)(cb + 32 * ks), c1 = *(const f32x4*)(cb + 32 * ks + 4);
;         f32x4 g0, g1;
;         g0.x = gelu_tanh(bf2f(x0[ks].x & 0xffffu) + bf2f(x1[ks].x & 0xffffu) + c0.x); g0.y = gelu_tanh(bf2f(x0[ks].x >> 16) + bf2f(x1[ks].x >> 16) + c0.y);
;         g0.z = gelu_tanh(bf2f(x0[ks].y & 0xffffu) + bf2f(x1[ks].y & 0xffffu) + c0.z); g0.w = gelu_tanh(bf2f(x0[ks].y >> 16) + bf2f(x1[ks].y >> 16) + c0.w);
;         g1.x = gelu_tanh(bf2f(x0[ks].z & 0xffffu) + bf2f(x1[ks].z & 0xffffu) + c1.x); g1.y = gelu_tanh(bf2f(x0[ks].z >> 16) + bf2f(x1[ks].z >> 16) + c1.y);
;         g1.z = gelu_tanh(bf2f(x0[ks].w & 0xffffu) + bf2f(x1[ks].w & 0xffffu) + c1.z); g1.w = gelu_tanh(bf2f(x0[ks].w >> 16) + bf2f(x1[ks].w >> 16) + c1.w);
;         af[ks] = pack8(g0, g1); }
;     const LAS unsigned char* wl = lds + W2_LDS + kind * 32768;
;     f32x4 acc[4];
; #pragma unroll
;     for (int nt = 0; nt < 4; ++nt) { acc[nt] = (f32x4){0.f, 0.f, 0.f, 0.f};
; #pragma unroll
;         for (int ks = 0; ks < 8; ++ks) { const bf16x8 wfr = *(const LAS bf16x8*)(wl + w2off(16 * (fr >> 2) + 4 * nt + (fr & 3), 4 * ks + fq)); acc[nt] = __builtin_amdgcn_mfma_f32_16x16x32_bf16(wfr, af[ks], acc[nt], 0, 0, 0); } }
	v_pk_add_f32 v[38:39], v[38:39], v[48:49]
	v_add_u32_e32 v56, s37, v114
	v_pk_mul_f32 v[48:49], v[38:39], v[38:39]
	v_pk_mul_f32 v[52:53], v[60:61], v[62:63]
	v_fmamk_f32 v21, v49, 0xbdd2d3e7, v153
	v_mul_f32_e32 v21, v39, v21
	v_fmamk_f32 v10, v48, 0xbdd2d3e7, v153
	v_exp_f32_e32 v48, v21
	v_cvt_pk_bf16_f32 v21, v52, v53
	v_and_b32_e32 v49, 0xffff0000, v11
	v_and_b32_e32 v53, 0xffff0000, v12
	v_add_f32_e32 v52, 1.0, v48
	v_lshlrev_b32_e32 v48, 16, v11
	v_pk_add_f32 v[48:49], v[48:49], 0 op_sel_hi:[1,0]
	v_mul_f32_e32 v10, v38, v10
	v_pk_add_f32 v[48:49], v[48:49], v[50:51]
	v_exp_f32_e32 v10, v10
	v_pk_mul_f32 v[50:51], v[48:49], v[48:49]
	v_add_f32_e32 v10, 1.0, v10
	v_fmamk_f32 v11, v50, 0xbdd2d3e7, v153
	v_mul_f32_e32 v11, v48, v11
	v_exp_f32_e32 v50, v11
	v_fmamk_f32 v11, v51, 0xbdd2d3e7, v153
	v_mul_f32_e32 v11, v49, v11
	v_exp_f32_e32 v51, v11
	v_rcp_f32_e32 v11, v52
	v_lshlrev_b32_e32 v52, 16, v12
	v_pk_add_f32 v[52:53], v[52:53], 0 op_sel_hi:[1,0]
	v_add_f32_e32 v50, 1.0, v50
	v_pk_add_f32 v[34:35], v[52:53], v[34:35]
	v_add_f32_e32 v51, 1.0, v51
	v_pk_mul_f32 v[52:53], v[34:35], v[34:35]
	v_rcp_f32_e32 v10, v10
	v_fmamk_f32 v12, v52, 0xbdd2d3e7, v153
	v_fmamk_f32 v52, v53, 0xbdd2d3e7, v153
	v_mul_f32_e32 v52, v35, v52
	v_exp_f32_e32 v52, v52
	v_and_b32_e32 v53, 0xffff0000, v13
	v_mul_f32_e32 v12, v34, v12
	v_exp_f32_e32 v12, v12
	v_add_f32_e32 v54, 1.0, v52
	v_lshlrev_b32_e32 v52, 16, v13
	v_pk_add_f32 v[52:53], v[52:53], 0 op_sel_hi:[1,0]
	v_add_f32_e32 v12, 1.0, v12
	v_pk_add_f32 v[36:37], v[52:53], v[36:37]
	v_rcp_f32_e32 v12, v12
	v_pk_mul_f32 v[52:53], v[36:37], v[36:37]
	v_rcp_f32_e32 v50, v50
	v_fmamk_f32 v13, v52, 0xbdd2d3e7, v153
	v_mul_f32_e32 v13, v36, v13
	v_exp_f32_e32 v52, v13
	v_fmamk_f32 v13, v53, 0xbdd2d3e7, v153
	v_mul_f32_e32 v13, v37, v13
	v_exp_f32_e32 v53, v13
	v_add_f32_e32 v52, 1.0, v52
	v_rcp_f32_e32 v13, v54
	v_rcp_f32_e32 v52, v52
	v_add_f32_e32 v53, 1.0, v53
	v_rcp_f32_e32 v53, v53
	v_rcp_f32_e32 v51, v51
	v_pk_mul_f32 v[12:13], v[34:35], v[12:13]
	v_pk_mul_f32 v[10:11], v[38:39], v[10:11]
	v_pk_mul_f32 v[34:35], v[36:37], v[52:53]
	s_waitcnt vmcnt(8)
	v_lshlrev_b32_e32 v36, 16, v2
	v_and_b32_e32 v37, 0xffff0000, v2
	v_pk_add_f32 v[36:37], v[36:37], 0 op_sel_hi:[1,0]
	v_pk_mul_f32 v[38:39], v[48:49], v[50:51]
	v_cvt_pk_bf16_f32 v10, v10, v11
	v_cvt_pk_bf16_f32 v11, v38, v39
	s_waitcnt lgkmcnt(0)
	v_pk_add_f32 v[36:37], v[36:37], v[44:45]
	v_cvt_pk_bf16_f32 v12, v12, v13
	v_pk_mul_f32 v[38:39], v[36:37], v[36:37]
	s_nop 0
	v_fmamk_f32 v2, v38, 0xbdd2d3e7, v153
	v_mul_f32_e32 v2, v36, v2
	v_fmamk_f32 v13, v39, 0xbdd2d3e7, v153
	v_exp_f32_e32 v2, v2
	v_mul_f32_e32 v13, v37, v13
	v_exp_f32_e32 v38, v13
	v_cvt_pk_bf16_f32 v13, v34, v35
	v_add_f32_e32 v2, 1.0, v2
	v_rcp_f32_e32 v34, v2
	v_add_f32_e32 v2, 1.0, v38
	v_rcp_f32_e32 v35, v2
	v_lshlrev_b32_e32 v2, 16, v3
	v_and_b32_e32 v3, 0xffff0000, v3
	v_pk_add_f32 v[2:3], v[2:3], 0 op_sel_hi:[1,0]
	s_nop 0
	v_pk_add_f32 v[44:45], v[2:3], v[46:47]
	v_pk_mul_f32 v[46:47], v[36:37], v[34:35]
	v_pk_mul_f32 v[2:3], v[44:45], v[44:45]
	s_nop 0
	v_fmamk_f32 v2, v2, 0xbdd2d3e7, v153
	v_mul_f32_e32 v2, v44, v2
	v_fmamk_f32 v3, v3, 0xbdd2d3e7, v153
	v_exp_f32_e32 v2, v2
	v_mul_f32_e32 v3, v45, v3
	v_exp_f32_e32 v3, v3
	v_add_f32_e32 v2, 1.0, v2
	v_rcp_f32_e32 v48, v2
	v_add_f32_e32 v34, 1.0, v3
	v_lshlrev_b32_e32 v2, 16, v4
	v_and_b32_e32 v3, 0xffff0000, v4
	v_pk_add_f32 v[2:3], v[2:3], 0 op_sel_hi:[1,0]
	v_rcp_f32_e32 v49, v34
	v_pk_add_f32 v[50:51], v[2:3], v[40:41]
	v_pk_mul_f32 v[44:45], v[44:45], v[48:49]
	v_pk_mul_f32 v[2:3], v[50:51], v[50:51]
	s_nop 0
	v_fmamk_f32 v2, v2, 0xbdd2d3e7, v153
	v_mul_f32_e32 v2, v50, v2
	v_fmamk_f32 v3, v3, 0xbdd2d3e7, v153
	v_exp_f32_e32 v2, v2
	v_mul_f32_e32 v3, v51, v3
	v_exp_f32_e32 v3, v3
	v_add_f32_e32 v2, 1.0, v2
	v_rcp_f32_e32 v52, v2
	v_add_f32_e32 v2, 1.0, v3
	v_add_u32_e32 v3, v56, v115
	ds_read_b128 v[34:37], v3
	v_rcp_f32_e32 v53, v2
	v_lshlrev_b32_e32 v2, 16, v5
	v_and_b32_e32 v3, 0xffff0000, v5
	v_pk_add_f32 v[38:39], v[2:3], 0 op_sel_hi:[1,0]
	v_add_u32_e32 v2, v56, v116
	ds_read_b128 v[2:5], v2
	v_pk_add_f32 v[42:43], v[38:39], v[42:43]
	s_waitcnt lgkmcnt(1)
	v_mfma_f32_16x16x32_bf16 v[34:37], v[34:37], v[6:9], 0
	v_add_u32_e32 v38, v56, v117
	ds_read_b128 v[38:41], v38
	v_pk_mul_f32 v[54:55], v[42:43], v[42:43]
	s_waitcnt lgkmcnt(1)
	v_mfma_f32_16x16x32_bf16 v[2:5], v[2:5], v[14:17], v[34:37]
	v_fmamk_f32 v54, v54, 0xbdd2d3e7, v153
	s_nop 1
	v_add_u32_e32 v34, v56, v118
	ds_read_b128 v[34:37], v34
	s_waitcnt lgkmcnt(1)
	v_mfma_f32_16x16x32_bf16 v[2:5], v[38:41], v[22:25], v[2:5]
	v_add_u32_e32 v38, v56, v119
	ds_read_b128 v[38:41], v38
	v_fmamk_f32 v55, v55, 0xbdd2d3e7, v153
	s_waitcnt lgkmcnt(1)
	v_mfma_f32_16x16x32_bf16 v[2:5], v[34:37], v[30:33], v[2:5]
	v_add_u32_e32 v34, v56, v120
	ds_read_b128 v[34:37], v34
	v_mul_f32_e32 v54, v42, v54
	s_waitcnt lgkmcnt(1)
	v_mfma_f32_16x16x32_bf16 v[2:5], v[38:41], v[26:29], v[2:5]
	v_add_u32_e32 v38, v56, v121
	ds_read_b128 v[38:41], v38
	v_mul_f32_e32 v55, v43, v55
	v_exp_f32_e32 v54, v54
	v_exp_f32_e32 v55, v55
	s_waitcnt lgkmcnt(1)
	v_mfma_f32_16x16x32_bf16 v[2:5], v[34:37], v[18:21], v[2:5]
	v_add_u32_e32 v34, v56, v122
	ds_read_b128 v[34:37], v34
	v_add_f32_e32 v54, 1.0, v54
	v_add_f32_e32 v55, 1.0, v55
	v_rcp_f32_e32 v54, v54
	v_rcp_f32_e32 v55, v55
	v_pk_mul_f32 v[48:49], v[50:51], v[52:53]
	v_add_u32_e32 v52, s37, v123
	s_waitcnt lgkmcnt(1)
	v_mfma_f32_16x16x32_bf16 v[2:5], v[38:41], v[10:13], v[2:5]
	v_add_u32_e32 v38, v52, v124
	ds_read_b128 v[38:41], v38
	v_pk_mul_f32 v[50:51], v[42:43], v[54:55]
	v_cvt_pk_bf16_f32 v42, v46, v47
	v_cvt_pk_bf16_f32 v43, v44, v45
	v_cvt_pk_bf16_f32 v44, v48, v49
	v_cvt_pk_bf16_f32 v45, v50, v51
	v_add_u32_e32 v46, v52, v126
	ds_read_b128 v[46:49], v46
	s_waitcnt lgkmcnt(2)
; #define LAS __attribute__((address_space(3)))
; DI void st8bf_(bf16_t* p, f32x4 v0, f32x4 v1) { u32x4 w; w.x = pk2(v0.x, v0.y); w.y = pk2(v0.z, v0.w); w.z = pk2(v1.x, v1.y); w.w = pk2(v1.z, v1.w); *(u32x4*)p = w; }
; DI void w2_compute(const Args& a, LAS unsigned char* lds, int task, int lane, const u32x4 (&x0)[8], const u32x4 (&x1)[8]) {
;     ...
;     for (int nt = 0; nt < 4; ++nt) { acc[nt] = (f32x4){0.f, 0.f, 0.f, 0.f};
; #pragma unroll
;         for (int ks = 0; ks < 8; ++ks) { const bf16x8 wfr = *(const LAS bf16x8*)(wl + w2off(16 * (fr >> 2) + 4 * nt + (fr & 3), 4 * ks + fq)); acc[nt] = __builtin_amdgcn_mfma_f32_16x16x32_bf16(wfr, af[ks], acc[nt], 0, 0, 0); } }
;     bf16_t* kc = (bf16_t*)(ws + WS_KC) + ((size_t)kind * AROWS + row0 + fr) * 64 + 16 * fq;
;     st8bf_(kc, acc[0], acc[1]); st8bf_(kc + 8, acc[2], acc[3]);
; DI void w2_unit(const Args& a, LAS unsigned char* lds, int v, int wave, int lane) {
;     ...
;     w2_load(a, t0, lane, xa0, xa1);
;     w2_load(a, t0 + 1, lane, xb0, xb1);
;     w2_compute(a, lds, t0, lane, xa0, xa1);
;     w2_load(a, t0 + 2, lane, xa0, xa1);
;     w2_compute(a, lds, t0 + 1, lane, xb0, xb1);
;     w2_load(a, t0 + 3, lane, xb0, xb1);
	v_mfma_f32_16x16x32_bf16 v[34:37], v[34:37], v[42:45], v[2:5]
	v_add_u32_e32 v54, s37, v132
	v_add_u32_e32 v50, v54, v135
	s_nop 0
	v_add_u32_e32 v2, v52, v125
	ds_read_b128 v[2:5], v2
	s_waitcnt lgkmcnt(2)
	v_mfma_f32_16x16x32_bf16 v[38:41], v[38:41], v[6:9], 0
	s_nop 0
	v_cvt_pk_bf16_f32 v34, v34, v35
	v_cvt_pk_bf16_f32 v35, v36, v37
	s_waitcnt lgkmcnt(0)
	v_mfma_f32_16x16x32_bf16 v[2:5], v[2:5], v[14:17], v[38:41]
	s_nop 2
	v_add_u32_e32 v38, v52, v127
	ds_read_b128 v[38:41], v38
	v_mfma_f32_16x16x32_bf16 v[2:5], v[46:49], v[22:25], v[2:5]
	v_add_u32_e32 v46, v52, v128
	ds_read_b128 v[46:49], v46
	s_waitcnt lgkmcnt(1)
	v_mfma_f32_16x16x32_bf16 v[2:5], v[38:41], v[30:33], v[2:5]
	v_add_u32_e32 v38, v52, v129
	ds_read_b128 v[38:41], v38
	s_waitcnt lgkmcnt(1)
	v_mfma_f32_16x16x32_bf16 v[2:5], v[46:49], v[26:29], v[2:5]
	v_add_u32_e32 v46, v52, v130
	ds_read_b128 v[46:49], v46
	s_waitcnt lgkmcnt(1)
	v_mfma_f32_16x16x32_bf16 v[2:5], v[38:41], v[18:21], v[2:5]
	v_add_u32_e32 v38, v52, v131
	ds_read_b128 v[38:41], v38
	ds_read_b128 v[50:53], v50
	s_waitcnt lgkmcnt(2)
	v_mfma_f32_16x16x32_bf16 v[2:5], v[46:49], v[10:13], v[2:5]
	v_add_u32_e32 v46, v54, v133
	ds_read_b128 v[46:49], v46
	s_waitcnt lgkmcnt(2)
	v_mfma_f32_16x16x32_bf16 v[38:41], v[38:41], v[42:45], v[2:5]
	s_nop 3
	v_add_u32_e32 v2, v54, v134
	ds_read_b128 v[2:5], v2
	s_waitcnt lgkmcnt(1)
	v_mfma_f32_16x16x32_bf16 v[46:49], v[46:49], v[6:9], 0
	v_cvt_pk_bf16_f32 v36, v38, v39
	v_cvt_pk_bf16_f32 v37, v40, v41
	s_waitcnt lgkmcnt(0)
	v_mfma_f32_16x16x32_bf16 v[2:5], v[2:5], v[14:17], v[46:49]
	s_nop 3
	v_add_u32_e32 v46, v54, v136
	ds_read_b128 v[46:49], v46
	v_mfma_f32_16x16x32_bf16 v[2:5], v[50:53], v[22:25], v[2:5]
	v_add_u32_e32 v50, v54, v137
	ds_read_b128 v[50:53], v50
	s_waitcnt lgkmcnt(1)
	v_mfma_f32_16x16x32_bf16 v[2:5], v[46:49], v[30:33], v[2:5]
	v_add_u32_e32 v46, v54, v138
	ds_read_b128 v[46:49], v46
	s_waitcnt lgkmcnt(1)
	v_mfma_f32_16x16x32_bf16 v[2:5], v[50:53], v[26:29], v[2:5]
	v_add_u32_e32 v50, v54, v140
	ds_read_b128 v[50:53], v50
	s_waitcnt lgkmcnt(1)
	v_mfma_f32_16x16x32_bf16 v[2:5], v[46:49], v[18:21], v[2:5]
	v_add_u32_e32 v46, v54, v139
	ds_read_b128 v[46:49], v46
	v_add_u32_e32 v54, s37, v141
	s_waitcnt lgkmcnt(0)
	v_mfma_f32_16x16x32_bf16 v[2:5], v[46:49], v[10:13], v[2:5]
	v_add_u32_e32 v46, v54, v142
	ds_read_b128 v[46:49], v46
	v_mfma_f32_16x16x32_bf16 v[50:53], v[50:53], v[42:45], v[2:5]
	s_nop 4
	v_add_u32_e32 v2, v54, v143
	ds_read_b128 v[2:5], v2
	s_waitcnt lgkmcnt(1)
	v_mfma_f32_16x16x32_bf16 v[6:9], v[46:49], v[6:9], 0
	v_add_u32_e32 v46, v54, v144
	ds_read_b128 v[46:49], v46
	s_waitcnt lgkmcnt(1)
	v_mfma_f32_16x16x32_bf16 v[2:5], v[2:5], v[14:17], v[6:9]
	s_nop 3
	v_add_u32_e32 v6, v54, v145
	ds_read_b128 v[6:9], v6
	v_add_u32_e32 v14, v54, v146
	ds_read_b128 v[14:17], v14
	s_waitcnt lgkmcnt(2)
	v_mfma_f32_16x16x32_bf16 v[2:5], v[46:49], v[22:25], v[2:5]
	v_add_u32_e32 v22, v54, v147
	ds_read_b128 v[22:25], v22
	s_waitcnt lgkmcnt(2)
	v_mfma_f32_16x16x32_bf16 v[2:5], v[6:9], v[30:33], v[2:5]
	v_mov_b32_e32 v7, s11
	v_or_b32_e32 v6, s9, v1
	v_lshlrev_b64 v[30:31], 9, v[6:7]
	v_add_u32_e32 v6, v54, v148
	ds_read_b128 v[6:9], v6
	s_waitcnt lgkmcnt(2)
	v_mfma_f32_16x16x32_bf16 v[2:5], v[14:17], v[26:29], v[2:5]
	v_add_u32_e32 v14, v54, v149
	ds_read_b128 v[46:49], v14
	s_mul_hi_i32 s9, s10, 0x10800
	s_waitcnt lgkmcnt(2)
	v_mfma_f32_16x16x32_bf16 v[2:5], v[22:25], v[18:21], v[2:5]
	s_mul_i32 s10, s10, 0x10800
	s_ashr_i32 s11, s17, 31
	s_add_u32 s10, s10, s17
	s_waitcnt lgkmcnt(1)
	v_mfma_f32_16x16x32_bf16 v[10:13], v[6:9], v[10:13], v[2:5]
	s_addc_u32 s9, s9, s11
	v_lshl_add_u64 v[58:59], v[104:105], 0, v[30:31]
	s_waitcnt vmcnt(7)
	v_mov_b64_e32 v[54:55], v[192:193]
	v_mov_b64_e32 v[56:57], v[194:195]
	s_waitcnt vmcnt(6)
	v_mov_b64_e32 v[18:19], v[196:197]
	v_mov_b64_e32 v[20:21], v[198:199]
	s_waitcnt vmcnt(5)
	v_mov_b64_e32 v[26:27], v[200:201]
	v_mov_b64_e32 v[28:29], v[202:203]
	s_waitcnt vmcnt(4)
	v_mov_b64_e32 v[30:31], v[204:205]
	v_mov_b64_e32 v[32:33], v[206:207]
	s_waitcnt lgkmcnt(0)
	v_mfma_f32_16x16x32_bf16 v[10:13], v[46:49], v[42:45], v[10:13]
	v_mov_b32_e32 v43, s9
	s_or_b32 s9, s12, 2
	s_add_i32 s11, s9, s13
	v_or_b32_e32 v42, s10, v1
	s_ashr_i32 s10, s11, 12
	s_and_b32 s11, s11, 0xffff000
	s_sub_i32 s9, s9, s11
	s_lshl_b32 s37, s9, 4
	s_ashr_i32 s11, s10, 31
	s_lshl_b64 s[38:39], s[10:11], 16
	s_ashr_i32 s11, s37, 31
	v_lshlrev_b64 v[42:43], 7, v[42:43]
	s_add_u32 s9, s38, s37
	v_lshl_add_u64 v[42:43], v[108:109], 0, v[42:43]
	s_addc_u32 s11, s39, s11
	s_lshl_b32 s38, s8, 8
	s_waitcnt vmcnt(3)
	v_mov_b64_e32 v[22:23], v[208:209]
	v_mov_b64_e32 v[24:25], v[210:211]
	s_waitcnt vmcnt(2)
	v_mov_b64_e32 v[14:15], v[212:213]
	v_mov_b64_e32 v[16:17], v[214:215]
	s_waitcnt vmcnt(1)
	v_mov_b64_e32 v[6:7], v[220:221]
	v_mov_b64_e32 v[8:9], v[222:223]
	s_waitcnt vmcnt(0)
	v_mov_b64_e32 v[2:3], v[224:225]
	v_mov_b64_e32 v[4:5], v[226:227]
	v_mov_b32_e32 v191, s11
	v_or_b32_e32 v190, s9, v1
	v_lshlrev_b64 v[190:191], 9, v[190:191]
	v_lshl_add_u64 v[190:191], v[104:105], 0, v[190:191]
	global_load_dwordx4 v[192:195], v[190:191], off
	global_load_dwordx4 v[196:199], v[190:191], off offset:64
	global_load_dwordx4 v[200:203], v[190:191], off offset:128
	global_load_dwordx4 v[204:207], v[190:191], off offset:192
	global_load_dwordx4 v[208:211], v[190:191], off offset:256
	global_load_dwordx4 v[212:215], v[190:191], off offset:320
	global_load_dwordx4 v[220:223], v[190:191], off offset:384
	global_load_dwordx4 v[224:227], v[190:191], off offset:448
	s_ashr_i32 s39, s38, 31
	global_store_dwordx4 v[42:43], v[34:37], off
	s_lshl_b32 s17, s8, 15
	s_add_i32 s17, s34, s17
	v_cvt_pk_bf16_f32 v34, v50, v51
	v_cvt_pk_bf16_f32 v35, v52, v53
	v_cvt_pk_bf16_f32 v36, v10, v11
	v_cvt_pk_bf16_f32 v37, v12, v13
	global_store_dwordx4 v[42:43], v[34:37], off offset:16
	s_addk_i32 s16, 0x800
	v_lshlrev_b32_e32 v44, 16, v54
	v_lshl_add_u64 v[34:35], s[38:39], 2, v[106:107]
	v_lshl_add_u32 v190, s38, 2, v186
	ds_read_b128 v[10:13], v190 offset:32768
	ds_read_b128 v[36:39], v190 offset:32784
	ds_read_b128 v[40:43], v190 offset:32896
	v_and_b32_e32 v45, 0xffff0000, v54
	v_pk_add_f32 v[44:45], v[44:45], 0 op_sel_hi:[1,0]
	v_lshlrev_b32_e32 v50, 16, v55
	v_and_b32_e32 v51, 0xffff0000, v55
	v_pk_add_f32 v[50:51], v[50:51], 0 op_sel_hi:[1,0]
	s_waitcnt lgkmcnt(2)
; DI bf16x8 pack8(f32x4 a, f32x4 b) { u32x4 p; p.x = pk2(a.x, a.y); p.y = pk2(a.z, a.w); p.z = pk2(b.x, b.y); p.w = pk2(b.z, b.w); return __builtin_bit_cast(bf16x8, p); }
; DI void w2_compute(const Args& a, LAS unsigned char* lds, int task, int lane, const u32x4 (&x0)[8], const u32x4 (&x1)[8]) {
;     ...
;     for (int ks = 0; ks < 8; ++ks) { const f32x4 c0 = *(const f32x4*)(cb + 32 * ks), c1 = *(const f32x4*)(cb + 32 * ks + 4);
;         f32x4 g0, g1;
;         g0.x = gelu_tanh(bf2f(x0[ks].x & 0xffffu) + bf2f(x1[ks].x & 0xffffu) + c0.x); g0.y = gelu_tanh(bf2f(x0[ks].x >> 16) + bf2f(x1[ks].x >> 16) + c0.y);
;         g0.z = gelu_tanh(bf2f(x0[ks].y & 0xffffu) + bf2f(x1[ks].y & 0xffffu) + c0.z); g0.w = gelu_tanh(bf2f(x0[ks].y >> 16) + bf2f(x1[ks].y >> 16) + c0.w);
;         g1.x = gelu_tanh(bf2f(x0[ks].z & 0xffffu) + bf2f(x1[ks].z & 0xffffu) + c1.x); g1.y = gelu_tanh(bf2f(x0[ks].z >> 16) + bf2f(x1[ks].z >> 16) + c1.y);
;         g1.z = gelu_tanh(bf2f(x0[ks].w & 0xffffu) + bf2f(x1[ks].w & 0xffffu) + c1.z); g1.w = gelu_tanh(bf2f(x0[ks].w >> 16) + bf2f(x1[ks].w >> 16) + c1.w);
;         af[ks] = pack8(g0, g1); }
	v_pk_add_f32 v[10:11], v[44:45], v[10:11]
	s_nop 0
	v_pk_mul_f32 v[44:45], v[10:11], v[10:11]
	v_pk_add_f32 v[12:13], v[50:51], v[12:13]
	v_fmamk_f32 v44, v44, 0xbdd2d3e7, v153
	v_mul_f32_e32 v44, v10, v44
	v_exp_f32_e32 v48, v44
	v_fmamk_f32 v44, v45, 0xbdd2d3e7, v153
	v_mul_f32_e32 v44, v11, v44
	v_exp_f32_e32 v49, v44
	ds_read_b128 v[44:47], v190 offset:32912
	v_pk_mul_f32 v[50:51], v[12:13], v[12:13]
	v_add_f32_e32 v48, 1.0, v48
	v_fmamk_f32 v50, v50, 0xbdd2d3e7, v153
	v_add_f32_e32 v49, 1.0, v49
	v_mul_f32_e32 v50, v12, v50
	v_rcp_f32_e32 v48, v48
	v_rcp_f32_e32 v49, v49
	v_exp_f32_e32 v50, v50
	v_fmamk_f32 v51, v51, 0xbdd2d3e7, v153
	v_mul_f32_e32 v51, v13, v51
	v_pk_mul_f32 v[10:11], v[10:11], v[48:49]
	v_add_f32_e32 v48, 1.0, v50
	v_rcp_f32_e32 v52, v48
	v_lshlrev_b32_e32 v48, 16, v56
	v_and_b32_e32 v49, 0xffff0000, v56
	v_pk_add_f32 v[48:49], v[48:49], 0 op_sel_hi:[1,0]
	v_exp_f32_e32 v51, v51
	s_waitcnt lgkmcnt(2)
	v_pk_add_f32 v[54:55], v[48:49], v[36:37]
	v_cvt_pk_bf16_f32 v10, v10, v11
	v_pk_mul_f32 v[36:37], v[54:55], v[54:55]
	v_add_f32_e32 v50, 1.0, v51
	v_fmamk_f32 v36, v36, 0xbdd2d3e7, v153
	v_mul_f32_e32 v36, v54, v36
	v_fmamk_f32 v37, v37, 0xbdd2d3e7, v153
	v_exp_f32_e32 v36, v36
	v_mul_f32_e32 v37, v55, v37
	v_exp_f32_e32 v37, v37
	v_rcp_f32_e32 v53, v50
	v_add_f32_e32 v36, 1.0, v36
	v_rcp_f32_e32 v56, v36
	v_add_f32_e32 v48, 1.0, v37
	v_lshlrev_b32_e32 v36, 16, v57
	v_and_b32_e32 v37, 0xffff0000, v57
	v_pk_add_f32 v[36:37], v[36:37], 0 op_sel_hi:[1,0]
	v_rcp_f32_e32 v57, v48
	v_pk_add_f32 v[58:59], v[36:37], v[38:39]
	v_pk_mul_f32 v[12:13], v[12:13], v[52:53]
	v_pk_mul_f32 v[36:37], v[58:59], v[58:59]
	v_pk_mul_f32 v[52:53], v[54:55], v[56:57]
	v_fmamk_f32 v36, v36, 0xbdd2d3e7, v153
	v_mul_f32_e32 v36, v58, v36
	v_fmamk_f32 v37, v37, 0xbdd2d3e7, v153
	v_exp_f32_e32 v36, v36
	v_mul_f32_e32 v37, v59, v37
	v_exp_f32_e32 v37, v37
	v_cvt_pk_bf16_f32 v11, v12, v13
	v_cvt_pk_bf16_f32 v12, v52, v53
	v_lshlrev_b32_e32 v52, 16, v18
	v_and_b32_e32 v53, 0xffff0000, v18
	v_add_f32_e32 v36, 1.0, v36
	v_pk_add_f32 v[52:53], v[52:53], 0 op_sel_hi:[1,0]
	v_rcp_f32_e32 v60, v36
	v_add_f32_e32 v36, 1.0, v37
	s_waitcnt lgkmcnt(1)
	v_pk_add_f32 v[40:41], v[52:53], v[40:41]
	v_rcp_f32_e32 v61, v36
	ds_read_b128 v[36:39], v190 offset:33040
	ds_read_b128 v[48:51], v190 offset:33024
	v_pk_mul_f32 v[52:53], v[40:41], v[40:41]
	v_pk_mul_f32 v[54:55], v[58:59], v[60:61]
	v_fmamk_f32 v13, v52, 0xbdd2d3e7, v153
	v_mul_f32_e32 v13, v40, v13
	v_exp_f32_e32 v18, v13
	v_fmamk_f32 v13, v53, 0xbdd2d3e7, v153
	v_mul_f32_e32 v13, v41, v13
	v_exp_f32_e32 v53, v13
	v_add_f32_e32 v18, 1.0, v18
	v_rcp_f32_e32 v52, v18
	v_cvt_pk_bf16_f32 v13, v54, v55
	v_add_f32_e32 v18, 1.0, v53
	v_rcp_f32_e32 v53, v18
	v_lshlrev_b32_e32 v18, 16, v19
	v_and_b32_e32 v19, 0xffff0000, v19
	v_pk_add_f32 v[18:19], v[18:19], 0 op_sel_hi:[1,0]
	v_pk_mul_f32 v[52:53], v[40:41], v[52:53]
	v_pk_add_f32 v[18:19], v[18:19], v[42:43]
	v_and_b32_e32 v41, 0xffff0000, v20
	v_pk_mul_f32 v[42:43], v[18:19], v[18:19]
	s_nop 0
	v_fmamk_f32 v42, v42, 0xbdd2d3e7, v153
	v_mul_f32_e32 v42, v18, v42
	v_exp_f32_e32 v42, v42
	v_fmamk_f32 v43, v43, 0xbdd2d3e7, v153
	v_mul_f32_e32 v43, v19, v43
	v_exp_f32_e32 v43, v43
	v_add_f32_e32 v40, 1.0, v42
	v_rcp_f32_e32 v54, v40
	v_lshlrev_b32_e32 v40, 16, v20
	v_pk_add_f32 v[40:41], v[40:41], 0 op_sel_hi:[1,0]
	v_add_f32_e32 v42, 1.0, v43
	s_waitcnt lgkmcnt(2)
	v_pk_add_f32 v[56:57], v[40:41], v[44:45]
	v_rcp_f32_e32 v55, v42
	v_pk_mul_f32 v[40:41], v[56:57], v[56:57]
	v_pk_mul_f32 v[54:55], v[18:19], v[54:55]
	v_fmamk_f32 v20, v40, 0xbdd2d3e7, v153
	v_fmamk_f32 v40, v41, 0xbdd2d3e7, v153
	v_mul_f32_e32 v40, v57, v40
	v_exp_f32_e32 v40, v40
	v_and_b32_e32 v41, 0xffff0000, v21
	v_mul_f32_e32 v20, v56, v20
	v_exp_f32_e32 v20, v20
	v_add_f32_e32 v42, 1.0, v40
	v_lshlrev_b32_e32 v40, 16, v21
	v_pk_add_f32 v[40:41], v[40:41], 0 op_sel_hi:[1,0]
	v_add_f32_e32 v20, 1.0, v20
	v_pk_add_f32 v[58:59], v[40:41], v[46:47]
	v_rcp_f32_e32 v20, v20
	v_pk_mul_f32 v[40:41], v[58:59], v[58:59]
	v_cvt_pk_bf16_f32 v18, v52, v53
	v_fmamk_f32 v21, v40, 0xbdd2d3e7, v153
	v_mul_f32_e32 v21, v58, v21
	v_exp_f32_e32 v40, v21
	v_fmamk_f32 v21, v41, 0xbdd2d3e7, v153
	v_mul_f32_e32 v21, v59, v21
	v_exp_f32_e32 v41, v21
	v_add_f32_e32 v40, 1.0, v40
	v_rcp_f32_e32 v60, v40
	v_rcp_f32_e32 v21, v42
	v_add_f32_e32 v40, 1.0, v41
	v_rcp_f32_e32 v61, v40
	ds_read_b128 v[40:43], v190 offset:33168
	ds_read_b128 v[44:47], v190 offset:33152
	v_lshlrev_b32_e32 v52, 16, v26
	v_and_b32_e32 v53, 0xffff0000, v26
	v_pk_add_f32 v[52:53], v[52:53], 0 op_sel_hi:[1,0]
	v_pk_mul_f32 v[20:21], v[56:57], v[20:21]
	v_cvt_pk_bf16_f32 v19, v54, v55
	v_cvt_pk_bf16_f32 v20, v20, v21
	v_pk_mul_f32 v[56:57], v[58:59], v[60:61]
	s_waitcnt lgkmcnt(2)
; DI bf16x8 pack8(f32x4 a, f32x4 b) { u32x4 p; p.x = pk2(a.x, a.y); p.y = pk2(a.z, a.w); p.z = pk2(b.x, b.y); p.w = pk2(b.z, b.w); return __builtin_bit_cast(bf16x8, p); }
; DI void w2_compute(const Args& a, LAS unsigned char* lds, int task, int lane, const u32x4 (&x0)[8], const u32x4 (&x1)[8]) {
;     ...
;     for (int ks = 0; ks < 8; ++ks) { const f32x4 c0 = *(const f32x4*)(cb + 32 * ks), c1 = *(const f32x4*)(cb + 32 * ks + 4);
;         f32x4 g0, g1;
;         g0.x = gelu_tanh(bf2f(x0[ks].x & 0xffffu) + bf2f(x1[ks].x & 0xffffu) + c0.x); g0.y = gelu_tanh(bf2f(x0[ks].x >> 16) + bf2f(x1[ks].x >> 16) + c0.y);
;         g0.z = gelu_tanh(bf2f(x0[ks].y & 0xffffu) + bf2f(x1[ks].y & 0xffffu) + c0.z); g0.w = gelu_tanh(bf2f(x0[ks].y >> 16) + bf2f(x1[ks].y >> 16) + c0.w);
;         g1.x = gelu_tanh(bf2f(x0[ks].z & 0xffffu) + bf2f(x1[ks].z & 0xffffu) + c1.x); g1.y = gelu_tanh(bf2f(x0[ks].z >> 16) + bf2f(x1[ks].z >> 16) + c1.y);
;         g1.z = gelu_tanh(bf2f(x0[ks].w & 0xffffu) + bf2f(x1[ks].w & 0xffffu) + c1.z); g1.w = gelu_tanh(bf2f(x0[ks].w >> 16) + bf2f(x1[ks].w >> 16) + c1.w);
;         af[ks] = pack8(g0, g1); }
	v_pk_add_f32 v[48:49], v[52:53], v[48:49]
	s_nop 0
	v_pk_mul_f32 v[52:53], v[48:49], v[48:49]
	s_nop 0
	v_fmamk_f32 v21, v52, 0xbdd2d3e7, v153
	v_mul_f32_e32 v21, v48, v21
	v_exp_f32_e32 v26, v21
	v_fmamk_f32 v21, v53, 0xbdd2d3e7, v153
	v_mul_f32_e32 v21, v49, v21
	v_exp_f32_e32 v53, v21
	v_add_f32_e32 v26, 1.0, v26
	v_rcp_f32_e32 v52, v26
	v_cvt_pk_bf16_f32 v21, v56, v57
	v_add_f32_e32 v26, 1.0, v53
	v_rcp_f32_e32 v53, v26
	v_lshlrev_b32_e32 v26, 16, v27
	v_and_b32_e32 v27, 0xffff0000, v27
	v_pk_add_f32 v[26:27], v[26:27], 0 op_sel_hi:[1,0]
	v_pk_mul_f32 v[52:53], v[48:49], v[52:53]
	v_pk_add_f32 v[26:27], v[26:27], v[50:51]
	v_and_b32_e32 v49, 0xffff0000, v28
	v_pk_mul_f32 v[50:51], v[26:27], v[26:27]
	s_nop 0
	v_fmamk_f32 v50, v50, 0xbdd2d3e7, v153
	v_mul_f32_e32 v50, v26, v50
	v_exp_f32_e32 v50, v50
	v_fmamk_f32 v51, v51, 0xbdd2d3e7, v153
	v_mul_f32_e32 v51, v27, v51
	v_exp_f32_e32 v51, v51
	v_add_f32_e32 v48, 1.0, v50
	v_rcp_f32_e32 v54, v48
	v_lshlrev_b32_e32 v48, 16, v28
	v_pk_add_f32 v[48:49], v[48:49], 0 op_sel_hi:[1,0]
	v_add_f32_e32 v50, 1.0, v51
	v_pk_add_f32 v[56:57], v[48:49], v[36:37]
	v_rcp_f32_e32 v55, v50
	v_pk_mul_f32 v[36:37], v[56:57], v[56:57]
	v_pk_mul_f32 v[54:55], v[26:27], v[54:55]
	v_fmamk_f32 v28, v36, 0xbdd2d3e7, v153
	v_fmamk_f32 v36, v37, 0xbdd2d3e7, v153
	v_mul_f32_e32 v36, v57, v36
	v_exp_f32_e32 v36, v36
	v_and_b32_e32 v37, 0xffff0000, v29
	v_mul_f32_e32 v28, v56, v28
	v_exp_f32_e32 v28, v28
	v_add_f32_e32 v48, 1.0, v36
	v_lshlrev_b32_e32 v36, 16, v29
	v_pk_add_f32 v[36:37], v[36:37], 0 op_sel_hi:[1,0]
	v_add_f32_e32 v28, 1.0, v28
	v_pk_add_f32 v[58:59], v[36:37], v[38:39]
	v_rcp_f32_e32 v28, v28
	v_pk_mul_f32 v[36:37], v[58:59], v[58:59]
	v_cvt_pk_bf16_f32 v26, v52, v53
	v_fmamk_f32 v29, v36, 0xbdd2d3e7, v153
	v_mul_f32_e32 v29, v58, v29
	v_exp_f32_e32 v36, v29
	v_fmamk_f32 v29, v37, 0xbdd2d3e7, v153
	v_mul_f32_e32 v29, v59, v29
	v_exp_f32_e32 v37, v29
	v_rcp_f32_e32 v29, v48
	v_lshlrev_b32_e32 v52, 16, v30
	v_and_b32_e32 v53, 0xffff0000, v30
	v_add_f32_e32 v36, 1.0, v36
	v_pk_add_f32 v[52:53], v[52:53], 0 op_sel_hi:[1,0]
	v_rcp_f32_e32 v60, v36
	v_add_f32_e32 v36, 1.0, v37
	s_waitcnt lgkmcnt(0)
	v_pk_add_f32 v[44:45], v[52:53], v[44:45]
	v_rcp_f32_e32 v61, v36
	ds_read_b128 v[36:39], v190 offset:33296
	ds_read_b128 v[48:51], v190 offset:33280
	v_pk_mul_f32 v[28:29], v[56:57], v[28:29]
	v_pk_mul_f32 v[52:53], v[44:45], v[44:45]
	v_cvt_pk_bf16_f32 v28, v28, v29
	v_fmamk_f32 v29, v52, 0xbdd2d3e7, v153
	v_mul_f32_e32 v29, v44, v29
	v_exp_f32_e32 v30, v29
	v_fmamk_f32 v29, v53, 0xbdd2d3e7, v153
	v_mul_f32_e32 v29, v45, v29
	v_exp_f32_e32 v53, v29
	v_add_f32_e32 v30, 1.0, v30
	v_rcp_f32_e32 v52, v30
	v_cvt_pk_bf16_f32 v27, v54, v55
	v_add_f32_e32 v30, 1.0, v53
	v_rcp_f32_e32 v53, v30
	v_lshlrev_b32_e32 v30, 16, v31
	v_and_b32_e32 v31, 0xffff0000, v31
	v_pk_add_f32 v[30:31], v[30:31], 0 op_sel_hi:[1,0]
	v_pk_mul_f32 v[52:53], v[44:45], v[52:53]
	v_pk_add_f32 v[30:31], v[30:31], v[46:47]
	v_and_b32_e32 v45, 0xffff0000, v32
	v_pk_mul_f32 v[46:47], v[30:31], v[30:31]
	v_pk_mul_f32 v[56:57], v[58:59], v[60:61]
	v_fmamk_f32 v46, v46, 0xbdd2d3e7, v153
	v_mul_f32_e32 v46, v30, v46
	v_exp_f32_e32 v46, v46
	v_cvt_pk_bf16_f32 v29, v56, v57
	v_fmamk_f32 v47, v47, 0xbdd2d3e7, v153
	v_mul_f32_e32 v47, v31, v47
	v_add_f32_e32 v44, 1.0, v46
	v_rcp_f32_e32 v54, v44
	v_lshlrev_b32_e32 v44, 16, v32
	v_pk_add_f32 v[44:45], v[44:45], 0 op_sel_hi:[1,0]
	v_exp_f32_e32 v47, v47
	v_pk_add_f32 v[56:57], v[44:45], v[40:41]
	v_add_f32_e32 v46, 1.0, v47
	v_pk_mul_f32 v[40:41], v[56:57], v[56:57]
	v_rcp_f32_e32 v55, v46
	v_fmamk_f32 v32, v40, 0xbdd2d3e7, v153
	v_fmamk_f32 v40, v41, 0xbdd2d3e7, v153
	v_mul_f32_e32 v40, v57, v40
	v_exp_f32_e32 v40, v40
	v_and_b32_e32 v41, 0xffff0000, v33
	v_mul_f32_e32 v32, v56, v32
	v_exp_f32_e32 v32, v32
	v_add_f32_e32 v44, 1.0, v40
	v_lshlrev_b32_e32 v40, 16, v33
	v_pk_add_f32 v[40:41], v[40:41], 0 op_sel_hi:[1,0]
	v_add_f32_e32 v32, 1.0, v32
	v_pk_add_f32 v[58:59], v[40:41], v[42:43]
	v_rcp_f32_e32 v32, v32
	v_pk_mul_f32 v[40:41], v[58:59], v[58:59]
	v_pk_mul_f32 v[54:55], v[30:31], v[54:55]
	v_fmamk_f32 v33, v40, 0xbdd2d3e7, v153
	v_mul_f32_e32 v33, v58, v33
	v_exp_f32_e32 v40, v33
	v_fmamk_f32 v33, v41, 0xbdd2d3e7, v153
	v_mul_f32_e32 v33, v59, v33
	v_exp_f32_e32 v41, v33
	v_add_f32_e32 v40, 1.0, v40
	v_rcp_f32_e32 v60, v40
	v_rcp_f32_e32 v33, v44
	v_add_f32_e32 v40, 1.0, v41
	v_rcp_f32_e32 v61, v40
	ds_read_b128 v[40:43], v190 offset:33424
	ds_read_b128 v[44:47], v190 offset:33408
	v_cvt_pk_bf16_f32 v30, v52, v53
	v_lshlrev_b32_e32 v52, 16, v22
	v_and_b32_e32 v53, 0xffff0000, v22
	v_pk_add_f32 v[52:53], v[52:53], 0 op_sel_hi:[1,0]
	v_pk_mul_f32 v[32:33], v[56:57], v[32:33]
	v_cvt_pk_bf16_f32 v31, v54, v55
	v_cvt_pk_bf16_f32 v32, v32, v33
	v_pk_mul_f32 v[56:57], v[58:59], v[60:61]
	s_waitcnt lgkmcnt(2)
; DI bf16x8 pack8(f32x4 a, f32x4 b) { u32x4 p; p.x = pk2(a.x, a.y); p.y = pk2(a.z, a.w); p.z = pk2(b.x, b.y); p.w = pk2(b.z, b.w); return __builtin_bit_cast(bf16x8, p); }
; DI void w2_compute(const Args& a, LAS unsigned char* lds, int task, int lane, const u32x4 (&x0)[8], const u32x4 (&x1)[8]) {
;     ...
;     for (int ks = 0; ks < 8; ++ks) { const f32x4 c0 = *(const f32x4*)(cb + 32 * ks), c1 = *(const f32x4*)(cb + 32 * ks + 4);
;         f32x4 g0, g1;
;         g0.x = gelu_tanh(bf2f(x0[ks].x & 0xffffu) + bf2f(x1[ks].x & 0xffffu) + c0.x); g0.y = gelu_tanh(bf2f(x0[ks].x >> 16) + bf2f(x1[ks].x >> 16) + c0.y);
;         g0.z = gelu_tanh(bf2f(x0[ks].y & 0xffffu) + bf2f(x1[ks].y & 0xffffu) + c0.z); g0.w = gelu_tanh(bf2f(x0[ks].y >> 16) + bf2f(x1[ks].y >> 16) + c0.w);
;         g1.x = gelu_tanh(bf2f(x0[ks].z & 0xffffu) + bf2f(x1[ks].z & 0xffffu) + c1.x); g1.y = gelu_tanh(bf2f(x0[ks].z >> 16) + bf2f(x1[ks].z >> 16) + c1.y);
;         g1.z = gelu_tanh(bf2f(x0[ks].w & 0xffffu) + bf2f(x1[ks].w & 0xffffu) + c1.z); g1.w = gelu_tanh(bf2f(x0[ks].w >> 16) + bf2f(x1[ks].w >> 16) + c1.w);
;         af[ks] = pack8(g0, g1); }
	v_pk_add_f32 v[48:49], v[52:53], v[48:49]
	s_nop 0
	v_pk_mul_f32 v[52:53], v[48:49], v[48:49]
	s_nop 0
	v_fmamk_f32 v22, v52, 0xbdd2d3e7, v153
	v_mul_f32_e32 v22, v48, v22
	v_fmamk_f32 v33, v53, 0xbdd2d3e7, v153
	v_exp_f32_e32 v22, v22
	v_mul_f32_e32 v33, v49, v33
	v_exp_f32_e32 v53, v33
	v_cvt_pk_bf16_f32 v33, v56, v57
	v_add_f32_e32 v22, 1.0, v22
	v_rcp_f32_e32 v52, v22
	v_add_f32_e32 v22, 1.0, v53
	v_rcp_f32_e32 v53, v22
	v_lshlrev_b32_e32 v22, 16, v23
	v_and_b32_e32 v23, 0xffff0000, v23
	v_pk_add_f32 v[22:23], v[22:23], 0 op_sel_hi:[1,0]
	v_pk_mul_f32 v[52:53], v[48:49], v[52:53]
	v_pk_add_f32 v[22:23], v[22:23], v[50:51]
	v_and_b32_e32 v49, 0xffff0000, v24
	v_pk_mul_f32 v[50:51], v[22:23], v[22:23]
	s_nop 0
	v_fmamk_f32 v50, v50, 0xbdd2d3e7, v153
	v_mul_f32_e32 v50, v22, v50
	v_exp_f32_e32 v50, v50
	v_fmamk_f32 v51, v51, 0xbdd2d3e7, v153
	v_mul_f32_e32 v51, v23, v51
	v_exp_f32_e32 v51, v51
	v_add_f32_e32 v48, 1.0, v50
	v_rcp_f32_e32 v54, v48
	v_lshlrev_b32_e32 v48, 16, v24
	v_pk_add_f32 v[48:49], v[48:49], 0 op_sel_hi:[1,0]
	v_add_f32_e32 v50, 1.0, v51
	v_pk_add_f32 v[56:57], v[48:49], v[36:37]
	v_rcp_f32_e32 v55, v50
	v_pk_mul_f32 v[36:37], v[56:57], v[56:57]
	v_pk_mul_f32 v[54:55], v[22:23], v[54:55]
	v_fmamk_f32 v24, v36, 0xbdd2d3e7, v153
	v_fmamk_f32 v36, v37, 0xbdd2d3e7, v153
	v_mul_f32_e32 v36, v57, v36
	v_exp_f32_e32 v36, v36
	v_and_b32_e32 v37, 0xffff0000, v25
	v_mul_f32_e32 v24, v56, v24
	v_exp_f32_e32 v24, v24
	v_add_f32_e32 v48, 1.0, v36
	v_lshlrev_b32_e32 v36, 16, v25
	v_pk_add_f32 v[36:37], v[36:37], 0 op_sel_hi:[1,0]
	v_add_f32_e32 v24, 1.0, v24
	v_pk_add_f32 v[58:59], v[36:37], v[38:39]
	v_rcp_f32_e32 v24, v24
	v_pk_mul_f32 v[36:37], v[58:59], v[58:59]
	v_cvt_pk_bf16_f32 v22, v52, v53
	v_fmamk_f32 v25, v36, 0xbdd2d3e7, v153
	v_mul_f32_e32 v25, v58, v25
	v_exp_f32_e32 v36, v25
	v_fmamk_f32 v25, v37, 0xbdd2d3e7, v153
	v_mul_f32_e32 v25, v59, v25
	v_exp_f32_e32 v37, v25
	v_rcp_f32_e32 v25, v48
	v_add_f32_e32 v36, 1.0, v36
	v_lshlrev_b32_e32 v52, 16, v14
	v_and_b32_e32 v53, 0xffff0000, v14
	v_rcp_f32_e32 v60, v36
	v_add_f32_e32 v36, 1.0, v37
	v_pk_add_f32 v[52:53], v[52:53], 0 op_sel_hi:[1,0]
	v_rcp_f32_e32 v61, v36
	ds_read_b128 v[36:39], v190 offset:33552
	ds_read_b128 v[48:51], v190 offset:33536
	s_waitcnt lgkmcnt(2)
	v_pk_add_f32 v[52:53], v[52:53], v[44:45]
	v_pk_mul_f32 v[24:25], v[56:57], v[24:25]
	v_pk_mul_f32 v[44:45], v[52:53], v[52:53]
	v_cvt_pk_bf16_f32 v24, v24, v25
	v_fmamk_f32 v25, v45, 0xbdd2d3e7, v153
	v_mul_f32_e32 v25, v53, v25
	v_fmamk_f32 v14, v44, 0xbdd2d3e7, v153
	v_exp_f32_e32 v44, v25
	v_pk_mul_f32 v[56:57], v[58:59], v[60:61]
	v_and_b32_e32 v45, 0xffff0000, v15
	v_cvt_pk_bf16_f32 v25, v56, v57
	v_add_f32_e32 v56, 1.0, v44
	v_lshlrev_b32_e32 v44, 16, v15
	v_pk_add_f32 v[44:45], v[44:45], 0 op_sel_hi:[1,0]
	v_cvt_pk_bf16_f32 v23, v54, v55
	v_pk_add_f32 v[54:55], v[44:45], v[46:47]
	v_mul_f32_e32 v14, v52, v14
	v_pk_mul_f32 v[44:45], v[54:55], v[54:55]
	v_exp_f32_e32 v14, v14
	v_fmamk_f32 v15, v44, 0xbdd2d3e7, v153
	v_mul_f32_e32 v15, v54, v15
	v_exp_f32_e32 v44, v15
	v_fmamk_f32 v15, v45, 0xbdd2d3e7, v153
	v_mul_f32_e32 v15, v55, v15
	v_exp_f32_e32 v45, v15
	v_add_f32_e32 v44, 1.0, v44
	v_rcp_f32_e32 v15, v56
	v_rcp_f32_e32 v56, v44
	v_add_f32_e32 v46, 1.0, v45
	v_lshlrev_b32_e32 v44, 16, v16
	v_and_b32_e32 v45, 0xffff0000, v16
	v_pk_add_f32 v[44:45], v[44:45], 0 op_sel_hi:[1,0]
	v_rcp_f32_e32 v57, v46
	v_pk_add_f32 v[58:59], v[44:45], v[40:41]
	v_add_f32_e32 v14, 1.0, v14
	v_pk_mul_f32 v[40:41], v[58:59], v[58:59]
	v_rcp_f32_e32 v14, v14
	v_fmamk_f32 v16, v40, 0xbdd2d3e7, v153
	v_fmamk_f32 v40, v41, 0xbdd2d3e7, v153
	v_mul_f32_e32 v40, v59, v40
	v_exp_f32_e32 v40, v40
	v_and_b32_e32 v41, 0xffff0000, v17
	v_mul_f32_e32 v16, v58, v16
	v_exp_f32_e32 v16, v16
	v_add_f32_e32 v44, 1.0, v40
	v_lshlrev_b32_e32 v40, 16, v17
	v_pk_add_f32 v[40:41], v[40:41], 0 op_sel_hi:[1,0]
	v_add_f32_e32 v16, 1.0, v16
	v_pk_add_f32 v[60:61], v[40:41], v[42:43]
	v_rcp_f32_e32 v16, v16
	v_pk_mul_f32 v[40:41], v[60:61], v[60:61]
	v_pk_mul_f32 v[14:15], v[52:53], v[14:15]
	v_fmamk_f32 v17, v40, 0xbdd2d3e7, v153
	v_mul_f32_e32 v17, v60, v17
	v_exp_f32_e32 v40, v17
	v_fmamk_f32 v17, v41, 0xbdd2d3e7, v153
	v_mul_f32_e32 v17, v61, v17
	v_exp_f32_e32 v41, v17
	v_add_f32_e32 v40, 1.0, v40
	v_rcp_f32_e32 v17, v44
	v_rcp_f32_e32 v62, v40
	v_add_f32_e32 v63, 1.0, v41
	ds_read_b128 v[40:43], v190 offset:33680
	ds_read_b128 v[44:47], v190 offset:33664
	v_pk_mul_f32 v[34:35], v[54:55], v[56:57]
	v_cvt_pk_bf16_f32 v14, v14, v15
	v_cvt_pk_bf16_f32 v15, v34, v35
	v_lshlrev_b32_e32 v34, 16, v6
	v_and_b32_e32 v35, 0xffff0000, v6
	v_pk_add_f32 v[34:35], v[34:35], 0 op_sel_hi:[1,0]
	v_pk_mul_f32 v[16:17], v[58:59], v[16:17]
	v_rcp_f32_e32 v63, v63
	v_cvt_pk_bf16_f32 v16, v16, v17
	v_add_u32_e32 v56, s17, v114
	v_pk_mul_f32 v[52:53], v[60:61], v[62:63]
	s_waitcnt lgkmcnt(2)
; #define LAS __attribute__((address_space(3)))
; DI bf16x8 pack8(f32x4 a, f32x4 b) { u32x4 p; p.x = pk2(a.x, a.y); p.y = pk2(a.z, a.w); p.z = pk2(b.x, b.y); p.w = pk2(b.z, b.w); return __builtin_bit_cast(bf16x8, p); }
; DI void w2_compute(const Args& a, LAS unsigned char* lds, int task, int lane, const u32x4 (&x0)[8], const u32x4 (&x1)[8]) {
;     ...
;     for (int ks = 0; ks < 8; ++ks) { const f32x4 c0 = *(const f32x4*)(cb + 32 * ks), c1 = *(const f32x4*)(cb + 32 * ks + 4);
;         f32x4 g0, g1;
;         g0.x = gelu_tanh(bf2f(x0[ks].x & 0xffffu) + bf2f(x1[ks].x & 0xffffu) + c0.x); g0.y = gelu_tanh(bf2f(x0[ks].x >> 16) + bf2f(x1[ks].x >> 16) + c0.y);
;         g0.z = gelu_tanh(bf2f(x0[ks].y & 0xffffu) + bf2f(x1[ks].y & 0xffffu) + c0.z); g0.w = gelu_tanh(bf2f(x0[ks].y >> 16) + bf2f(x1[ks].y >> 16) + c0.w);
;         g1.x = gelu_tanh(bf2f(x0[ks].z & 0xffffu) + bf2f(x1[ks].z & 0xffffu) + c1.x); g1.y = gelu_tanh(bf2f(x0[ks].z >> 16) + bf2f(x1[ks].z >> 16) + c1.y);
;         g1.z = gelu_tanh(bf2f(x0[ks].w & 0xffffu) + bf2f(x1[ks].w & 0xffffu) + c1.z); g1.w = gelu_tanh(bf2f(x0[ks].w >> 16) + bf2f(x1[ks].w >> 16) + c1.w);
;         af[ks] = pack8(g0, g1); }
;     const LAS unsigned char* wl = lds + W2_LDS + kind * 32768;
;     f32x4 acc[4];
; #pragma unroll
;     for (int nt = 0; nt < 4; ++nt) { acc[nt] = (f32x4){0.f, 0.f, 0.f, 0.f};
; #pragma unroll
;         for (int ks = 0; ks < 8; ++ks) { const bf16x8 wfr = *(const LAS bf16x8*)(wl + w2off(16 * (fr >> 2) + 4 * nt + (fr & 3), 4 * ks + fq)); acc[nt] = __builtin_amdgcn_mfma_f32_16x16x32_bf16(wfr, af[ks], acc[nt], 0, 0, 0); } }
	v_pk_add_f32 v[34:35], v[34:35], v[48:49]
	s_nop 0
	v_pk_mul_f32 v[48:49], v[34:35], v[34:35]
	s_nop 0
	v_fmamk_f32 v17, v49, 0xbdd2d3e7, v153
	v_mul_f32_e32 v17, v35, v17
	v_fmamk_f32 v6, v48, 0xbdd2d3e7, v153
	v_exp_f32_e32 v48, v17
	v_cvt_pk_bf16_f32 v17, v52, v53
	v_and_b32_e32 v49, 0xffff0000, v7
	v_and_b32_e32 v53, 0xffff0000, v8
	v_add_f32_e32 v52, 1.0, v48
	v_lshlrev_b32_e32 v48, 16, v7
	v_pk_add_f32 v[48:49], v[48:49], 0 op_sel_hi:[1,0]
	v_mul_f32_e32 v6, v34, v6
	v_pk_add_f32 v[48:49], v[48:49], v[50:51]
	v_exp_f32_e32 v6, v6
	v_pk_mul_f32 v[50:51], v[48:49], v[48:49]
	v_add_f32_e32 v6, 1.0, v6
	v_fmamk_f32 v7, v50, 0xbdd2d3e7, v153
	v_mul_f32_e32 v7, v48, v7
	v_exp_f32_e32 v50, v7
	v_fmamk_f32 v7, v51, 0xbdd2d3e7, v153
	v_mul_f32_e32 v7, v49, v7
	v_exp_f32_e32 v51, v7
	v_rcp_f32_e32 v7, v52
	v_lshlrev_b32_e32 v52, 16, v8
	v_pk_add_f32 v[52:53], v[52:53], 0 op_sel_hi:[1,0]
	v_add_f32_e32 v50, 1.0, v50
	v_pk_add_f32 v[36:37], v[52:53], v[36:37]
	v_add_f32_e32 v51, 1.0, v51
	v_pk_mul_f32 v[52:53], v[36:37], v[36:37]
	v_rcp_f32_e32 v6, v6
	v_fmamk_f32 v8, v52, 0xbdd2d3e7, v153
	v_fmamk_f32 v52, v53, 0xbdd2d3e7, v153
	v_mul_f32_e32 v52, v37, v52
	v_exp_f32_e32 v52, v52
	v_and_b32_e32 v53, 0xffff0000, v9
	v_mul_f32_e32 v8, v36, v8
	v_exp_f32_e32 v8, v8
	v_add_f32_e32 v54, 1.0, v52
	v_lshlrev_b32_e32 v52, 16, v9
	v_pk_add_f32 v[52:53], v[52:53], 0 op_sel_hi:[1,0]
	v_rcp_f32_e32 v50, v50
	v_pk_add_f32 v[38:39], v[52:53], v[38:39]
	v_rcp_f32_e32 v51, v51
	v_pk_mul_f32 v[52:53], v[38:39], v[38:39]
	v_add_f32_e32 v8, 1.0, v8
	v_fmamk_f32 v9, v52, 0xbdd2d3e7, v153
	v_mul_f32_e32 v9, v38, v9
	v_exp_f32_e32 v52, v9
	v_fmamk_f32 v9, v53, 0xbdd2d3e7, v153
	v_mul_f32_e32 v9, v39, v9
	v_exp_f32_e32 v53, v9
	v_add_f32_e32 v52, 1.0, v52
	v_rcp_f32_e32 v8, v8
	v_rcp_f32_e32 v9, v54
	v_add_f32_e32 v53, 1.0, v53
	v_rcp_f32_e32 v52, v52
	v_rcp_f32_e32 v53, v53
	v_pk_mul_f32 v[6:7], v[34:35], v[6:7]
	v_pk_mul_f32 v[34:35], v[48:49], v[50:51]
	v_cvt_pk_bf16_f32 v6, v6, v7
	v_cvt_pk_bf16_f32 v7, v34, v35
	v_lshlrev_b32_e32 v34, 16, v2
	v_and_b32_e32 v35, 0xffff0000, v2
	v_pk_add_f32 v[34:35], v[34:35], 0 op_sel_hi:[1,0]
	v_pk_mul_f32 v[8:9], v[36:37], v[8:9]
	s_waitcnt lgkmcnt(0)
	v_pk_add_f32 v[34:35], v[34:35], v[44:45]
	v_pk_mul_f32 v[36:37], v[38:39], v[52:53]
	v_pk_mul_f32 v[38:39], v[34:35], v[34:35]
	v_cvt_pk_bf16_f32 v8, v8, v9
	v_fmamk_f32 v2, v38, 0xbdd2d3e7, v153
	v_mul_f32_e32 v2, v34, v2
	v_fmamk_f32 v9, v39, 0xbdd2d3e7, v153
	v_exp_f32_e32 v2, v2
	v_mul_f32_e32 v9, v35, v9
	v_exp_f32_e32 v38, v9
	v_cvt_pk_bf16_f32 v9, v36, v37
	v_add_f32_e32 v2, 1.0, v2
	v_rcp_f32_e32 v36, v2
	v_add_f32_e32 v2, 1.0, v38
	v_rcp_f32_e32 v37, v2
	v_lshlrev_b32_e32 v2, 16, v3
	v_and_b32_e32 v3, 0xffff0000, v3
	v_pk_add_f32 v[2:3], v[2:3], 0 op_sel_hi:[1,0]
	s_nop 0
	v_pk_add_f32 v[44:45], v[2:3], v[46:47]
	v_pk_mul_f32 v[46:47], v[34:35], v[36:37]
	v_pk_mul_f32 v[2:3], v[44:45], v[44:45]
	s_nop 0
	v_fmamk_f32 v2, v2, 0xbdd2d3e7, v153
	v_mul_f32_e32 v2, v44, v2
	v_fmamk_f32 v3, v3, 0xbdd2d3e7, v153
	v_exp_f32_e32 v2, v2
	v_mul_f32_e32 v3, v45, v3
	v_exp_f32_e32 v3, v3
	v_add_f32_e32 v2, 1.0, v2
	v_rcp_f32_e32 v48, v2
	v_add_f32_e32 v34, 1.0, v3
	v_lshlrev_b32_e32 v2, 16, v4
	v_and_b32_e32 v3, 0xffff0000, v4
	v_pk_add_f32 v[2:3], v[2:3], 0 op_sel_hi:[1,0]
	v_rcp_f32_e32 v49, v34
	v_pk_add_f32 v[50:51], v[2:3], v[40:41]
	v_pk_mul_f32 v[44:45], v[44:45], v[48:49]
	v_pk_mul_f32 v[2:3], v[50:51], v[50:51]
	s_nop 0
	v_fmamk_f32 v2, v2, 0xbdd2d3e7, v153
	v_mul_f32_e32 v2, v50, v2
	v_fmamk_f32 v3, v3, 0xbdd2d3e7, v153
	v_exp_f32_e32 v2, v2
	v_mul_f32_e32 v3, v51, v3
	v_exp_f32_e32 v3, v3
	v_add_f32_e32 v2, 1.0, v2
	v_rcp_f32_e32 v52, v2
	v_add_f32_e32 v2, 1.0, v3
	v_add_u32_e32 v3, v56, v115
	ds_read_b128 v[34:37], v3
	v_rcp_f32_e32 v53, v2
	v_lshlrev_b32_e32 v2, 16, v5
	v_and_b32_e32 v3, 0xffff0000, v5
	v_pk_add_f32 v[38:39], v[2:3], 0 op_sel_hi:[1,0]
	v_add_u32_e32 v2, v56, v116
	ds_read_b128 v[2:5], v2
	v_pk_add_f32 v[42:43], v[38:39], v[42:43]
	s_waitcnt lgkmcnt(1)
	v_mfma_f32_16x16x32_bf16 v[34:37], v[34:37], v[10:13], 0
	v_add_u32_e32 v38, v56, v117
	ds_read_b128 v[38:41], v38
	v_pk_mul_f32 v[54:55], v[42:43], v[42:43]
	s_waitcnt lgkmcnt(1)
	v_mfma_f32_16x16x32_bf16 v[2:5], v[2:5], v[18:21], v[34:37]
	v_fmamk_f32 v54, v54, 0xbdd2d3e7, v153
	s_nop 1
	v_add_u32_e32 v34, v56, v118
	ds_read_b128 v[34:37], v34
	s_waitcnt lgkmcnt(1)
	v_mfma_f32_16x16x32_bf16 v[2:5], v[38:41], v[26:29], v[2:5]
	v_add_u32_e32 v38, v56, v119
	ds_read_b128 v[38:41], v38
	v_fmamk_f32 v55, v55, 0xbdd2d3e7, v153
	s_waitcnt lgkmcnt(1)
	v_mfma_f32_16x16x32_bf16 v[2:5], v[34:37], v[30:33], v[2:5]
	v_add_u32_e32 v34, v56, v120
	ds_read_b128 v[34:37], v34
	v_mul_f32_e32 v54, v42, v54
	s_waitcnt lgkmcnt(1)
	v_mfma_f32_16x16x32_bf16 v[2:5], v[38:41], v[22:25], v[2:5]
	v_add_u32_e32 v38, v56, v121
	ds_read_b128 v[38:41], v38
	v_mul_f32_e32 v55, v43, v55
	v_exp_f32_e32 v54, v54
	v_exp_f32_e32 v55, v55
	s_waitcnt lgkmcnt(1)
	v_mfma_f32_16x16x32_bf16 v[2:5], v[34:37], v[14:17], v[2:5]
	v_add_u32_e32 v34, v56, v122
	ds_read_b128 v[34:37], v34
	v_add_f32_e32 v54, 1.0, v54
	v_add_f32_e32 v55, 1.0, v55
	v_rcp_f32_e32 v54, v54
	v_rcp_f32_e32 v55, v55
	v_pk_mul_f32 v[48:49], v[50:51], v[52:53]
	v_add_u32_e32 v52, s17, v123
	s_waitcnt lgkmcnt(1)
	v_mfma_f32_16x16x32_bf16 v[2:5], v[38:41], v[6:9], v[2:5]
	v_add_u32_e32 v38, v52, v124
	ds_read_b128 v[38:41], v38
	v_pk_mul_f32 v[50:51], v[42:43], v[54:55]
	v_cvt_pk_bf16_f32 v42, v46, v47
	v_cvt_pk_bf16_f32 v43, v44, v45
	v_cvt_pk_bf16_f32 v44, v48, v49
	v_cvt_pk_bf16_f32 v45, v50, v51
	s_waitcnt lgkmcnt(0)
; #define LAS __attribute__((address_space(3)))
; DI void st8bf_(bf16_t* p, f32x4 v0, f32x4 v1) { u32x4 w; w.x = pk2(v0.x, v0.y); w.y = pk2(v0.z, v0.w); w.z = pk2(v1.x, v1.y); w.w = pk2(v1.z, v1.w); *(u32x4*)p = w; }
; DI void w2_load(const Args& a, int task, int lane, u32x4 (&x0)[8], u32x4 (&x1)[8]) {
;     const int fr = lane & 15, fq = lane >> 4;
;     const int kind = task / (AROWS_S / 16), pr0 = (task % (AROWS_S / 16)) * 16;
;     const bf16_t* h0 = (const bf16_t*)(a.ws + WS_GH) + ((size_t)kind * AROWS_S + pr0 + fr) * 256 + 8 * fq;
;     const bool bnd = (task & 3) == 3 && fr == 15;
;     const int hb = ((pr0 + 16) >> 6) < 1023 ? ((pr0 + 16) >> 6) : 1023;
;     const bf16_t* h1 = (const bf16_t*)(a.ws + WS_GH) + (size_t)2 * AROWS_S * 256 + ((size_t)kind * 1024 + hb) * 256 + 8 * fq;
; #pragma unroll
;     for (int ks = 0; ks < 8; ++ks) { x0[ks] = *(const u32x4*)(h0 + 32 * ks); x1[ks] = bnd ? *(const u32x4*)(h1 + 32 * ks) : (u32x4){0u, 0u, 0u, 0u}; }
; DI void w2_compute(const Args& a, LAS unsigned char* lds, int task, int lane, const u32x4 (&x0)[8], const u32x4 (&x1)[8]) {
;     ...
;     for (int nt = 0; nt < 4; ++nt) { acc[nt] = (f32x4){0.f, 0.f, 0.f, 0.f};
; #pragma unroll
;         for (int ks = 0; ks < 8; ++ks) { const bf16x8 wfr = *(const LAS bf16x8*)(wl + w2off(16 * (fr >> 2) + 4 * nt + (fr & 3), 4 * ks + fq)); acc[nt] = __builtin_amdgcn_mfma_f32_16x16x32_bf16(wfr, af[ks], acc[nt], 0, 0, 0); } }
;     bf16_t* kc = (bf16_t*)(ws + WS_KC) + ((size_t)kind * AROWS + row0 + fr) * 64 + 16 * fq;
;     st8bf_(kc, acc[0], acc[1]); st8bf_(kc + 8, acc[2], acc[3]);
	v_mfma_f32_16x16x32_bf16 v[38:41], v[38:41], v[10:13], 0
	v_add_u32_e32 v46, v52, v126
	ds_read_b128 v[46:49], v46
	v_add_u32_e32 v54, s17, v132
	v_mfma_f32_16x16x32_bf16 v[2:5], v[34:37], v[42:45], v[2:5]
	v_add_u32_e32 v34, v52, v125
	ds_read_b128 v[34:37], v34
	v_add_u32_e32 v50, v54, v135
	s_waitcnt lgkmcnt(0)
	v_mfma_f32_16x16x32_bf16 v[34:37], v[34:37], v[18:21], v[38:41]
	s_nop 2
	v_add_u32_e32 v38, v52, v127
	ds_read_b128 v[38:41], v38
	v_cvt_pk_bf16_f32 v2, v2, v3
	v_mfma_f32_16x16x32_bf16 v[34:37], v[46:49], v[26:29], v[34:37]
	v_add_u32_e32 v46, v52, v128
	ds_read_b128 v[46:49], v46
	v_cvt_pk_bf16_f32 v3, v4, v5
	s_waitcnt lgkmcnt(1)
	v_mfma_f32_16x16x32_bf16 v[34:37], v[38:41], v[30:33], v[34:37]
	v_add_u32_e32 v38, v52, v129
	ds_read_b128 v[38:41], v38
	s_waitcnt lgkmcnt(1)
	v_mfma_f32_16x16x32_bf16 v[34:37], v[46:49], v[22:25], v[34:37]
	v_add_u32_e32 v46, v52, v130
	ds_read_b128 v[46:49], v46
	s_waitcnt lgkmcnt(1)
	v_mfma_f32_16x16x32_bf16 v[34:37], v[38:41], v[14:17], v[34:37]
	v_add_u32_e32 v38, v52, v131
	ds_read_b128 v[38:41], v38
	ds_read_b128 v[50:53], v50
	s_waitcnt lgkmcnt(2)
	v_mfma_f32_16x16x32_bf16 v[34:37], v[46:49], v[6:9], v[34:37]
	v_add_u32_e32 v46, v54, v133
	ds_read_b128 v[46:49], v46
	s_waitcnt lgkmcnt(2)
	v_mfma_f32_16x16x32_bf16 v[34:37], v[38:41], v[42:45], v[34:37]
	v_add_u32_e32 v38, v54, v134
	ds_read_b128 v[38:41], v38
	s_nop 5
	v_cvt_pk_bf16_f32 v4, v34, v35
	s_waitcnt lgkmcnt(1)
	v_mfma_f32_16x16x32_bf16 v[46:49], v[46:49], v[10:13], 0
	v_cvt_pk_bf16_f32 v5, v36, v37
	s_waitcnt lgkmcnt(0)
	v_mfma_f32_16x16x32_bf16 v[38:41], v[38:41], v[18:21], v[46:49]
	s_nop 4
	v_add_u32_e32 v46, v54, v136
	ds_read_b128 v[46:49], v46
	v_mfma_f32_16x16x32_bf16 v[38:41], v[50:53], v[26:29], v[38:41]
	v_add_u32_e32 v50, v54, v137
	ds_read_b128 v[50:53], v50
	s_waitcnt lgkmcnt(1)
	v_mfma_f32_16x16x32_bf16 v[38:41], v[46:49], v[30:33], v[38:41]
	v_add_u32_e32 v46, v54, v138
	ds_read_b128 v[46:49], v46
	s_waitcnt lgkmcnt(1)
	v_mfma_f32_16x16x32_bf16 v[38:41], v[50:53], v[22:25], v[38:41]
	v_add_u32_e32 v50, v54, v140
	ds_read_b128 v[50:53], v50
	s_waitcnt lgkmcnt(1)
	v_mfma_f32_16x16x32_bf16 v[38:41], v[46:49], v[14:17], v[38:41]
	v_add_u32_e32 v46, v54, v139
	ds_read_b128 v[46:49], v46
	v_add_u32_e32 v54, s17, v141
	s_waitcnt lgkmcnt(0)
	v_mfma_f32_16x16x32_bf16 v[38:41], v[46:49], v[6:9], v[38:41]
	v_add_u32_e32 v46, v54, v142
	ds_read_b128 v[46:49], v46
	v_mfma_f32_16x16x32_bf16 v[38:41], v[50:53], v[42:45], v[38:41]
	v_add_u32_e32 v50, v54, v143
	ds_read_b128 v[50:53], v50
	s_waitcnt lgkmcnt(1)
	v_mfma_f32_16x16x32_bf16 v[10:13], v[46:49], v[10:13], 0
	v_add_u32_e32 v46, v54, v144
	ds_read_b128 v[46:49], v46
	s_waitcnt lgkmcnt(1)
	v_mfma_f32_16x16x32_bf16 v[10:13], v[50:53], v[18:21], v[10:13]
	v_add_u32_e32 v18, v54, v145
	ds_read_b128 v[18:21], v18
	s_waitcnt lgkmcnt(1)
	v_mfma_f32_16x16x32_bf16 v[10:13], v[46:49], v[26:29], v[10:13]
	v_add_u32_e32 v26, v54, v146
	ds_read_b128 v[26:29], v26
	v_add_u32_e32 v46, v54, v147
	ds_read_b128 v[46:49], v46
	s_waitcnt lgkmcnt(2)
	v_mfma_f32_16x16x32_bf16 v[10:13], v[18:21], v[30:33], v[10:13]
	v_mov_b32_e32 v19, s11
	v_or_b32_e32 v18, s9, v1
	v_lshlrev_b64 v[30:31], 9, v[18:19]
	s_waitcnt lgkmcnt(1)
	v_mfma_f32_16x16x32_bf16 v[10:13], v[26:29], v[22:25], v[10:13]
	v_add_u32_e32 v18, v54, v148
	ds_read_b128 v[18:21], v18
	s_mul_hi_i32 s9, s8, 0x10800
	s_waitcnt lgkmcnt(1)
	v_mfma_f32_16x16x32_bf16 v[10:13], v[46:49], v[14:17], v[10:13]
	v_add_u32_e32 v14, v54, v149
	ds_read_b128 v[14:17], v14
	s_mul_i32 s8, s8, 0x10800
	s_ashr_i32 s11, s16, 31
	s_add_u32 s8, s8, s16
	s_waitcnt lgkmcnt(1)
	v_mfma_f32_16x16x32_bf16 v[6:9], v[18:21], v[6:9], v[10:13]
	s_addc_u32 s9, s9, s11
	v_lshl_add_u64 v[22:23], v[104:105], 0, v[30:31]
	s_nop 0
	v_mov_b32_e32 v11, s9
	s_or_b32 s9, s12, 3
	s_add_i32 s11, s9, s13
	v_or_b32_e32 v10, s8, v1
	s_ashr_i32 s8, s11, 12
	s_and_b32 s11, s11, 0xffff000
	s_waitcnt lgkmcnt(0)
	v_mfma_f32_16x16x32_bf16 v[6:9], v[14:17], v[42:45], v[6:9]
	s_sub_i32 s9, s9, s11
	s_lshl_b32 s11, s9, 4
	s_ashr_i32 s9, s8, 31
	v_lshlrev_b64 v[10:11], 7, v[10:11]
	s_lshl_b64 s[12:13], s[8:9], 16
	s_ashr_i32 s16, s11, 31
	v_lshl_add_u64 v[10:11], v[108:109], 0, v[10:11]
	s_add_u32 s12, s12, s11
	s_waitcnt vmcnt(9)
	v_mov_b64_e32 v[96:97], v[192:193]
	v_mov_b64_e32 v[98:99], v[194:195]
	s_waitcnt vmcnt(8)
	v_mov_b64_e32 v[92:93], v[196:197]
	v_mov_b64_e32 v[94:95], v[198:199]
	s_waitcnt vmcnt(7)
	v_mov_b64_e32 v[86:87], v[200:201]
	v_mov_b64_e32 v[88:89], v[202:203]
	s_waitcnt vmcnt(6)
	v_mov_b64_e32 v[82:83], v[204:205]
	v_mov_b64_e32 v[84:85], v[206:207]
	s_waitcnt vmcnt(5)
	v_mov_b64_e32 v[78:79], v[208:209]
	v_mov_b64_e32 v[80:81], v[210:211]
	s_waitcnt vmcnt(4)
	v_mov_b64_e32 v[74:75], v[212:213]
	v_mov_b64_e32 v[76:77], v[214:215]
	s_waitcnt vmcnt(3)
	v_mov_b64_e32 v[70:71], v[220:221]
	v_mov_b64_e32 v[72:73], v[222:223]
	s_waitcnt vmcnt(2)
	v_mov_b64_e32 v[66:67], v[224:225]
	v_mov_b64_e32 v[68:69], v[226:227]
	s_addc_u32 s13, s13, s16
	global_store_dwordx4 v[10:11], v[2:5], off
	s_lshl_b64 s[16:17], s[8:9], 19
	s_nop 0
	v_cvt_pk_bf16_f32 v2, v38, v39
	v_cvt_pk_bf16_f32 v3, v40, v41
	v_cvt_pk_bf16_f32 v4, v6, v7
	v_cvt_pk_bf16_f32 v5, v8, v9
	global_store_dwordx4 v[10:11], v[2:5], off offset:16
	s_nop 1
	v_mov_b32_e32 v3, s13
	v_or_b32_e32 v2, s12, v1
	v_lshlrev_b64 v[2:3], 9, v[2:3]
	v_lshl_add_u64 v[90:91], v[104:105], 0, v[2:3]
	global_load_dwordx4 v[58:61], v[90:91], off
	s_add_i32 s12, s11, 16
	s_ashr_i32 s12, s12, 6
	s_min_i32 s12, s12, 0x3ff
	s_ashr_i32 s13, s12, 31
	s_add_u32 s9, s28, s16
	s_addc_u32 s17, s29, s17
	s_lshl_b64 s[12:13], s[12:13], 9
	s_add_u32 s16, s9, s12
	s_addc_u32 s17, s17, s13
	s_and_saveexec_b64 s[12:13], vcc
	s_xor_b64 s[12:13], exec, s[12:13]
	s_cbranch_execz .LBB0_1368
	global_load_dwordx4 v[46:49], v[90:91], off offset:64

; DI bf16x8 pack8(f32x4 a, f32x4 b) { u32x4 p; p.x = pk2(a.x, a.y); p.y = pk2(a.z, a.w); p.z = pk2(b.x, b.y); p.w = pk2(b.z, b.w); return __builtin_bit_cast(bf16x8, p); }
; DI void w2_compute(const Args& a, LAS unsigned char* lds, int task, int lane, const u32x4 (&x0)[8], const u32x4 (&x1)[8]) {
;     ...
;     const float* cb = (const float*)(ws + WS_CBIAS) + kind * 256 + 8 * fq;
;     bf16x8 af[8];
; #pragma unroll
;     for (int ks = 0; ks < 8; ++ks) { const f32x4 c0 = *(const f32x4*)(cb + 32 * ks), c1 = *(const f32x4*)(cb + 32 * ks + 4);
;         f32x4 g0, g1;
;         g0.x = gelu_tanh(bf2f(x0[ks].x & 0xffffu) + bf2f(x1[ks].x & 0xffffu) + c0.x); g0.y = gelu_tanh(bf2f(x0[ks].x >> 16) + bf2f(x1[ks].x >> 16) + c0.y);
;         g0.z = gelu_tanh(bf2f(x0[ks].y & 0xffffu) + bf2f(x1[ks].y & 0xffffu) + c0.z); g0.w = gelu_tanh(bf2f(x0[ks].y >> 16) + bf2f(x1[ks].y >> 16) + c0.w);
;         g1.x = gelu_tanh(bf2f(x0[ks].z & 0xffffu) + bf2f(x1[ks].z & 0xffffu) + c1.x); g1.y = gelu_tanh(bf2f(x0[ks].z >> 16) + bf2f(x1[ks].z >> 16) + c1.y);
;         g1.z = gelu_tanh(bf2f(x0[ks].w & 0xffffu) + bf2f(x1[ks].w & 0xffffu) + c1.z); g1.w = gelu_tanh(bf2f(x0[ks].w >> 16) + bf2f(x1[ks].w >> 16) + c1.w);
;         af[ks] = pack8(g0, g1); }
.LBB0_1382:
	s_or_b64 exec, exec, s[12:13]
	s_lshl_b32 s12, s10, 8
	s_ashr_i32 s13, s12, 31
	v_lshl_add_u64 v[112:113], s[12:13], 2, v[106:107]
	v_lshl_add_u32 v191, s12, 2, v186
	ds_read_b128 v[154:157], v191 offset:32768
	ds_read_b128 v[160:163], v191 offset:32784
	ds_read_b128 v[164:167], v191 offset:32896
	ds_read_b128 v[168:171], v191 offset:32912
	v_lshlrev_b32_e32 v100, 16, v98
	v_and_b32_e32 v101, 0xffff0000, v98
	v_lshlrev_b32_e32 v98, 16, v99
	v_and_b32_e32 v99, 0xffff0000, v99
	v_lshlrev_b32_e32 v172, 16, v92
	v_and_b32_e32 v173, 0xffff0000, v92
	v_pk_add_f32 v[176:177], v[100:101], 0 op_sel_hi:[1,0]
	v_pk_add_f32 v[178:179], v[98:99], 0 op_sel_hi:[1,0]
	v_pk_add_f32 v[180:181], v[172:173], 0 op_sel_hi:[1,0]
	ds_read_b128 v[98:101], v191 offset:33040
	ds_read_b128 v[172:175], v191 offset:33024
	v_lshlrev_b32_e32 v90, 16, v96
	v_and_b32_e32 v91, 0xffff0000, v96
	v_lshlrev_b32_e32 v96, 16, v97
	v_and_b32_e32 v97, 0xffff0000, v97
	v_lshlrev_b32_e32 v92, 16, v93
	v_and_b32_e32 v93, 0xffff0000, v93
	v_pk_add_f32 v[90:91], v[90:91], 0 op_sel_hi:[1,0]
	v_pk_add_f32 v[96:97], v[96:97], 0 op_sel_hi:[1,0]
	v_pk_add_f32 v[92:93], v[92:93], 0 op_sel_hi:[1,0]
	s_lshl_b32 s9, s10, 15
	s_add_i32 s9, s34, s9
	s_addk_i32 s37, 0x800
	s_ashr_i32 s12, s37, 31
	s_waitcnt lgkmcnt(5)
	v_pk_add_f32 v[90:91], v[90:91], v[154:155]
	v_pk_add_f32 v[96:97], v[96:97], v[156:157]
	s_waitcnt lgkmcnt(4)
	v_pk_add_f32 v[154:155], v[176:177], v[160:161]
	v_pk_add_f32 v[156:157], v[178:179], v[162:163]
	s_waitcnt lgkmcnt(3)
	v_pk_add_f32 v[160:161], v[180:181], v[164:165]
	v_pk_add_f32 v[164:165], v[92:93], v[166:167]
	v_pk_mul_f32 v[92:93], v[90:91], v[90:91]
	v_pk_mul_f32 v[162:163], v[96:97], v[96:97]
	v_pk_mul_f32 v[166:167], v[154:155], v[154:155]
	v_pk_mul_f32 v[176:177], v[156:157], v[156:157]
	v_fmamk_f32 v92, v92, 0xbdd2d3e7, v153
	v_fmamk_f32 v93, v93, 0xbdd2d3e7, v153
	v_fmamk_f32 v102, v162, 0xbdd2d3e7, v153
	v_fmamk_f32 v111, v163, 0xbdd2d3e7, v153
	v_fmamk_f32 v162, v166, 0xbdd2d3e7, v153
	v_fmamk_f32 v163, v167, 0xbdd2d3e7, v153
	v_fmamk_f32 v166, v176, 0xbdd2d3e7, v153
	v_fmamk_f32 v167, v177, 0xbdd2d3e7, v153
	v_mul_f32_e32 v92, v90, v92
	v_mul_f32_e32 v93, v91, v93
	v_mul_f32_e32 v102, v96, v102
	v_mul_f32_e32 v111, v97, v111
	v_mul_f32_e32 v162, v154, v162
	v_mul_f32_e32 v163, v155, v163
	v_mul_f32_e32 v166, v156, v166
	v_mul_f32_e32 v167, v157, v167
	v_exp_f32_e32 v92, v92
	v_exp_f32_e32 v93, v93
	v_exp_f32_e32 v102, v102
	v_exp_f32_e32 v111, v111
	v_exp_f32_e32 v162, v162
	v_exp_f32_e32 v163, v163
	v_pk_mul_f32 v[178:179], v[160:161], v[160:161]
	v_exp_f32_e32 v166, v166
	v_exp_f32_e32 v167, v167
	v_fmamk_f32 v176, v178, 0xbdd2d3e7, v153
	v_fmamk_f32 v177, v179, 0xbdd2d3e7, v153
	v_mul_f32_e32 v176, v160, v176
	v_mul_f32_e32 v177, v161, v177
	v_exp_f32_e32 v176, v176
	v_exp_f32_e32 v177, v177
	v_add_f32_e32 v92, 1.0, v92
	v_add_f32_e32 v93, 1.0, v93
	v_add_f32_e32 v102, 1.0, v102
	v_add_f32_e32 v111, 1.0, v111
	v_add_f32_e32 v178, 1.0, v162
	v_add_f32_e32 v179, 1.0, v163
	v_add_f32_e32 v182, 1.0, v166
	v_add_f32_e32 v183, 1.0, v167
	v_rcp_f32_e32 v92, v92
	v_rcp_f32_e32 v93, v93
	v_rcp_f32_e32 v162, v102
	v_rcp_f32_e32 v163, v111
	v_rcp_f32_e32 v166, v178
	v_rcp_f32_e32 v167, v179
	v_pk_mul_f32 v[180:181], v[164:165], v[164:165]
	v_add_f32_e32 v184, 1.0, v176
	v_add_f32_e32 v185, 1.0, v177
	v_rcp_f32_e32 v176, v182
	v_rcp_f32_e32 v177, v183
	v_fmamk_f32 v180, v180, 0xbdd2d3e7, v153
	v_pk_mul_f32 v[90:91], v[90:91], v[92:93]
	v_pk_mul_f32 v[92:93], v[96:97], v[162:163]
	v_pk_mul_f32 v[96:97], v[154:155], v[166:167]
	v_cvt_pk_bf16_f32 v90, v90, v91
	v_cvt_pk_bf16_f32 v91, v92, v93
	v_cvt_pk_bf16_f32 v92, v96, v97
	v_mul_f32_e32 v96, v164, v180
	v_exp_f32_e32 v102, v96
	v_fmamk_f32 v96, v181, 0xbdd2d3e7, v153
	v_pk_mul_f32 v[154:155], v[156:157], v[176:177]
	v_mul_f32_e32 v96, v165, v96
	v_cvt_pk_bf16_f32 v93, v154, v155
	v_exp_f32_e32 v111, v96
	v_lshlrev_b32_e32 v154, 16, v94
	v_and_b32_e32 v155, 0xffff0000, v94
	v_pk_add_f32 v[154:155], v[154:155], 0 op_sel_hi:[1,0]
	v_add_f32_e32 v102, 1.0, v102
	s_waitcnt lgkmcnt(2)
	v_pk_add_f32 v[168:169], v[154:155], v[168:169]
	v_rcp_f32_e32 v166, v102
	v_pk_mul_f32 v[154:155], v[168:169], v[168:169]
	v_add_f32_e32 v102, 1.0, v111
	v_fmamk_f32 v94, v154, 0xbdd2d3e7, v153
	v_fmamk_f32 v111, v155, 0xbdd2d3e7, v153
	v_lshlrev_b32_e32 v154, 16, v95
	v_and_b32_e32 v155, 0xffff0000, v95
	v_mul_f32_e32 v111, v169, v111
	v_pk_add_f32 v[154:155], v[154:155], 0 op_sel_hi:[1,0]
	v_exp_f32_e32 v111, v111
	v_pk_add_f32 v[170:171], v[154:155], v[170:171]
	v_rcp_f32_e32 v167, v102
	v_pk_mul_f32 v[154:155], v[170:171], v[170:171]
	v_add_f32_e32 v102, 1.0, v111
	v_fmamk_f32 v95, v154, 0xbdd2d3e7, v153
	v_mul_f32_e32 v95, v170, v95
	v_exp_f32_e32 v111, v95
	v_fmamk_f32 v95, v155, 0xbdd2d3e7, v153
	v_mul_f32_e32 v95, v171, v95
	v_rcp_f32_e32 v178, v184
	v_rcp_f32_e32 v179, v185
	v_exp_f32_e32 v154, v95
	v_rcp_f32_e32 v95, v102
	v_add_f32_e32 v102, 1.0, v111
	v_pk_mul_f32 v[96:97], v[160:161], v[178:179]
	v_rcp_f32_e32 v176, v102
	v_add_f32_e32 v102, 1.0, v154
	ds_read_b128 v[154:157], v191 offset:33168
	ds_read_b128 v[160:163], v191 offset:33152
	v_mul_f32_e32 v94, v168, v94
	v_exp_f32_e32 v94, v94
	v_pk_mul_f32 v[164:165], v[164:165], v[166:167]
	v_rcp_f32_e32 v177, v102
	v_add_f32_e32 v94, 1.0, v94
	v_rcp_f32_e32 v94, v94
	s_nop 0
	v_pk_mul_f32 v[166:167], v[168:169], v[94:95]
	v_cvt_pk_bf16_f32 v95, v164, v165
	v_lshlrev_b32_e32 v164, 16, v86
	v_and_b32_e32 v165, 0xffff0000, v86
	v_pk_add_f32 v[164:165], v[164:165], 0 op_sel_hi:[1,0]
	v_cvt_pk_bf16_f32 v94, v96, v97
	s_waitcnt lgkmcnt(2)
; DI bf16x8 pack8(f32x4 a, f32x4 b) { u32x4 p; p.x = pk2(a.x, a.y); p.y = pk2(a.z, a.w); p.z = pk2(b.x, b.y); p.w = pk2(b.z, b.w); return __builtin_bit_cast(bf16x8, p); }
; DI void w2_compute(const Args& a, LAS unsigned char* lds, int task, int lane, const u32x4 (&x0)[8], const u32x4 (&x1)[8]) {
;     ...
;     for (int ks = 0; ks < 8; ++ks) { const f32x4 c0 = *(const f32x4*)(cb + 32 * ks), c1 = *(const f32x4*)(cb + 32 * ks + 4);
;         f32x4 g0, g1;
;         g0.x = gelu_tanh(bf2f(x0[ks].x & 0xffffu) + bf2f(x1[ks].x & 0xffffu) + c0.x); g0.y = gelu_tanh(bf2f(x0[ks].x >> 16) + bf2f(x1[ks].x >> 16) + c0.y);
;         g0.z = gelu_tanh(bf2f(x0[ks].y & 0xffffu) + bf2f(x1[ks].y & 0xffffu) + c0.z); g0.w = gelu_tanh(bf2f(x0[ks].y >> 16) + bf2f(x1[ks].y >> 16) + c0.w);
;         g1.x = gelu_tanh(bf2f(x0[ks].z & 0xffffu) + bf2f(x1[ks].z & 0xffffu) + c1.x); g1.y = gelu_tanh(bf2f(x0[ks].z >> 16) + bf2f(x1[ks].z >> 16) + c1.y);
;         g1.z = gelu_tanh(bf2f(x0[ks].w & 0xffffu) + bf2f(x1[ks].w & 0xffffu) + c1.z); g1.w = gelu_tanh(bf2f(x0[ks].w >> 16) + bf2f(x1[ks].w >> 16) + c1.w);
;         af[ks] = pack8(g0, g1); }
	v_pk_add_f32 v[164:165], v[164:165], v[172:173]
	v_cvt_pk_bf16_f32 v96, v166, v167
	v_pk_mul_f32 v[166:167], v[164:165], v[164:165]
	v_pk_mul_f32 v[168:169], v[170:171], v[176:177]
	v_fmamk_f32 v86, v166, 0xbdd2d3e7, v153
	v_mul_f32_e32 v86, v164, v86
	v_fmamk_f32 v97, v167, 0xbdd2d3e7, v153
	v_exp_f32_e32 v86, v86
	v_mul_f32_e32 v97, v165, v97
	v_exp_f32_e32 v102, v97
	v_cvt_pk_bf16_f32 v97, v168, v169
	v_add_f32_e32 v86, 1.0, v86
	v_rcp_f32_e32 v166, v86
	v_add_f32_e32 v86, 1.0, v102
	v_rcp_f32_e32 v167, v86
	v_lshlrev_b32_e32 v86, 16, v87
	v_and_b32_e32 v87, 0xffff0000, v87
	v_pk_add_f32 v[86:87], v[86:87], 0 op_sel_hi:[1,0]
	s_nop 0
	v_pk_add_f32 v[86:87], v[86:87], v[174:175]
	s_nop 0
	v_pk_mul_f32 v[168:169], v[86:87], v[86:87]
	s_nop 0
	v_fmamk_f32 v102, v168, 0xbdd2d3e7, v153
	v_fmamk_f32 v111, v169, 0xbdd2d3e7, v153
	v_pk_mul_f32 v[168:169], v[164:165], v[166:167]
	v_lshlrev_b32_e32 v164, 16, v88
	v_and_b32_e32 v165, 0xffff0000, v88
	v_pk_add_f32 v[164:165], v[164:165], 0 op_sel_hi:[1,0]
	v_mul_f32_e32 v102, v86, v102
	v_pk_add_f32 v[172:173], v[164:165], v[98:99]
	v_exp_f32_e32 v102, v102
	v_pk_mul_f32 v[98:99], v[172:173], v[172:173]
	v_mul_f32_e32 v111, v87, v111
	v_fmamk_f32 v88, v98, 0xbdd2d3e7, v153
	v_fmamk_f32 v98, v99, 0xbdd2d3e7, v153
	v_exp_f32_e32 v111, v111
	v_mul_f32_e32 v98, v173, v98
	v_exp_f32_e32 v98, v98
	v_add_f32_e32 v102, 1.0, v102
	v_rcp_f32_e32 v170, v102
	v_add_f32_e32 v102, 1.0, v111
	v_rcp_f32_e32 v171, v102
	v_add_f32_e32 v102, 1.0, v98
	v_lshlrev_b32_e32 v98, 16, v89
	v_and_b32_e32 v99, 0xffff0000, v89
	v_pk_add_f32 v[98:99], v[98:99], 0 op_sel_hi:[1,0]
	v_mul_f32_e32 v88, v172, v88
	v_pk_add_f32 v[174:175], v[98:99], v[100:101]
	v_exp_f32_e32 v88, v88
	v_pk_mul_f32 v[98:99], v[174:175], v[174:175]
	v_pk_mul_f32 v[170:171], v[86:87], v[170:171]
	v_fmamk_f32 v89, v98, 0xbdd2d3e7, v153
	v_mul_f32_e32 v89, v174, v89
	v_exp_f32_e32 v98, v89
	v_fmamk_f32 v89, v99, 0xbdd2d3e7, v153
	v_mul_f32_e32 v89, v175, v89
	v_exp_f32_e32 v99, v89
	v_add_f32_e32 v98, 1.0, v98
	v_rcp_f32_e32 v176, v98
	v_add_f32_e32 v88, 1.0, v88
	v_add_f32_e32 v98, 1.0, v99
	v_rcp_f32_e32 v177, v98
	ds_read_b128 v[98:101], v191 offset:33296
	ds_read_b128 v[164:167], v191 offset:33280
	v_rcp_f32_e32 v88, v88
	v_rcp_f32_e32 v89, v102
	v_cvt_pk_bf16_f32 v86, v168, v169
	v_lshlrev_b32_e32 v168, 16, v82
	v_and_b32_e32 v169, 0xffff0000, v82
	v_pk_add_f32 v[168:169], v[168:169], 0 op_sel_hi:[1,0]
	v_pk_mul_f32 v[88:89], v[172:173], v[88:89]
	s_waitcnt lgkmcnt(2)
	v_pk_add_f32 v[160:161], v[168:169], v[160:161]
	v_cvt_pk_bf16_f32 v88, v88, v89
	v_pk_mul_f32 v[168:169], v[160:161], v[160:161]
	v_pk_mul_f32 v[172:173], v[174:175], v[176:177]
	v_fmamk_f32 v82, v168, 0xbdd2d3e7, v153
	v_mul_f32_e32 v82, v160, v82
	v_fmamk_f32 v89, v169, 0xbdd2d3e7, v153
	v_exp_f32_e32 v82, v82
	v_mul_f32_e32 v89, v161, v89
	v_exp_f32_e32 v102, v89
	v_cvt_pk_bf16_f32 v89, v172, v173
	v_add_f32_e32 v82, 1.0, v82
	v_rcp_f32_e32 v168, v82
	v_add_f32_e32 v82, 1.0, v102
	v_rcp_f32_e32 v169, v82
	v_lshlrev_b32_e32 v82, 16, v83
	v_and_b32_e32 v83, 0xffff0000, v83
	v_pk_add_f32 v[82:83], v[82:83], 0 op_sel_hi:[1,0]
	v_pk_mul_f32 v[168:169], v[160:161], v[168:169]
	v_pk_add_f32 v[82:83], v[82:83], v[162:163]
	v_lshlrev_b32_e32 v160, 16, v84
	v_pk_mul_f32 v[162:163], v[82:83], v[82:83]
	v_and_b32_e32 v161, 0xffff0000, v84
	v_fmamk_f32 v102, v162, 0xbdd2d3e7, v153
	v_mul_f32_e32 v102, v82, v102
	v_fmamk_f32 v111, v163, 0xbdd2d3e7, v153
	v_exp_f32_e32 v102, v102
	v_mul_f32_e32 v111, v83, v111
	v_exp_f32_e32 v111, v111
	v_pk_add_f32 v[160:161], v[160:161], 0 op_sel_hi:[1,0]
	v_add_f32_e32 v102, 1.0, v102
	v_pk_add_f32 v[172:173], v[160:161], v[154:155]
	v_cvt_pk_bf16_f32 v87, v170, v171
	v_pk_mul_f32 v[154:155], v[172:173], v[172:173]
	v_rcp_f32_e32 v170, v102
	v_add_f32_e32 v102, 1.0, v111
	v_fmamk_f32 v84, v154, 0xbdd2d3e7, v153
	v_fmamk_f32 v111, v155, 0xbdd2d3e7, v153
	v_lshlrev_b32_e32 v154, 16, v85
	v_and_b32_e32 v155, 0xffff0000, v85
	v_mul_f32_e32 v111, v173, v111
	v_pk_add_f32 v[154:155], v[154:155], 0 op_sel_hi:[1,0]
	v_exp_f32_e32 v111, v111
	v_pk_add_f32 v[174:175], v[154:155], v[156:157]
	v_rcp_f32_e32 v171, v102
	v_pk_mul_f32 v[154:155], v[174:175], v[174:175]
	v_add_f32_e32 v102, 1.0, v111
	v_fmamk_f32 v85, v154, 0xbdd2d3e7, v153
	v_mul_f32_e32 v85, v174, v85
	v_exp_f32_e32 v111, v85
	v_fmamk_f32 v85, v155, 0xbdd2d3e7, v153
	v_mul_f32_e32 v85, v175, v85
	v_exp_f32_e32 v154, v85
	v_rcp_f32_e32 v85, v102
	v_add_f32_e32 v102, 1.0, v111
	v_rcp_f32_e32 v176, v102
	v_add_f32_e32 v102, 1.0, v154
	ds_read_b128 v[154:157], v191 offset:33424
	ds_read_b128 v[160:163], v191 offset:33408
	v_mul_f32_e32 v84, v172, v84
	v_exp_f32_e32 v84, v84
	v_pk_mul_f32 v[170:171], v[82:83], v[170:171]
	v_cvt_pk_bf16_f32 v82, v168, v169
	v_lshlrev_b32_e32 v168, 16, v78
	v_add_f32_e32 v84, 1.0, v84
	v_rcp_f32_e32 v84, v84
	v_and_b32_e32 v169, 0xffff0000, v78
	v_pk_add_f32 v[168:169], v[168:169], 0 op_sel_hi:[1,0]
	v_rcp_f32_e32 v177, v102
	v_pk_mul_f32 v[84:85], v[172:173], v[84:85]
	v_cvt_pk_bf16_f32 v83, v170, v171
	v_cvt_pk_bf16_f32 v84, v84, v85
	v_pk_mul_f32 v[172:173], v[174:175], v[176:177]
	s_waitcnt lgkmcnt(2)
; DI bf16x8 pack8(f32x4 a, f32x4 b) { u32x4 p; p.x = pk2(a.x, a.y); p.y = pk2(a.z, a.w); p.z = pk2(b.x, b.y); p.w = pk2(b.z, b.w); return __builtin_bit_cast(bf16x8, p); }
; DI void w2_compute(const Args& a, LAS unsigned char* lds, int task, int lane, const u32x4 (&x0)[8], const u32x4 (&x1)[8]) {
;     ...
;     for (int ks = 0; ks < 8; ++ks) { const f32x4 c0 = *(const f32x4*)(cb + 32 * ks), c1 = *(const f32x4*)(cb + 32 * ks + 4);
;         f32x4 g0, g1;
;         g0.x = gelu_tanh(bf2f(x0[ks].x & 0xffffu) + bf2f(x1[ks].x & 0xffffu) + c0.x); g0.y = gelu_tanh(bf2f(x0[ks].x >> 16) + bf2f(x1[ks].x >> 16) + c0.y);
;         g0.z = gelu_tanh(bf2f(x0[ks].y & 0xffffu) + bf2f(x1[ks].y & 0xffffu) + c0.z); g0.w = gelu_tanh(bf2f(x0[ks].y >> 16) + bf2f(x1[ks].y >> 16) + c0.w);
;         g1.x = gelu_tanh(bf2f(x0[ks].z & 0xffffu) + bf2f(x1[ks].z & 0xffffu) + c1.x); g1.y = gelu_tanh(bf2f(x0[ks].z >> 16) + bf2f(x1[ks].z >> 16) + c1.y);
;         g1.z = gelu_tanh(bf2f(x0[ks].w & 0xffffu) + bf2f(x1[ks].w & 0xffffu) + c1.z); g1.w = gelu_tanh(bf2f(x0[ks].w >> 16) + bf2f(x1[ks].w >> 16) + c1.w);
;         af[ks] = pack8(g0, g1); }
	v_pk_add_f32 v[164:165], v[168:169], v[164:165]
	s_nop 0
	v_pk_mul_f32 v[168:169], v[164:165], v[164:165]
	s_nop 0
	v_fmamk_f32 v78, v168, 0xbdd2d3e7, v153
	v_mul_f32_e32 v78, v164, v78
	v_fmamk_f32 v85, v169, 0xbdd2d3e7, v153
	v_exp_f32_e32 v78, v78
	v_mul_f32_e32 v85, v165, v85
	v_exp_f32_e32 v102, v85
	v_cvt_pk_bf16_f32 v85, v172, v173
	v_add_f32_e32 v78, 1.0, v78
	v_rcp_f32_e32 v168, v78
	v_add_f32_e32 v78, 1.0, v102
	v_rcp_f32_e32 v169, v78
	v_lshlrev_b32_e32 v78, 16, v79
	v_and_b32_e32 v79, 0xffff0000, v79
	v_pk_add_f32 v[78:79], v[78:79], 0 op_sel_hi:[1,0]
	v_pk_mul_f32 v[168:169], v[164:165], v[168:169]
	v_pk_add_f32 v[78:79], v[78:79], v[166:167]
	v_lshlrev_b32_e32 v164, 16, v80
	v_and_b32_e32 v165, 0xffff0000, v80
	v_pk_mul_f32 v[166:167], v[78:79], v[78:79]
	v_pk_add_f32 v[164:165], v[164:165], 0 op_sel_hi:[1,0]
	v_fmamk_f32 v102, v166, 0xbdd2d3e7, v153
	v_pk_add_f32 v[172:173], v[164:165], v[98:99]
	v_mul_f32_e32 v102, v78, v102
	v_fmamk_f32 v111, v167, 0xbdd2d3e7, v153
	v_pk_mul_f32 v[98:99], v[172:173], v[172:173]
	v_exp_f32_e32 v102, v102
	v_mul_f32_e32 v111, v79, v111
	v_fmamk_f32 v80, v98, 0xbdd2d3e7, v153
	v_fmamk_f32 v98, v99, 0xbdd2d3e7, v153
	v_exp_f32_e32 v111, v111
	v_mul_f32_e32 v98, v173, v98
	v_exp_f32_e32 v98, v98
	v_add_f32_e32 v102, 1.0, v102
	v_rcp_f32_e32 v170, v102
	v_add_f32_e32 v102, 1.0, v111
	v_rcp_f32_e32 v171, v102
	v_add_f32_e32 v102, 1.0, v98
	v_lshlrev_b32_e32 v98, 16, v81
	v_and_b32_e32 v99, 0xffff0000, v81
	v_pk_add_f32 v[98:99], v[98:99], 0 op_sel_hi:[1,0]
	v_mul_f32_e32 v80, v172, v80
	v_pk_add_f32 v[174:175], v[98:99], v[100:101]
	v_exp_f32_e32 v80, v80
	v_pk_mul_f32 v[98:99], v[174:175], v[174:175]
	v_pk_mul_f32 v[170:171], v[78:79], v[170:171]
	v_fmamk_f32 v81, v98, 0xbdd2d3e7, v153
	v_mul_f32_e32 v81, v174, v81
	v_exp_f32_e32 v98, v81
	v_fmamk_f32 v81, v99, 0xbdd2d3e7, v153
	v_mul_f32_e32 v81, v175, v81
	v_exp_f32_e32 v99, v81
	v_add_f32_e32 v80, 1.0, v80
	v_rcp_f32_e32 v80, v80
	v_rcp_f32_e32 v81, v102
	v_add_f32_e32 v98, 1.0, v98
	v_rcp_f32_e32 v176, v98
	v_add_f32_e32 v98, 1.0, v99
	v_cvt_pk_bf16_f32 v78, v168, v169
	v_lshlrev_b32_e32 v168, 16, v74
	v_and_b32_e32 v169, 0xffff0000, v74
	v_rcp_f32_e32 v177, v98
	ds_read_b128 v[98:101], v191 offset:33552
	ds_read_b128 v[164:167], v191 offset:33536
	v_pk_add_f32 v[168:169], v[168:169], 0 op_sel_hi:[1,0]
	v_pk_mul_f32 v[80:81], v[172:173], v[80:81]
	s_waitcnt lgkmcnt(2)
	v_pk_add_f32 v[168:169], v[168:169], v[160:161]
	v_cvt_pk_bf16_f32 v80, v80, v81
	v_pk_mul_f32 v[160:161], v[168:169], v[168:169]
	v_cvt_pk_bf16_f32 v79, v170, v171
	v_fmamk_f32 v74, v160, 0xbdd2d3e7, v153
	v_fmamk_f32 v81, v161, 0xbdd2d3e7, v153
	v_lshlrev_b32_e32 v160, 16, v75
	v_and_b32_e32 v161, 0xffff0000, v75
	v_pk_add_f32 v[160:161], v[160:161], 0 op_sel_hi:[1,0]
	v_mul_f32_e32 v81, v169, v81
	v_pk_add_f32 v[170:171], v[160:161], v[162:163]
	v_exp_f32_e32 v102, v81
	v_pk_mul_f32 v[160:161], v[170:171], v[170:171]
	v_pk_mul_f32 v[172:173], v[174:175], v[176:177]
	v_fmamk_f32 v75, v160, 0xbdd2d3e7, v153
	v_mul_f32_e32 v75, v170, v75
	v_exp_f32_e32 v111, v75
	v_fmamk_f32 v75, v161, 0xbdd2d3e7, v153
	v_mul_f32_e32 v75, v171, v75
	v_exp_f32_e32 v160, v75
	v_add_f32_e32 v102, 1.0, v102
	v_rcp_f32_e32 v75, v102
	v_add_f32_e32 v102, 1.0, v111
	v_cvt_pk_bf16_f32 v81, v172, v173
	v_rcp_f32_e32 v172, v102
	v_add_f32_e32 v102, 1.0, v160
	v_lshlrev_b32_e32 v160, 16, v76
	v_and_b32_e32 v161, 0xffff0000, v76
	v_pk_add_f32 v[160:161], v[160:161], 0 op_sel_hi:[1,0]
	v_rcp_f32_e32 v173, v102
	v_pk_add_f32 v[174:175], v[160:161], v[154:155]
	v_mul_f32_e32 v74, v168, v74
	v_pk_mul_f32 v[154:155], v[174:175], v[174:175]
	v_exp_f32_e32 v74, v74
	v_fmamk_f32 v76, v154, 0xbdd2d3e7, v153
	v_fmamk_f32 v111, v155, 0xbdd2d3e7, v153
	v_lshlrev_b32_e32 v154, 16, v77
	v_and_b32_e32 v155, 0xffff0000, v77
	v_mul_f32_e32 v111, v175, v111
	v_pk_add_f32 v[154:155], v[154:155], 0 op_sel_hi:[1,0]
	v_exp_f32_e32 v111, v111
	v_pk_add_f32 v[176:177], v[154:155], v[156:157]
	v_mul_f32_e32 v76, v174, v76
	v_pk_mul_f32 v[154:155], v[176:177], v[176:177]
	v_add_f32_e32 v102, 1.0, v111
	v_fmamk_f32 v77, v154, 0xbdd2d3e7, v153
	v_mul_f32_e32 v77, v176, v77
	v_exp_f32_e32 v111, v77
	v_fmamk_f32 v77, v155, 0xbdd2d3e7, v153
	v_mul_f32_e32 v77, v177, v77
	v_exp_f32_e32 v154, v77
	v_rcp_f32_e32 v77, v102
	v_add_f32_e32 v102, 1.0, v111
	v_rcp_f32_e32 v178, v102
	v_add_f32_e32 v102, 1.0, v154
	ds_read_b128 v[154:157], v191 offset:33680
	ds_read_b128 v[160:163], v191 offset:33664
	v_add_f32_e32 v74, 1.0, v74
	v_exp_f32_e32 v76, v76
	v_rcp_f32_e32 v74, v74
	v_pk_mul_f32 v[112:113], v[170:171], v[172:173]
	v_rcp_f32_e32 v179, v102
	v_add_f32_e32 v76, 1.0, v76
	v_rcp_f32_e32 v76, v76
	v_pk_mul_f32 v[74:75], v[168:169], v[74:75]
	v_pk_mul_f32 v[168:169], v[176:177], v[178:179]
	v_cvt_pk_bf16_f32 v74, v74, v75
	v_cvt_pk_bf16_f32 v75, v112, v113
	v_lshlrev_b32_e32 v112, 16, v70
	v_and_b32_e32 v113, 0xffff0000, v70
	v_pk_add_f32 v[112:113], v[112:113], 0 op_sel_hi:[1,0]
	v_pk_mul_f32 v[76:77], v[174:175], v[76:77]
	s_waitcnt lgkmcnt(2)
; #define LAS __attribute__((address_space(3)))
; DI bf16x8 pack8(f32x4 a, f32x4 b) { u32x4 p; p.x = pk2(a.x, a.y); p.y = pk2(a.z, a.w); p.z = pk2(b.x, b.y); p.w = pk2(b.z, b.w); return __builtin_bit_cast(bf16x8, p); }
; DI void w2_compute(const Args& a, LAS unsigned char* lds, int task, int lane, const u32x4 (&x0)[8], const u32x4 (&x1)[8]) {
;     ...
;         g0.x = gelu_tanh(bf2f(x0[ks].x & 0xffffu) + bf2f(x1[ks].x & 0xffffu) + c0.x); g0.y = gelu_tanh(bf2f(x0[ks].x >> 16) + bf2f(x1[ks].x >> 16) + c0.y);
;         g0.z = gelu_tanh(bf2f(x0[ks].y & 0xffffu) + bf2f(x1[ks].y & 0xffffu) + c0.z); g0.w = gelu_tanh(bf2f(x0[ks].y >> 16) + bf2f(x1[ks].y >> 16) + c0.w);
;         g1.x = gelu_tanh(bf2f(x0[ks].z & 0xffffu) + bf2f(x1[ks].z & 0xffffu) + c1.x); g1.y = gelu_tanh(bf2f(x0[ks].z >> 16) + bf2f(x1[ks].z >> 16) + c1.y);
;         g1.z = gelu_tanh(bf2f(x0[ks].w & 0xffffu) + bf2f(x1[ks].w & 0xffffu) + c1.z); g1.w = gelu_tanh(bf2f(x0[ks].w >> 16) + bf2f(x1[ks].w >> 16) + c1.w);
;         af[ks] = pack8(g0, g1); }
;     const LAS unsigned char* wl = lds + W2_LDS + kind * 32768;
;     f32x4 acc[4];
; #pragma unroll
;     for (int nt = 0; nt < 4; ++nt) { acc[nt] = (f32x4){0.f, 0.f, 0.f, 0.f};
; #pragma unroll
;         for (int ks = 0; ks < 8; ++ks) { const bf16x8 wfr = *(const LAS bf16x8*)(wl + w2off(16 * (fr >> 2) + 4 * nt + (fr & 3), 4 * ks + fq)); acc[nt] = __builtin_amdgcn_mfma_f32_16x16x32_bf16(wfr, af[ks], acc[nt], 0, 0, 0); } }
	v_pk_add_f32 v[112:113], v[112:113], v[164:165]
	s_nop 0
	v_pk_mul_f32 v[164:165], v[112:113], v[112:113]
	v_cvt_pk_bf16_f32 v76, v76, v77
	v_fmamk_f32 v70, v164, 0xbdd2d3e7, v153
	v_fmamk_f32 v77, v165, 0xbdd2d3e7, v153
	v_lshlrev_b32_e32 v164, 16, v71
	v_and_b32_e32 v165, 0xffff0000, v71
	v_pk_add_f32 v[164:165], v[164:165], 0 op_sel_hi:[1,0]
	v_mul_f32_e32 v77, v113, v77
	v_pk_add_f32 v[164:165], v[164:165], v[166:167]
	v_exp_f32_e32 v102, v77
	v_pk_mul_f32 v[166:167], v[164:165], v[164:165]
	v_cvt_pk_bf16_f32 v77, v168, v169
	v_fmamk_f32 v71, v166, 0xbdd2d3e7, v153
	v_mul_f32_e32 v71, v164, v71
	v_exp_f32_e32 v111, v71
	v_lshlrev_b32_e32 v168, 16, v72
	v_and_b32_e32 v169, 0xffff0000, v72
	v_pk_add_f32 v[168:169], v[168:169], 0 op_sel_hi:[1,0]
	v_fmamk_f32 v71, v167, 0xbdd2d3e7, v153
	v_pk_add_f32 v[98:99], v[168:169], v[98:99]
	v_add_f32_e32 v102, 1.0, v102
	v_mul_f32_e32 v71, v165, v71
	v_pk_mul_f32 v[168:169], v[98:99], v[98:99]
	v_exp_f32_e32 v167, v71
	v_rcp_f32_e32 v71, v102
	v_add_f32_e32 v102, 1.0, v111
	v_fmamk_f32 v72, v168, 0xbdd2d3e7, v153
	v_fmamk_f32 v111, v169, 0xbdd2d3e7, v153
	v_lshlrev_b32_e32 v168, 16, v73
	v_and_b32_e32 v169, 0xffff0000, v73
	v_mul_f32_e32 v111, v99, v111
	v_pk_add_f32 v[168:169], v[168:169], 0 op_sel_hi:[1,0]
	v_exp_f32_e32 v111, v111
	v_pk_add_f32 v[100:101], v[168:169], v[100:101]
	v_rcp_f32_e32 v166, v102
	v_pk_mul_f32 v[168:169], v[100:101], v[100:101]
	v_add_f32_e32 v102, 1.0, v167
	v_fmamk_f32 v73, v168, 0xbdd2d3e7, v153
	v_mul_f32_e32 v73, v100, v73
	v_rcp_f32_e32 v167, v102
	v_add_f32_e32 v102, 1.0, v111
	v_exp_f32_e32 v111, v73
	v_fmamk_f32 v73, v169, 0xbdd2d3e7, v153
	v_mul_f32_e32 v72, v98, v72
	v_mul_f32_e32 v73, v101, v73
	v_exp_f32_e32 v72, v72
	v_exp_f32_e32 v169, v73
	v_mul_f32_e32 v70, v112, v70
	v_exp_f32_e32 v70, v70
	v_rcp_f32_e32 v73, v102
	v_add_f32_e32 v102, 1.0, v111
	v_add_f32_e32 v72, 1.0, v72
	v_rcp_f32_e32 v168, v102
	v_add_f32_e32 v102, 1.0, v169
	v_rcp_f32_e32 v72, v72
	v_rcp_f32_e32 v169, v102
	v_add_f32_e32 v70, 1.0, v70
	v_rcp_f32_e32 v70, v70
	v_pk_mul_f32 v[72:73], v[98:99], v[72:73]
	v_pk_mul_f32 v[98:99], v[100:101], v[168:169]
	v_lshlrev_b32_e32 v100, 16, v66
	v_and_b32_e32 v101, 0xffff0000, v66
	v_pk_add_f32 v[100:101], v[100:101], 0 op_sel_hi:[1,0]
	v_pk_mul_f32 v[70:71], v[112:113], v[70:71]
	v_pk_mul_f32 v[112:113], v[164:165], v[166:167]
	s_waitcnt lgkmcnt(0)
	v_pk_add_f32 v[100:101], v[100:101], v[160:161]
	v_cvt_pk_bf16_f32 v70, v70, v71
	v_cvt_pk_bf16_f32 v71, v112, v113
	v_pk_mul_f32 v[112:113], v[100:101], v[100:101]
	v_cvt_pk_bf16_f32 v72, v72, v73
	v_fmamk_f32 v66, v112, 0xbdd2d3e7, v153
	v_mul_f32_e32 v66, v100, v66
	v_fmamk_f32 v73, v113, 0xbdd2d3e7, v153
	v_exp_f32_e32 v66, v66
	v_mul_f32_e32 v73, v101, v73
	v_exp_f32_e32 v102, v73
	v_cvt_pk_bf16_f32 v73, v98, v99
	v_add_f32_e32 v66, 1.0, v66
	v_rcp_f32_e32 v98, v66
	v_add_f32_e32 v66, 1.0, v102
	v_rcp_f32_e32 v99, v66
	v_lshlrev_b32_e32 v66, 16, v67
	v_and_b32_e32 v67, 0xffff0000, v67
	v_pk_add_f32 v[66:67], v[66:67], 0 op_sel_hi:[1,0]
	v_pk_mul_f32 v[164:165], v[100:101], v[98:99]
	v_pk_add_f32 v[112:113], v[66:67], v[162:163]
	v_add_u32_e32 v102, s9, v114
	v_pk_mul_f32 v[66:67], v[112:113], v[112:113]
	v_add_u32_e32 v160, v102, v118
	v_fmamk_f32 v66, v66, 0xbdd2d3e7, v153
	v_mul_f32_e32 v66, v112, v66
	v_fmamk_f32 v67, v67, 0xbdd2d3e7, v153
	v_exp_f32_e32 v66, v66
	v_mul_f32_e32 v67, v113, v67
	v_exp_f32_e32 v67, v67
	ds_read_b128 v[160:163], v160
	v_add_f32_e32 v66, 1.0, v66
	v_rcp_f32_e32 v166, v66
	v_add_f32_e32 v98, 1.0, v67
	v_lshlrev_b32_e32 v66, 16, v68
	v_and_b32_e32 v67, 0xffff0000, v68
	v_pk_add_f32 v[66:67], v[66:67], 0 op_sel_hi:[1,0]
	v_rcp_f32_e32 v167, v98
	v_pk_add_f32 v[168:169], v[66:67], v[154:155]
	v_pk_mul_f32 v[112:113], v[112:113], v[166:167]
	v_pk_mul_f32 v[66:67], v[168:169], v[168:169]
	s_nop 0
	v_fmamk_f32 v66, v66, 0xbdd2d3e7, v153
	v_mul_f32_e32 v66, v168, v66
	v_fmamk_f32 v67, v67, 0xbdd2d3e7, v153
	v_exp_f32_e32 v66, v66
	v_mul_f32_e32 v67, v169, v67
	v_exp_f32_e32 v67, v67
	v_add_f32_e32 v66, 1.0, v66
	v_rcp_f32_e32 v170, v66
	v_add_f32_e32 v98, 1.0, v67
	v_lshlrev_b32_e32 v66, 16, v69
	v_and_b32_e32 v67, 0xffff0000, v69
	v_pk_add_f32 v[66:67], v[66:67], 0 op_sel_hi:[1,0]
	v_rcp_f32_e32 v171, v98
	v_pk_add_f32 v[172:173], v[66:67], v[156:157]
	v_add_u32_e32 v98, v102, v116
	v_pk_mul_f32 v[154:155], v[172:173], v[172:173]
	v_pk_mul_f32 v[166:167], v[168:169], v[170:171]
	v_fmamk_f32 v66, v154, 0xbdd2d3e7, v153
	v_mul_f32_e32 v66, v172, v66
	v_exp_f32_e32 v99, v66
	v_add_u32_e32 v66, v102, v115
	ds_read_b128 v[66:69], v66
	v_add_u32_e32 v154, v102, v117
	v_add_f32_e32 v111, 1.0, v99
	ds_read_b128 v[98:101], v98
	v_rcp_f32_e32 v174, v111
	v_fmamk_f32 v111, v155, 0xbdd2d3e7, v153
	ds_read_b128 v[154:157], v154
	s_waitcnt lgkmcnt(2)
	v_mfma_f32_16x16x32_bf16 v[66:69], v[66:69], v[90:93], 0
	v_mul_f32_e32 v111, v173, v111
	v_exp_f32_e32 v111, v111
	s_waitcnt lgkmcnt(1)
	v_mfma_f32_16x16x32_bf16 v[66:69], v[98:101], v[94:97], v[66:69]
	v_add_u32_e32 v98, v102, v119
	ds_read_b128 v[98:101], v98
	v_add_f32_e32 v111, 1.0, v111
	s_waitcnt lgkmcnt(1)
	v_mfma_f32_16x16x32_bf16 v[66:69], v[154:157], v[86:89], v[66:69]
	v_add_u32_e32 v154, v102, v120
	ds_read_b128 v[154:157], v154
	v_rcp_f32_e32 v175, v111
	v_mfma_f32_16x16x32_bf16 v[66:69], v[160:163], v[82:85], v[66:69]
	v_add_u32_e32 v111, v102, v121
	ds_read_b128 v[160:163], v111
	v_pk_mul_f32 v[168:169], v[172:173], v[174:175]
	s_waitcnt lgkmcnt(2)
	v_mfma_f32_16x16x32_bf16 v[66:69], v[98:101], v[78:81], v[66:69]
	v_add_u32_e32 v98, v102, v122
	ds_read_b128 v[98:101], v98
	v_add_u32_e32 v102, s9, v123
	s_waitcnt lgkmcnt(2)
; #define LAS __attribute__((address_space(3)))
; DI bf16x8 pack8(f32x4 a, f32x4 b) { u32x4 p; p.x = pk2(a.x, a.y); p.y = pk2(a.z, a.w); p.z = pk2(b.x, b.y); p.w = pk2(b.z, b.w); return __builtin_bit_cast(bf16x8, p); }
; DI void st8bf_(bf16_t* p, f32x4 v0, f32x4 v1) { u32x4 w; w.x = pk2(v0.x, v0.y); w.y = pk2(v0.z, v0.w); w.z = pk2(v1.x, v1.y); w.w = pk2(v1.z, v1.w); *(u32x4*)p = w; }
; DI void w2_compute(const Args& a, LAS unsigned char* lds, int task, int lane, const u32x4 (&x0)[8], const u32x4 (&x1)[8]) {
;     ...
;     const float* cb = (const float*)(ws + WS_CBIAS) + kind * 256 + 8 * fq;
;     bf16x8 af[8];
; #pragma unroll
;     for (int ks = 0; ks < 8; ++ks) { const f32x4 c0 = *(const f32x4*)(cb + 32 * ks), c1 = *(const f32x4*)(cb + 32 * ks + 4);
;         f32x4 g0, g1;
;         g0.x = gelu_tanh(bf2f(x0[ks].x & 0xffffu) + bf2f(x1[ks].x & 0xffffu) + c0.x); g0.y = gelu_tanh(bf2f(x0[ks].x >> 16) + bf2f(x1[ks].x >> 16) + c0.y);
;         g0.z = gelu_tanh(bf2f(x0[ks].y & 0xffffu) + bf2f(x1[ks].y & 0xffffu) + c0.z); g0.w = gelu_tanh(bf2f(x0[ks].y >> 16) + bf2f(x1[ks].y >> 16) + c0.w);
;         g1.x = gelu_tanh(bf2f(x0[ks].z & 0xffffu) + bf2f(x1[ks].z & 0xffffu) + c1.x); g1.y = gelu_tanh(bf2f(x0[ks].z >> 16) + bf2f(x1[ks].z >> 16) + c1.y);
;         g1.z = gelu_tanh(bf2f(x0[ks].w & 0xffffu) + bf2f(x1[ks].w & 0xffffu) + c1.z); g1.w = gelu_tanh(bf2f(x0[ks].w >> 16) + bf2f(x1[ks].w >> 16) + c1.w);
;         af[ks] = pack8(g0, g1); }
;     ...
;     for (int nt = 0; nt < 4; ++nt) { acc[nt] = (f32x4){0.f, 0.f, 0.f, 0.f};
; #pragma unroll
;         for (int ks = 0; ks < 8; ++ks) { const bf16x8 wfr = *(const LAS bf16x8*)(wl + w2off(16 * (fr >> 2) + 4 * nt + (fr & 3), 4 * ks + fq)); acc[nt] = __builtin_amdgcn_mfma_f32_16x16x32_bf16(wfr, af[ks], acc[nt], 0, 0, 0); } }
;     bf16_t* kc = (bf16_t*)(ws + WS_KC) + ((size_t)kind * AROWS + row0 + fr) * 64 + 16 * fq;
;     st8bf_(kc, acc[0], acc[1]); st8bf_(kc + 8, acc[2], acc[3]);
	v_mfma_f32_16x16x32_bf16 v[66:69], v[154:157], v[74:77], v[66:69]
	v_add_u32_e32 v111, v102, v124
	v_cvt_pk_bf16_f32 v154, v164, v165
	v_cvt_pk_bf16_f32 v155, v112, v113
	s_waitcnt lgkmcnt(1)
	v_mfma_f32_16x16x32_bf16 v[66:69], v[160:163], v[70:73], v[66:69]
	ds_read_b128 v[160:163], v111
	v_cvt_pk_bf16_f32 v156, v166, v167
	v_cvt_pk_bf16_f32 v157, v168, v169
	v_add_u32_e32 v111, v102, v126
	s_waitcnt lgkmcnt(0)
	v_mfma_f32_16x16x32_bf16 v[160:163], v[160:163], v[90:93], 0
	ds_read_b128 v[164:167], v111
	v_add_u32_e32 v111, v102, v127
	v_mfma_f32_16x16x32_bf16 v[66:69], v[98:101], v[154:157], v[66:69]
	v_add_u32_e32 v98, v102, v125
	ds_read_b128 v[98:101], v98
	s_waitcnt lgkmcnt(0)
	v_mfma_f32_16x16x32_bf16 v[98:101], v[98:101], v[94:97], v[160:163]
	s_nop 2
	ds_read_b128 v[160:163], v111
	v_add_u32_e32 v111, v102, v128
	v_cvt_pk_bf16_f32 v66, v66, v67
	v_mfma_f32_16x16x32_bf16 v[98:101], v[164:167], v[86:89], v[98:101]
	ds_read_b128 v[164:167], v111
	v_add_u32_e32 v111, v102, v129
	v_cvt_pk_bf16_f32 v67, v68, v69
	s_waitcnt lgkmcnt(1)
	v_mfma_f32_16x16x32_bf16 v[98:101], v[160:163], v[82:85], v[98:101]
	ds_read_b128 v[160:163], v111
	v_add_u32_e32 v111, v102, v130
	v_add_u32_e32 v102, v102, v131
	s_waitcnt lgkmcnt(1)
	v_mfma_f32_16x16x32_bf16 v[98:101], v[164:167], v[78:81], v[98:101]
	ds_read_b128 v[164:167], v111
	s_waitcnt lgkmcnt(1)
	v_mfma_f32_16x16x32_bf16 v[98:101], v[160:163], v[74:77], v[98:101]
	ds_read_b128 v[160:163], v102
	v_add_u32_e32 v102, s9, v132
	v_add_u32_e32 v111, v102, v133
	s_waitcnt lgkmcnt(1)
	v_mfma_f32_16x16x32_bf16 v[98:101], v[164:167], v[70:73], v[98:101]
	ds_read_b128 v[164:167], v111
	v_add_u32_e32 v111, v102, v134
	s_waitcnt lgkmcnt(1)
	v_mfma_f32_16x16x32_bf16 v[98:101], v[160:163], v[154:157], v[98:101]
	ds_read_b128 v[160:163], v111
	v_add_u32_e32 v111, v102, v135
	ds_read_b128 v[168:171], v111
	s_waitcnt lgkmcnt(2)
	v_mfma_f32_16x16x32_bf16 v[164:167], v[164:167], v[90:93], 0
	v_add_u32_e32 v111, v102, v136
	s_nop 1
	v_cvt_pk_bf16_f32 v68, v98, v99
	v_cvt_pk_bf16_f32 v69, v100, v101
	s_waitcnt lgkmcnt(1)
	v_mfma_f32_16x16x32_bf16 v[160:163], v[160:163], v[94:97], v[164:167]
	s_nop 2
	ds_read_b128 v[164:167], v111
	v_add_u32_e32 v111, v102, v137
	s_waitcnt lgkmcnt(1)
	v_mfma_f32_16x16x32_bf16 v[160:163], v[168:171], v[86:89], v[160:163]
	ds_read_b128 v[168:171], v111
	v_add_u32_e32 v111, v102, v138
	s_waitcnt lgkmcnt(1)
	v_mfma_f32_16x16x32_bf16 v[160:163], v[164:167], v[82:85], v[160:163]
	ds_read_b128 v[164:167], v111
	v_add_u32_e32 v111, v102, v139
	v_add_u32_e32 v102, v102, v140
	s_waitcnt lgkmcnt(1)
	v_mfma_f32_16x16x32_bf16 v[160:163], v[168:171], v[78:81], v[160:163]
	ds_read_b128 v[168:171], v111
	s_waitcnt lgkmcnt(1)
	v_mfma_f32_16x16x32_bf16 v[160:163], v[164:167], v[74:77], v[160:163]
	ds_read_b128 v[164:167], v102
	v_add_u32_e32 v102, s9, v141
	v_add_u32_e32 v111, v102, v142
	s_waitcnt lgkmcnt(1)
	v_mfma_f32_16x16x32_bf16 v[160:163], v[168:171], v[70:73], v[160:163]
	ds_read_b128 v[168:171], v111
	v_add_u32_e32 v111, v102, v143
	s_mul_hi_i32 s9, s10, 0x10800
	s_waitcnt lgkmcnt(1)
	v_mfma_f32_16x16x32_bf16 v[160:163], v[164:167], v[154:157], v[160:163]
	ds_read_b128 v[164:167], v111
	v_add_u32_e32 v111, v102, v144
	s_mul_i32 s10, s10, 0x10800
	s_waitcnt lgkmcnt(1)
	v_mfma_f32_16x16x32_bf16 v[90:93], v[168:171], v[90:93], 0
	ds_read_b128 v[168:171], v111
	s_add_u32 s10, s10, s37
	s_addc_u32 s9, s9, s12
	s_waitcnt lgkmcnt(1)
	v_mfma_f32_16x16x32_bf16 v[90:93], v[164:167], v[94:97], v[90:93]
	v_add_u32_e32 v94, v102, v145
	ds_read_b128 v[94:97], v94
	s_lshl_b32 s12, s8, 8
	s_waitcnt lgkmcnt(1)
	v_mfma_f32_16x16x32_bf16 v[86:89], v[168:171], v[86:89], v[90:93]
	s_ashr_i32 s13, s12, 31
	s_addk_i32 s11, 0x800
	s_nop 0
	v_add_u32_e32 v90, v102, v146
	ds_read_b128 v[90:93], v90
	s_waitcnt lgkmcnt(1)
	v_mfma_f32_16x16x32_bf16 v[82:85], v[94:97], v[82:85], v[86:89]
	s_nop 2
	v_add_u32_e32 v86, v102, v147
	ds_read_b128 v[86:89], v86
	s_waitcnt lgkmcnt(1)
	v_mfma_f32_16x16x32_bf16 v[78:81], v[90:93], v[78:81], v[82:85]
	s_nop 2
	v_add_u32_e32 v82, v102, v148
	ds_read_b128 v[82:85], v82
	s_waitcnt lgkmcnt(1)
	v_mfma_f32_16x16x32_bf16 v[74:77], v[86:89], v[74:77], v[78:81]
	s_waitcnt vmcnt(3)
	v_and_b32_e32 v87, 0xffff0000, v64
	s_nop 1
	v_add_u32_e32 v78, v102, v149
	ds_read_b128 v[78:81], v78
	s_waitcnt lgkmcnt(1)
	v_mfma_f32_16x16x32_bf16 v[70:73], v[82:85], v[70:73], v[74:77]
	v_lshlrev_b32_e32 v82, 16, v62
	s_nop 1
	v_mov_b32_e32 v75, s9
	v_or_b32_e32 v74, s10, v1
	s_waitcnt lgkmcnt(0)
	v_mfma_f32_16x16x32_bf16 v[70:73], v[78:81], v[154:157], v[70:73]
	v_lshlrev_b64 v[74:75], 7, v[74:75]
	v_lshl_add_u64 v[74:75], v[108:109], 0, v[74:75]
	global_store_dwordx4 v[74:75], v[66:69], off
	v_lshlrev_b32_e32 v80, 16, v58
	v_and_b32_e32 v81, 0xffff0000, v58
	v_cvt_pk_bf16_f32 v66, v160, v161
	v_cvt_pk_bf16_f32 v67, v162, v163
	s_nop 0
	v_cvt_pk_bf16_f32 v68, v70, v71
	v_cvt_pk_bf16_f32 v69, v72, v73
	global_store_dwordx4 v[74:75], v[66:69], off offset:16
	v_and_b32_e32 v83, 0xffff0000, v62
	v_pk_add_f32 v[80:81], v[82:83], v[80:81]
	v_lshl_add_u64 v[66:67], s[12:13], 2, v[106:107]
	v_lshl_add_u32 v192, s12, 2, v186
	ds_read_b128 v[68:71], v192 offset:32768
	ds_read_b128 v[72:75], v192 offset:32784
	ds_read_b128 v[76:79], v192 offset:32896
	v_lshlrev_b32_e32 v84, 16, v59
	v_and_b32_e32 v85, 0xffff0000, v59
	s_lshl_b32 s9, s8, 15
	s_add_i32 s9, s34, s9
	s_ashr_i32 s10, s11, 31
	s_waitcnt lgkmcnt(2)
; DI bf16x8 pack8(f32x4 a, f32x4 b) { u32x4 p; p.x = pk2(a.x, a.y); p.y = pk2(a.z, a.w); p.z = pk2(b.x, b.y); p.w = pk2(b.z, b.w); return __builtin_bit_cast(bf16x8, p); }
; DI void w2_compute(const Args& a, LAS unsigned char* lds, int task, int lane, const u32x4 (&x0)[8], const u32x4 (&x1)[8]) {
;     ...
;     for (int ks = 0; ks < 8; ++ks) { const f32x4 c0 = *(const f32x4*)(cb + 32 * ks), c1 = *(const f32x4*)(cb + 32 * ks + 4);
;         f32x4 g0, g1;
;         g0.x = gelu_tanh(bf2f(x0[ks].x & 0xffffu) + bf2f(x1[ks].x & 0xffffu) + c0.x); g0.y = gelu_tanh(bf2f(x0[ks].x >> 16) + bf2f(x1[ks].x >> 16) + c0.y);
;         g0.z = gelu_tanh(bf2f(x0[ks].y & 0xffffu) + bf2f(x1[ks].y & 0xffffu) + c0.z); g0.w = gelu_tanh(bf2f(x0[ks].y >> 16) + bf2f(x1[ks].y >> 16) + c0.w);
;         g1.x = gelu_tanh(bf2f(x0[ks].z & 0xffffu) + bf2f(x1[ks].z & 0xffffu) + c1.x); g1.y = gelu_tanh(bf2f(x0[ks].z >> 16) + bf2f(x1[ks].z >> 16) + c1.y);
;         g1.z = gelu_tanh(bf2f(x0[ks].w & 0xffffu) + bf2f(x1[ks].w & 0xffffu) + c1.z); g1.w = gelu_tanh(bf2f(x0[ks].w >> 16) + bf2f(x1[ks].w >> 16) + c1.w);
;         af[ks] = pack8(g0, g1); }
	v_pk_add_f32 v[68:69], v[80:81], v[68:69]
	s_nop 0
	v_pk_mul_f32 v[80:81], v[68:69], v[68:69]
	s_nop 0
	v_fmamk_f32 v58, v80, 0xbdd2d3e7, v153
	v_fmamk_f32 v62, v81, 0xbdd2d3e7, v153
	ds_read_b128 v[80:83], v192 offset:32912
	v_mul_f32_e32 v62, v69, v62
	v_exp_f32_e32 v62, v62
	v_mul_f32_e32 v58, v68, v58
	v_exp_f32_e32 v58, v58
	v_add_f32_e32 v86, 1.0, v62
	v_lshlrev_b32_e32 v62, 16, v63
	v_and_b32_e32 v63, 0xffff0000, v63
	v_pk_add_f32 v[62:63], v[62:63], v[84:85]
	v_lshlrev_b32_e32 v84, 16, v60
	v_pk_add_f32 v[62:63], v[62:63], v[70:71]
	v_and_b32_e32 v85, 0xffff0000, v60
	v_pk_mul_f32 v[70:71], v[62:63], v[62:63]
	v_add_f32_e32 v58, 1.0, v58
	v_fmamk_f32 v59, v70, 0xbdd2d3e7, v153
	v_mul_f32_e32 v59, v62, v59
	v_exp_f32_e32 v70, v59
	v_fmamk_f32 v59, v71, 0xbdd2d3e7, v153
	v_mul_f32_e32 v59, v63, v59
	v_exp_f32_e32 v71, v59
	v_rcp_f32_e32 v59, v86
	v_lshlrev_b32_e32 v86, 16, v64
	v_pk_add_f32 v[84:85], v[86:87], v[84:85]
	v_add_f32_e32 v70, 1.0, v70
	s_waitcnt lgkmcnt(2)
	v_pk_add_f32 v[72:73], v[84:85], v[72:73]
	v_add_f32_e32 v71, 1.0, v71
	v_pk_mul_f32 v[84:85], v[72:73], v[72:73]
	v_rcp_f32_e32 v58, v58
	v_fmamk_f32 v64, v85, 0xbdd2d3e7, v153
	v_mul_f32_e32 v64, v73, v64
	v_exp_f32_e32 v64, v64
	v_fmamk_f32 v60, v84, 0xbdd2d3e7, v153
	v_lshlrev_b32_e32 v84, 16, v61
	v_and_b32_e32 v85, 0xffff0000, v61
	v_add_f32_e32 v86, 1.0, v64
	v_lshlrev_b32_e32 v64, 16, v65
	v_and_b32_e32 v65, 0xffff0000, v65
	v_pk_add_f32 v[64:65], v[64:65], v[84:85]
	v_mul_f32_e32 v60, v72, v60
	v_pk_add_f32 v[64:65], v[64:65], v[74:75]
	v_exp_f32_e32 v60, v60
	v_pk_mul_f32 v[74:75], v[64:65], v[64:65]
	v_rcp_f32_e32 v70, v70
	v_fmamk_f32 v61, v74, 0xbdd2d3e7, v153
	v_mul_f32_e32 v61, v64, v61
	v_exp_f32_e32 v74, v61
	v_fmamk_f32 v61, v75, 0xbdd2d3e7, v153
	v_mul_f32_e32 v61, v65, v61
	v_exp_f32_e32 v75, v61
	v_add_f32_e32 v60, 1.0, v60
	v_add_f32_e32 v74, 1.0, v74
	v_rcp_f32_e32 v60, v60
	v_add_f32_e32 v75, 1.0, v75
	v_rcp_f32_e32 v61, v86
	v_rcp_f32_e32 v74, v74
	v_rcp_f32_e32 v75, v75
	v_rcp_f32_e32 v71, v71
	v_pk_mul_f32 v[60:61], v[72:73], v[60:61]
	s_waitcnt vmcnt(5)
	v_lshlrev_b32_e32 v84, 16, v54
	v_pk_mul_f32 v[72:73], v[64:65], v[74:75]
	v_lshlrev_b32_e32 v74, 16, v46
	v_and_b32_e32 v75, 0xffff0000, v46
	v_and_b32_e32 v85, 0xffff0000, v54
	v_pk_add_f32 v[74:75], v[84:85], v[74:75]
	v_pk_mul_f32 v[58:59], v[68:69], v[58:59]
	s_waitcnt lgkmcnt(1)
	v_pk_add_f32 v[74:75], v[74:75], v[76:77]
	v_pk_mul_f32 v[62:63], v[62:63], v[70:71]
	v_pk_mul_f32 v[76:77], v[74:75], v[74:75]
	v_cvt_pk_bf16_f32 v58, v58, v59
	v_fmamk_f32 v54, v77, 0xbdd2d3e7, v153
	v_cvt_pk_bf16_f32 v59, v62, v63
	ds_read_b128 v[62:65], v192 offset:33040
	ds_read_b128 v[68:71], v192 offset:33024
	v_mul_f32_e32 v54, v75, v54
	v_exp_f32_e32 v54, v54
	v_cvt_pk_bf16_f32 v60, v60, v61
	v_fmamk_f32 v46, v76, 0xbdd2d3e7, v153
	v_cvt_pk_bf16_f32 v61, v72, v73
	v_add_f32_e32 v76, 1.0, v54
	v_lshlrev_b32_e32 v72, 16, v47
	v_and_b32_e32 v73, 0xffff0000, v47
	v_lshlrev_b32_e32 v54, 16, v55
	v_and_b32_e32 v55, 0xffff0000, v55
	v_pk_add_f32 v[54:55], v[54:55], v[72:73]
	v_and_b32_e32 v77, 0xffff0000, v48
	v_pk_add_f32 v[54:55], v[54:55], v[78:79]
	v_lshlrev_b32_e32 v78, 16, v56
	v_pk_mul_f32 v[72:73], v[54:55], v[54:55]
	v_and_b32_e32 v79, 0xffff0000, v56
	v_fmamk_f32 v47, v72, 0xbdd2d3e7, v153
	v_mul_f32_e32 v47, v54, v47
	v_exp_f32_e32 v72, v47
	v_fmamk_f32 v47, v73, 0xbdd2d3e7, v153
	v_mul_f32_e32 v47, v55, v47
	v_exp_f32_e32 v73, v47
	v_rcp_f32_e32 v47, v76
	v_lshlrev_b32_e32 v76, 16, v48
	v_pk_add_f32 v[76:77], v[78:79], v[76:77]
	v_mul_f32_e32 v46, v74, v46
	s_waitcnt lgkmcnt(2)
	v_pk_add_f32 v[76:77], v[76:77], v[80:81]
	v_exp_f32_e32 v46, v46
	v_pk_mul_f32 v[78:79], v[76:77], v[76:77]
	v_add_f32_e32 v72, 1.0, v72
	v_fmamk_f32 v56, v79, 0xbdd2d3e7, v153
	v_mul_f32_e32 v56, v77, v56
	v_exp_f32_e32 v56, v56
	v_fmamk_f32 v48, v78, 0xbdd2d3e7, v153
	v_lshlrev_b32_e32 v78, 16, v49
	v_and_b32_e32 v79, 0xffff0000, v49
	v_add_f32_e32 v80, 1.0, v56
	v_lshlrev_b32_e32 v56, 16, v57
	v_and_b32_e32 v57, 0xffff0000, v57
	v_pk_add_f32 v[56:57], v[56:57], v[78:79]
	v_mul_f32_e32 v48, v76, v48
	v_pk_add_f32 v[56:57], v[56:57], v[82:83]
	v_exp_f32_e32 v48, v48
	v_pk_mul_f32 v[78:79], v[56:57], v[56:57]
	v_add_f32_e32 v46, 1.0, v46
	v_fmamk_f32 v49, v78, 0xbdd2d3e7, v153
	v_mul_f32_e32 v49, v56, v49
	v_exp_f32_e32 v78, v49
	v_fmamk_f32 v49, v79, 0xbdd2d3e7, v153
	v_mul_f32_e32 v49, v57, v49
	v_exp_f32_e32 v79, v49
	v_add_f32_e32 v73, 1.0, v73
	v_rcp_f32_e32 v46, v46
	v_rcp_f32_e32 v72, v72
	v_rcp_f32_e32 v73, v73
	v_add_f32_e32 v48, 1.0, v48
	v_add_f32_e32 v78, 1.0, v78
	v_add_f32_e32 v79, 1.0, v79
	v_rcp_f32_e32 v48, v48
	v_rcp_f32_e32 v49, v80
	v_rcp_f32_e32 v78, v78
	v_rcp_f32_e32 v79, v79
	v_pk_mul_f32 v[46:47], v[74:75], v[46:47]
	v_pk_mul_f32 v[54:55], v[54:55], v[72:73]
	v_pk_mul_f32 v[48:49], v[76:77], v[48:49]
	v_pk_mul_f32 v[76:77], v[56:57], v[78:79]
	v_cvt_pk_bf16_f32 v46, v46, v47
	v_cvt_pk_bf16_f32 v47, v54, v55
	ds_read_b128 v[54:57], v192 offset:33168
	ds_read_b128 v[72:75], v192 offset:33152
	s_waitcnt vmcnt(4)
	v_lshlrev_b32_e32 v78, 16, v42
	v_and_b32_e32 v79, 0xffff0000, v42
	s_waitcnt vmcnt(4)
	v_lshlrev_b32_e32 v80, 16, v50
	v_and_b32_e32 v81, 0xffff0000, v50
	v_pk_add_f32 v[78:79], v[80:81], v[78:79]
	v_cvt_pk_bf16_f32 v48, v48, v49
	s_waitcnt lgkmcnt(2)
; DI bf16x8 pack8(f32x4 a, f32x4 b) { u32x4 p; p.x = pk2(a.x, a.y); p.y = pk2(a.z, a.w); p.z = pk2(b.x, b.y); p.w = pk2(b.z, b.w); return __builtin_bit_cast(bf16x8, p); }
; DI void w2_compute(const Args& a, LAS unsigned char* lds, int task, int lane, const u32x4 (&x0)[8], const u32x4 (&x1)[8]) {
;     ...
;     for (int ks = 0; ks < 8; ++ks) { const f32x4 c0 = *(const f32x4*)(cb + 32 * ks), c1 = *(const f32x4*)(cb + 32 * ks + 4);
;         f32x4 g0, g1;
;         g0.x = gelu_tanh(bf2f(x0[ks].x & 0xffffu) + bf2f(x1[ks].x & 0xffffu) + c0.x); g0.y = gelu_tanh(bf2f(x0[ks].x >> 16) + bf2f(x1[ks].x >> 16) + c0.y);
;         g0.z = gelu_tanh(bf2f(x0[ks].y & 0xffffu) + bf2f(x1[ks].y & 0xffffu) + c0.z); g0.w = gelu_tanh(bf2f(x0[ks].y >> 16) + bf2f(x1[ks].y >> 16) + c0.w);
;         g1.x = gelu_tanh(bf2f(x0[ks].z & 0xffffu) + bf2f(x1[ks].z & 0xffffu) + c1.x); g1.y = gelu_tanh(bf2f(x0[ks].z >> 16) + bf2f(x1[ks].z >> 16) + c1.y);
;         g1.z = gelu_tanh(bf2f(x0[ks].w & 0xffffu) + bf2f(x1[ks].w & 0xffffu) + c1.z); g1.w = gelu_tanh(bf2f(x0[ks].w >> 16) + bf2f(x1[ks].w >> 16) + c1.w);
;         af[ks] = pack8(g0, g1); }
	v_pk_add_f32 v[68:69], v[78:79], v[68:69]
	s_nop 0
	v_pk_mul_f32 v[78:79], v[68:69], v[68:69]
	s_nop 0
	v_fmamk_f32 v49, v79, 0xbdd2d3e7, v153
	v_mul_f32_e32 v49, v69, v49
	v_exp_f32_e32 v50, v49
	v_fmamk_f32 v42, v78, 0xbdd2d3e7, v153
	v_cvt_pk_bf16_f32 v49, v76, v77
	v_lshlrev_b32_e32 v76, 16, v43
	v_add_f32_e32 v78, 1.0, v50
	v_and_b32_e32 v77, 0xffff0000, v43
	v_lshlrev_b32_e32 v50, 16, v51
	v_and_b32_e32 v51, 0xffff0000, v51
	v_pk_add_f32 v[50:51], v[50:51], v[76:77]
	v_lshlrev_b32_e32 v76, 16, v44
	v_pk_add_f32 v[50:51], v[50:51], v[70:71]
	v_and_b32_e32 v77, 0xffff0000, v44
	v_pk_mul_f32 v[70:71], v[50:51], v[50:51]
	v_and_b32_e32 v79, 0xffff0000, v52
	v_fmamk_f32 v43, v70, 0xbdd2d3e7, v153
	v_mul_f32_e32 v43, v50, v43
	v_exp_f32_e32 v70, v43
	v_fmamk_f32 v43, v71, 0xbdd2d3e7, v153
	v_mul_f32_e32 v43, v51, v43
	v_exp_f32_e32 v71, v43
	v_rcp_f32_e32 v43, v78
	v_lshlrev_b32_e32 v78, 16, v52
	v_pk_add_f32 v[76:77], v[78:79], v[76:77]
	v_mul_f32_e32 v42, v68, v42
	v_pk_add_f32 v[62:63], v[76:77], v[62:63]
	v_exp_f32_e32 v42, v42
	v_pk_mul_f32 v[76:77], v[62:63], v[62:63]
	v_add_f32_e32 v70, 1.0, v70
	v_fmamk_f32 v52, v77, 0xbdd2d3e7, v153
	v_mul_f32_e32 v52, v63, v52
	v_exp_f32_e32 v52, v52
	v_fmamk_f32 v44, v76, 0xbdd2d3e7, v153
	v_lshlrev_b32_e32 v76, 16, v45
	v_and_b32_e32 v77, 0xffff0000, v45
	v_add_f32_e32 v78, 1.0, v52
	v_lshlrev_b32_e32 v52, 16, v53
	v_and_b32_e32 v53, 0xffff0000, v53
	v_pk_add_f32 v[52:53], v[52:53], v[76:77]
	v_add_f32_e32 v71, 1.0, v71
	v_pk_add_f32 v[52:53], v[52:53], v[64:65]
	v_mul_f32_e32 v44, v62, v44
	v_pk_mul_f32 v[64:65], v[52:53], v[52:53]
	v_rcp_f32_e32 v70, v70
	v_fmamk_f32 v45, v64, 0xbdd2d3e7, v153
	v_mul_f32_e32 v45, v52, v45
	v_exp_f32_e32 v64, v45
	v_fmamk_f32 v45, v65, 0xbdd2d3e7, v153
	v_mul_f32_e32 v45, v53, v45
	v_exp_f32_e32 v44, v44
	v_rcp_f32_e32 v71, v71
	v_exp_f32_e32 v65, v45
	v_add_f32_e32 v42, 1.0, v42
	v_rcp_f32_e32 v42, v42
	v_add_f32_e32 v44, 1.0, v44
	v_add_f32_e32 v64, 1.0, v64
	v_add_f32_e32 v65, 1.0, v65
	v_pk_mul_f32 v[50:51], v[50:51], v[70:71]
	v_lshlrev_b32_e32 v70, 16, v30
	v_and_b32_e32 v71, 0xffff0000, v30
	s_waitcnt vmcnt(4)
	v_lshlrev_b32_e32 v76, 16, v38
	v_and_b32_e32 v77, 0xffff0000, v38
	v_rcp_f32_e32 v44, v44
	v_rcp_f32_e32 v45, v78
	v_rcp_f32_e32 v64, v64
	v_rcp_f32_e32 v65, v65
	v_pk_add_f32 v[70:71], v[76:77], v[70:71]
	v_pk_mul_f32 v[42:43], v[68:69], v[42:43]
	s_waitcnt lgkmcnt(0)
	v_pk_add_f32 v[70:71], v[70:71], v[72:73]
	v_pk_mul_f32 v[44:45], v[62:63], v[44:45]
	v_pk_mul_f32 v[72:73], v[70:71], v[70:71]
	v_pk_mul_f32 v[68:69], v[52:53], v[64:65]
	v_fmamk_f32 v38, v73, 0xbdd2d3e7, v153
	v_cvt_pk_bf16_f32 v42, v42, v43
	v_cvt_pk_bf16_f32 v43, v50, v51
	ds_read_b128 v[50:53], v192 offset:33296
	ds_read_b128 v[62:65], v192 offset:33280
	v_mul_f32_e32 v38, v71, v38
	v_exp_f32_e32 v38, v38
	v_cvt_pk_bf16_f32 v44, v44, v45
	v_fmamk_f32 v30, v72, 0xbdd2d3e7, v153
	v_cvt_pk_bf16_f32 v45, v68, v69
	v_add_f32_e32 v72, 1.0, v38
	v_lshlrev_b32_e32 v68, 16, v31
	v_and_b32_e32 v69, 0xffff0000, v31
	v_lshlrev_b32_e32 v38, 16, v39
	v_and_b32_e32 v39, 0xffff0000, v39
	v_pk_add_f32 v[38:39], v[38:39], v[68:69]
	v_and_b32_e32 v73, 0xffff0000, v32
	v_pk_add_f32 v[38:39], v[38:39], v[74:75]
	v_lshlrev_b32_e32 v74, 16, v40
	v_pk_mul_f32 v[68:69], v[38:39], v[38:39]
	v_and_b32_e32 v75, 0xffff0000, v40
	v_fmamk_f32 v31, v68, 0xbdd2d3e7, v153
	v_mul_f32_e32 v31, v38, v31
	v_exp_f32_e32 v68, v31
	v_fmamk_f32 v31, v69, 0xbdd2d3e7, v153
	v_mul_f32_e32 v31, v39, v31
	v_exp_f32_e32 v69, v31
	v_rcp_f32_e32 v31, v72
	v_lshlrev_b32_e32 v72, 16, v32
	v_pk_add_f32 v[72:73], v[74:75], v[72:73]
	v_mul_f32_e32 v30, v70, v30
	v_pk_add_f32 v[54:55], v[72:73], v[54:55]
	v_exp_f32_e32 v30, v30
	v_pk_mul_f32 v[72:73], v[54:55], v[54:55]
	v_add_f32_e32 v68, 1.0, v68
	v_fmamk_f32 v40, v73, 0xbdd2d3e7, v153
	v_mul_f32_e32 v40, v55, v40
	v_exp_f32_e32 v40, v40
	v_fmamk_f32 v32, v72, 0xbdd2d3e7, v153
	v_lshlrev_b32_e32 v72, 16, v33
	v_and_b32_e32 v73, 0xffff0000, v33
	v_add_f32_e32 v74, 1.0, v40
	v_lshlrev_b32_e32 v40, 16, v41
	v_and_b32_e32 v41, 0xffff0000, v41
	v_pk_add_f32 v[40:41], v[40:41], v[72:73]
	v_mul_f32_e32 v32, v54, v32
	v_pk_add_f32 v[40:41], v[40:41], v[56:57]
	v_exp_f32_e32 v32, v32
	v_pk_mul_f32 v[56:57], v[40:41], v[40:41]
	v_add_f32_e32 v30, 1.0, v30
	v_fmamk_f32 v33, v56, 0xbdd2d3e7, v153
	v_mul_f32_e32 v33, v40, v33
	v_exp_f32_e32 v56, v33
	v_fmamk_f32 v33, v57, 0xbdd2d3e7, v153
	v_mul_f32_e32 v33, v41, v33
	v_exp_f32_e32 v57, v33
	v_add_f32_e32 v69, 1.0, v69
	v_rcp_f32_e32 v30, v30
	v_rcp_f32_e32 v68, v68
	v_rcp_f32_e32 v69, v69
	v_add_f32_e32 v32, 1.0, v32
	v_add_f32_e32 v56, 1.0, v56
	v_add_f32_e32 v57, 1.0, v57
	v_rcp_f32_e32 v32, v32
	v_rcp_f32_e32 v33, v74
	v_rcp_f32_e32 v56, v56
	v_rcp_f32_e32 v57, v57
	v_pk_mul_f32 v[30:31], v[70:71], v[30:31]
	v_pk_mul_f32 v[38:39], v[38:39], v[68:69]
	v_pk_mul_f32 v[32:33], v[54:55], v[32:33]
	v_pk_mul_f32 v[68:69], v[40:41], v[56:57]
	v_cvt_pk_bf16_f32 v30, v30, v31
	v_cvt_pk_bf16_f32 v31, v38, v39
	ds_read_b128 v[38:41], v192 offset:33424
	ds_read_b128 v[54:57], v192 offset:33408
	s_waitcnt vmcnt(3)
	v_lshlrev_b32_e32 v70, 16, v26
	v_and_b32_e32 v71, 0xffff0000, v26
	s_waitcnt vmcnt(3)
	v_lshlrev_b32_e32 v72, 16, v34
	v_and_b32_e32 v73, 0xffff0000, v34
	v_pk_add_f32 v[70:71], v[72:73], v[70:71]
	v_cvt_pk_bf16_f32 v32, v32, v33
	s_waitcnt lgkmcnt(2)
; DI bf16x8 pack8(f32x4 a, f32x4 b) { u32x4 p; p.x = pk2(a.x, a.y); p.y = pk2(a.z, a.w); p.z = pk2(b.x, b.y); p.w = pk2(b.z, b.w); return __builtin_bit_cast(bf16x8, p); }
; DI void w2_compute(const Args& a, LAS unsigned char* lds, int task, int lane, const u32x4 (&x0)[8], const u32x4 (&x1)[8]) {
;     ...
;     for (int ks = 0; ks < 8; ++ks) { const f32x4 c0 = *(const f32x4*)(cb + 32 * ks), c1 = *(const f32x4*)(cb + 32 * ks + 4);
;         f32x4 g0, g1;
;         g0.x = gelu_tanh(bf2f(x0[ks].x & 0xffffu) + bf2f(x1[ks].x & 0xffffu) + c0.x); g0.y = gelu_tanh(bf2f(x0[ks].x >> 16) + bf2f(x1[ks].x >> 16) + c0.y);
;         g0.z = gelu_tanh(bf2f(x0[ks].y & 0xffffu) + bf2f(x1[ks].y & 0xffffu) + c0.z); g0.w = gelu_tanh(bf2f(x0[ks].y >> 16) + bf2f(x1[ks].y >> 16) + c0.w);
;         g1.x = gelu_tanh(bf2f(x0[ks].z & 0xffffu) + bf2f(x1[ks].z & 0xffffu) + c1.x); g1.y = gelu_tanh(bf2f(x0[ks].z >> 16) + bf2f(x1[ks].z >> 16) + c1.y);
;         g1.z = gelu_tanh(bf2f(x0[ks].w & 0xffffu) + bf2f(x1[ks].w & 0xffffu) + c1.z); g1.w = gelu_tanh(bf2f(x0[ks].w >> 16) + bf2f(x1[ks].w >> 16) + c1.w);
;         af[ks] = pack8(g0, g1); }
	v_pk_add_f32 v[62:63], v[70:71], v[62:63]
	s_nop 0
	v_pk_mul_f32 v[70:71], v[62:63], v[62:63]
	s_nop 0
	v_fmamk_f32 v33, v71, 0xbdd2d3e7, v153
	v_mul_f32_e32 v33, v63, v33
	v_exp_f32_e32 v34, v33
	v_fmamk_f32 v26, v70, 0xbdd2d3e7, v153
	v_cvt_pk_bf16_f32 v33, v68, v69
	v_lshlrev_b32_e32 v68, 16, v27
	v_add_f32_e32 v70, 1.0, v34
	v_and_b32_e32 v69, 0xffff0000, v27
	v_lshlrev_b32_e32 v34, 16, v35
	v_and_b32_e32 v35, 0xffff0000, v35
	v_pk_add_f32 v[34:35], v[34:35], v[68:69]
	v_lshlrev_b32_e32 v68, 16, v28
	v_pk_add_f32 v[34:35], v[34:35], v[64:65]
	v_and_b32_e32 v69, 0xffff0000, v28
	v_pk_mul_f32 v[64:65], v[34:35], v[34:35]
	v_and_b32_e32 v71, 0xffff0000, v36
	v_fmamk_f32 v27, v64, 0xbdd2d3e7, v153
	v_mul_f32_e32 v27, v34, v27
	v_exp_f32_e32 v64, v27
	v_fmamk_f32 v27, v65, 0xbdd2d3e7, v153
	v_mul_f32_e32 v27, v35, v27
	v_exp_f32_e32 v65, v27
	v_rcp_f32_e32 v27, v70
	v_lshlrev_b32_e32 v70, 16, v36
	v_pk_add_f32 v[68:69], v[70:71], v[68:69]
	v_mul_f32_e32 v26, v62, v26
	v_pk_add_f32 v[50:51], v[68:69], v[50:51]
	v_exp_f32_e32 v26, v26
	v_pk_mul_f32 v[68:69], v[50:51], v[50:51]
	v_add_f32_e32 v64, 1.0, v64
	v_fmamk_f32 v36, v69, 0xbdd2d3e7, v153
	v_mul_f32_e32 v36, v51, v36
	v_exp_f32_e32 v36, v36
	v_fmamk_f32 v28, v68, 0xbdd2d3e7, v153
	v_lshlrev_b32_e32 v68, 16, v29
	v_and_b32_e32 v69, 0xffff0000, v29
	v_add_f32_e32 v70, 1.0, v36
	v_lshlrev_b32_e32 v36, 16, v37
	v_and_b32_e32 v37, 0xffff0000, v37
	v_pk_add_f32 v[36:37], v[36:37], v[68:69]
	v_add_f32_e32 v65, 1.0, v65
	v_pk_add_f32 v[36:37], v[36:37], v[52:53]
	v_mul_f32_e32 v28, v50, v28
	v_pk_mul_f32 v[52:53], v[36:37], v[36:37]
	v_rcp_f32_e32 v64, v64
	v_fmamk_f32 v29, v52, 0xbdd2d3e7, v153
	v_mul_f32_e32 v29, v36, v29
	v_exp_f32_e32 v52, v29
	v_fmamk_f32 v29, v53, 0xbdd2d3e7, v153
	v_mul_f32_e32 v29, v37, v29
	v_exp_f32_e32 v28, v28
	v_rcp_f32_e32 v65, v65
	v_exp_f32_e32 v53, v29
	v_add_f32_e32 v26, 1.0, v26
	v_rcp_f32_e32 v26, v26
	v_add_f32_e32 v28, 1.0, v28
	v_add_f32_e32 v52, 1.0, v52
	v_add_f32_e32 v53, 1.0, v53
	v_pk_mul_f32 v[34:35], v[34:35], v[64:65]
	v_lshlrev_b32_e32 v64, 16, v14
	v_and_b32_e32 v65, 0xffff0000, v14
	s_waitcnt vmcnt(3)
	v_lshlrev_b32_e32 v68, 16, v22
	v_and_b32_e32 v69, 0xffff0000, v22
	v_rcp_f32_e32 v28, v28
	v_rcp_f32_e32 v29, v70
	v_rcp_f32_e32 v52, v52
	v_rcp_f32_e32 v53, v53
	v_pk_add_f32 v[64:65], v[68:69], v[64:65]
	v_pk_mul_f32 v[26:27], v[62:63], v[26:27]
	s_waitcnt lgkmcnt(0)
	v_pk_add_f32 v[54:55], v[64:65], v[54:55]
	v_pk_mul_f32 v[28:29], v[50:51], v[28:29]
	v_pk_mul_f32 v[64:65], v[54:55], v[54:55]
	v_pk_mul_f32 v[62:63], v[36:37], v[52:53]
	v_fmamk_f32 v22, v65, 0xbdd2d3e7, v153
	v_cvt_pk_bf16_f32 v26, v26, v27
	v_cvt_pk_bf16_f32 v27, v34, v35
	ds_read_b128 v[34:37], v192 offset:33552
	ds_read_b128 v[50:53], v192 offset:33536
	v_mul_f32_e32 v22, v55, v22
	v_exp_f32_e32 v22, v22
	v_cvt_pk_bf16_f32 v28, v28, v29
	v_fmamk_f32 v14, v64, 0xbdd2d3e7, v153
	v_cvt_pk_bf16_f32 v29, v62, v63
	v_add_f32_e32 v64, 1.0, v22
	v_lshlrev_b32_e32 v62, 16, v15
	v_and_b32_e32 v63, 0xffff0000, v15
	v_lshlrev_b32_e32 v22, 16, v23
	v_and_b32_e32 v23, 0xffff0000, v23
	v_pk_add_f32 v[22:23], v[22:23], v[62:63]
	v_lshlrev_b32_e32 v62, 16, v16
	v_pk_add_f32 v[22:23], v[22:23], v[56:57]
	v_and_b32_e32 v63, 0xffff0000, v16
	v_pk_mul_f32 v[56:57], v[22:23], v[22:23]
	v_and_b32_e32 v65, 0xffff0000, v24
	v_fmamk_f32 v15, v56, 0xbdd2d3e7, v153
	v_mul_f32_e32 v15, v22, v15
	v_exp_f32_e32 v56, v15
	v_fmamk_f32 v15, v57, 0xbdd2d3e7, v153
	v_mul_f32_e32 v15, v23, v15
	v_exp_f32_e32 v57, v15
	v_rcp_f32_e32 v15, v64
	v_lshlrev_b32_e32 v64, 16, v24
	v_pk_add_f32 v[62:63], v[64:65], v[62:63]
	v_mul_f32_e32 v14, v54, v14
	v_pk_add_f32 v[38:39], v[62:63], v[38:39]
	v_exp_f32_e32 v14, v14
	v_pk_mul_f32 v[62:63], v[38:39], v[38:39]
	v_add_f32_e32 v56, 1.0, v56
	v_fmamk_f32 v24, v63, 0xbdd2d3e7, v153
	v_mul_f32_e32 v24, v39, v24
	v_exp_f32_e32 v24, v24
	v_fmamk_f32 v16, v62, 0xbdd2d3e7, v153
	v_lshlrev_b32_e32 v62, 16, v17
	v_and_b32_e32 v63, 0xffff0000, v17
	v_add_f32_e32 v64, 1.0, v24
	v_lshlrev_b32_e32 v24, 16, v25
	v_and_b32_e32 v25, 0xffff0000, v25
	v_pk_add_f32 v[24:25], v[24:25], v[62:63]
	v_mul_f32_e32 v16, v38, v16
	v_pk_add_f32 v[24:25], v[24:25], v[40:41]
	v_exp_f32_e32 v16, v16
	v_pk_mul_f32 v[40:41], v[24:25], v[24:25]
	v_add_f32_e32 v14, 1.0, v14
	v_fmamk_f32 v17, v40, 0xbdd2d3e7, v153
	v_mul_f32_e32 v17, v24, v17
	v_exp_f32_e32 v40, v17
	v_fmamk_f32 v17, v41, 0xbdd2d3e7, v153
	v_mul_f32_e32 v17, v25, v17
	v_exp_f32_e32 v41, v17
	v_add_f32_e32 v57, 1.0, v57
	v_rcp_f32_e32 v14, v14
	v_rcp_f32_e32 v56, v56
	v_rcp_f32_e32 v57, v57
	v_add_f32_e32 v16, 1.0, v16
	v_add_f32_e32 v40, 1.0, v40
	v_add_f32_e32 v41, 1.0, v41
	v_rcp_f32_e32 v16, v16
	v_rcp_f32_e32 v17, v64
	v_rcp_f32_e32 v40, v40
	v_rcp_f32_e32 v41, v41
	v_pk_mul_f32 v[14:15], v[54:55], v[14:15]
	v_pk_mul_f32 v[22:23], v[22:23], v[56:57]
	v_pk_mul_f32 v[16:17], v[38:39], v[16:17]
	v_pk_mul_f32 v[54:55], v[24:25], v[40:41]
	v_cvt_pk_bf16_f32 v14, v14, v15
	v_cvt_pk_bf16_f32 v15, v22, v23
	ds_read_b128 v[22:25], v192 offset:33680
	ds_read_b128 v[38:41], v192 offset:33664
	s_waitcnt vmcnt(2)
	v_lshlrev_b32_e32 v56, 16, v10
	v_and_b32_e32 v57, 0xffff0000, v10
	s_waitcnt vmcnt(2)
	v_lshlrev_b32_e32 v62, 16, v18
	v_and_b32_e32 v63, 0xffff0000, v18
	v_pk_add_f32 v[56:57], v[62:63], v[56:57]
	v_cvt_pk_bf16_f32 v16, v16, v17
	s_waitcnt lgkmcnt(2)
; #define LAS __attribute__((address_space(3)))
; DI bf16x8 pack8(f32x4 a, f32x4 b) { u32x4 p; p.x = pk2(a.x, a.y); p.y = pk2(a.z, a.w); p.z = pk2(b.x, b.y); p.w = pk2(b.z, b.w); return __builtin_bit_cast(bf16x8, p); }
; DI void w2_compute(const Args& a, LAS unsigned char* lds, int task, int lane, const u32x4 (&x0)[8], const u32x4 (&x1)[8]) {
;     ...
;     for (int ks = 0; ks < 8; ++ks) { const f32x4 c0 = *(const f32x4*)(cb + 32 * ks), c1 = *(const f32x4*)(cb + 32 * ks + 4);
;         f32x4 g0, g1;
;         g0.x = gelu_tanh(bf2f(x0[ks].x & 0xffffu) + bf2f(x1[ks].x & 0xffffu) + c0.x); g0.y = gelu_tanh(bf2f(x0[ks].x >> 16) + bf2f(x1[ks].x >> 16) + c0.y);
;         g0.z = gelu_tanh(bf2f(x0[ks].y & 0xffffu) + bf2f(x1[ks].y & 0xffffu) + c0.z); g0.w = gelu_tanh(bf2f(x0[ks].y >> 16) + bf2f(x1[ks].y >> 16) + c0.w);
;         g1.x = gelu_tanh(bf2f(x0[ks].z & 0xffffu) + bf2f(x1[ks].z & 0xffffu) + c1.x); g1.y = gelu_tanh(bf2f(x0[ks].z >> 16) + bf2f(x1[ks].z >> 16) + c1.y);
;         g1.z = gelu_tanh(bf2f(x0[ks].w & 0xffffu) + bf2f(x1[ks].w & 0xffffu) + c1.z); g1.w = gelu_tanh(bf2f(x0[ks].w >> 16) + bf2f(x1[ks].w >> 16) + c1.w);
;         af[ks] = pack8(g0, g1); }
;     const LAS unsigned char* wl = lds + W2_LDS + kind * 32768;
;     f32x4 acc[4];
; #pragma unroll
;     for (int nt = 0; nt < 4; ++nt) { acc[nt] = (f32x4){0.f, 0.f, 0.f, 0.f};
; #pragma unroll
;         for (int ks = 0; ks < 8; ++ks) { const bf16x8 wfr = *(const LAS bf16x8*)(wl + w2off(16 * (fr >> 2) + 4 * nt + (fr & 3), 4 * ks + fq)); acc[nt] = __builtin_amdgcn_mfma_f32_16x16x32_bf16(wfr, af[ks], acc[nt], 0, 0, 0); } }
	v_pk_add_f32 v[50:51], v[56:57], v[50:51]
	s_nop 0
	v_pk_mul_f32 v[56:57], v[50:51], v[50:51]
	s_nop 0
	v_fmamk_f32 v17, v57, 0xbdd2d3e7, v153
	v_mul_f32_e32 v17, v51, v17
	v_exp_f32_e32 v18, v17
	v_fmamk_f32 v10, v56, 0xbdd2d3e7, v153
	v_cvt_pk_bf16_f32 v17, v54, v55
	v_lshlrev_b32_e32 v54, 16, v11
	v_add_f32_e32 v56, 1.0, v18
	v_and_b32_e32 v55, 0xffff0000, v11
	v_lshlrev_b32_e32 v18, 16, v19
	v_and_b32_e32 v19, 0xffff0000, v19
	v_pk_add_f32 v[18:19], v[18:19], v[54:55]
	v_lshlrev_b32_e32 v54, 16, v12
	v_pk_add_f32 v[18:19], v[18:19], v[52:53]
	v_and_b32_e32 v55, 0xffff0000, v12
	v_pk_mul_f32 v[52:53], v[18:19], v[18:19]
	v_and_b32_e32 v57, 0xffff0000, v20
	v_fmamk_f32 v11, v52, 0xbdd2d3e7, v153
	v_mul_f32_e32 v11, v18, v11
	v_exp_f32_e32 v52, v11
	v_fmamk_f32 v11, v53, 0xbdd2d3e7, v153
	v_mul_f32_e32 v11, v19, v11
	v_exp_f32_e32 v53, v11
	v_rcp_f32_e32 v11, v56
	v_lshlrev_b32_e32 v56, 16, v20
	v_pk_add_f32 v[54:55], v[56:57], v[54:55]
	v_mul_f32_e32 v10, v50, v10
	v_pk_add_f32 v[34:35], v[54:55], v[34:35]
	v_exp_f32_e32 v10, v10
	v_pk_mul_f32 v[54:55], v[34:35], v[34:35]
	v_add_f32_e32 v52, 1.0, v52
	v_fmamk_f32 v20, v55, 0xbdd2d3e7, v153
	v_mul_f32_e32 v20, v35, v20
	v_exp_f32_e32 v20, v20
	v_fmamk_f32 v12, v54, 0xbdd2d3e7, v153
	v_lshlrev_b32_e32 v54, 16, v13
	v_and_b32_e32 v55, 0xffff0000, v13
	v_add_f32_e32 v56, 1.0, v20
	v_lshlrev_b32_e32 v20, 16, v21
	v_and_b32_e32 v21, 0xffff0000, v21
	v_pk_add_f32 v[20:21], v[20:21], v[54:55]
	v_mul_f32_e32 v12, v34, v12
	v_pk_add_f32 v[20:21], v[20:21], v[36:37]
	v_exp_f32_e32 v12, v12
	v_pk_mul_f32 v[36:37], v[20:21], v[20:21]
	v_add_f32_e32 v10, 1.0, v10
	v_fmamk_f32 v13, v36, 0xbdd2d3e7, v153
	v_mul_f32_e32 v13, v20, v13
	v_add_f32_e32 v53, 1.0, v53
	v_exp_f32_e32 v36, v13
	v_fmamk_f32 v13, v37, 0xbdd2d3e7, v153
	v_rcp_f32_e32 v10, v10
	v_rcp_f32_e32 v52, v52
	v_rcp_f32_e32 v53, v53
	v_add_f32_e32 v12, 1.0, v12
	v_mul_f32_e32 v13, v21, v13
	v_rcp_f32_e32 v12, v12
	v_exp_f32_e32 v37, v13
	v_rcp_f32_e32 v13, v56
	v_pk_mul_f32 v[10:11], v[50:51], v[10:11]
	v_pk_mul_f32 v[18:19], v[18:19], v[52:53]
	v_cvt_pk_bf16_f32 v10, v10, v11
	v_pk_mul_f32 v[12:13], v[34:35], v[12:13]
	v_cvt_pk_bf16_f32 v11, v18, v19
	v_lshlrev_b32_e32 v18, 16, v2
	v_and_b32_e32 v19, 0xffff0000, v2
	s_waitcnt vmcnt(2)
	v_lshlrev_b32_e32 v34, 16, v6
	v_and_b32_e32 v35, 0xffff0000, v6
	v_pk_add_f32 v[18:19], v[18:19], v[34:35]
	v_add_f32_e32 v36, 1.0, v36
	s_waitcnt lgkmcnt(0)
	v_pk_add_f32 v[18:19], v[18:19], v[38:39]
	v_add_f32_e32 v37, 1.0, v37
	v_pk_mul_f32 v[34:35], v[18:19], v[18:19]
	v_rcp_f32_e32 v36, v36
	v_fmamk_f32 v2, v34, 0xbdd2d3e7, v153
	v_mul_f32_e32 v2, v18, v2
	v_fmamk_f32 v6, v35, 0xbdd2d3e7, v153
	v_rcp_f32_e32 v37, v37
	v_exp_f32_e32 v2, v2
	v_mul_f32_e32 v6, v19, v6
	v_exp_f32_e32 v6, v6
	v_pk_mul_f32 v[20:21], v[20:21], v[36:37]
	v_add_f32_e32 v2, 1.0, v2
	v_cvt_pk_bf16_f32 v12, v12, v13
	v_cvt_pk_bf16_f32 v13, v20, v21
	v_rcp_f32_e32 v20, v2
	v_add_f32_e32 v2, 1.0, v6
	v_rcp_f32_e32 v21, v2
	v_lshlrev_b32_e32 v2, 16, v3
	v_and_b32_e32 v3, 0xffff0000, v3
	v_lshlrev_b32_e32 v6, 16, v7
	v_and_b32_e32 v7, 0xffff0000, v7
	v_pk_add_f32 v[2:3], v[2:3], v[6:7]
	v_pk_mul_f32 v[36:37], v[18:19], v[20:21]
	v_pk_add_f32 v[34:35], v[2:3], v[40:41]
	v_lshlrev_b32_e32 v6, 16, v8
	v_pk_mul_f32 v[2:3], v[34:35], v[34:35]
	v_and_b32_e32 v7, 0xffff0000, v8
	v_fmamk_f32 v2, v2, 0xbdd2d3e7, v153
	v_mul_f32_e32 v2, v34, v2
	v_fmamk_f32 v3, v3, 0xbdd2d3e7, v153
	v_exp_f32_e32 v2, v2
	v_mul_f32_e32 v3, v35, v3
	v_exp_f32_e32 v3, v3
	v_add_u32_e32 v56, s9, v114
	v_add_f32_e32 v2, 1.0, v2
	v_rcp_f32_e32 v38, v2
	v_add_f32_e32 v18, 1.0, v3
	v_lshlrev_b32_e32 v2, 16, v4
	v_and_b32_e32 v3, 0xffff0000, v4
	v_pk_add_f32 v[2:3], v[2:3], v[6:7]
	v_lshlrev_b32_e32 v4, 16, v9
	v_pk_add_f32 v[40:41], v[2:3], v[22:23]
	v_rcp_f32_e32 v39, v18
	v_pk_mul_f32 v[2:3], v[40:41], v[40:41]
	v_pk_mul_f32 v[34:35], v[34:35], v[38:39]
	v_fmamk_f32 v2, v2, 0xbdd2d3e7, v153
	v_mul_f32_e32 v2, v40, v2
	v_fmamk_f32 v3, v3, 0xbdd2d3e7, v153
	v_exp_f32_e32 v2, v2
	v_mul_f32_e32 v3, v41, v3
	v_exp_f32_e32 v3, v3
	v_add_f32_e32 v2, 1.0, v2
	v_rcp_f32_e32 v50, v2
	v_add_f32_e32 v6, 1.0, v3
	v_lshlrev_b32_e32 v2, 16, v5
	v_and_b32_e32 v3, 0xffff0000, v5
	v_and_b32_e32 v5, 0xffff0000, v9
	v_pk_add_f32 v[2:3], v[2:3], v[4:5]
	v_rcp_f32_e32 v51, v6
	v_pk_add_f32 v[52:53], v[2:3], v[24:25]
	v_add_u32_e32 v6, v56, v116
	v_pk_mul_f32 v[18:19], v[52:53], v[52:53]
	v_pk_mul_f32 v[38:39], v[40:41], v[50:51]
	v_fmamk_f32 v2, v18, 0xbdd2d3e7, v153
	v_mul_f32_e32 v2, v52, v2
	v_exp_f32_e32 v7, v2
	v_add_u32_e32 v2, v56, v115
	ds_read_b128 v[2:5], v2
	v_fmamk_f32 v22, v19, 0xbdd2d3e7, v153
	v_add_f32_e32 v18, 1.0, v7
	ds_read_b128 v[6:9], v6
	v_rcp_f32_e32 v54, v18
	v_add_u32_e32 v18, v56, v117
	ds_read_b128 v[18:21], v18
	s_waitcnt lgkmcnt(2)
	v_mfma_f32_16x16x32_bf16 v[2:5], v[2:5], v[58:61], 0
	v_mul_f32_e32 v55, v53, v22
	v_add_u32_e32 v22, v56, v118
	ds_read_b128 v[22:25], v22
	s_waitcnt lgkmcnt(2)
	v_mfma_f32_16x16x32_bf16 v[2:5], v[6:9], v[46:49], v[2:5]
	v_add_u32_e32 v6, v56, v119
	ds_read_b128 v[6:9], v6
	v_exp_f32_e32 v55, v55
	s_waitcnt lgkmcnt(2)
	v_mfma_f32_16x16x32_bf16 v[2:5], v[18:21], v[42:45], v[2:5]
	v_add_u32_e32 v18, v56, v120
	ds_read_b128 v[18:21], v18
	v_add_f32_e32 v55, 1.0, v55
	s_waitcnt lgkmcnt(2)
; #define LAS __attribute__((address_space(3)))
; DI void st8bf_(bf16_t* p, f32x4 v0, f32x4 v1) { u32x4 w; w.x = pk2(v0.x, v0.y); w.y = pk2(v0.z, v0.w); w.z = pk2(v1.x, v1.y); w.w = pk2(v1.z, v1.w); *(u32x4*)p = w; }
; #define NEXT_UNIT4() do { __syncthreads(); if (tid == 0) *UQ = (int)__hip_atomic_fetch_add(qctr, 1u, __ATOMIC_RELAXED, __HIP_MEMORY_SCOPE_AGENT); __syncthreads(); u = __builtin_amdgcn_readfirstlane(*UQ); } while (0)
; DI void w2_compute(const Args& a, LAS unsigned char* lds, int task, int lane, const u32x4 (&x0)[8], const u32x4 (&x1)[8]) {
;     ...
;     for (int nt = 0; nt < 4; ++nt) { acc[nt] = (f32x4){0.f, 0.f, 0.f, 0.f};
; #pragma unroll
;         for (int ks = 0; ks < 8; ++ks) { const bf16x8 wfr = *(const LAS bf16x8*)(wl + w2off(16 * (fr >> 2) + 4 * nt + (fr & 3), 4 * ks + fq)); acc[nt] = __builtin_amdgcn_mfma_f32_16x16x32_bf16(wfr, af[ks], acc[nt], 0, 0, 0); } }
;     bf16_t* kc = (bf16_t*)(ws + WS_KC) + ((size_t)kind * AROWS + row0 + fr) * 64 + 16 * fq;
;     st8bf_(kc, acc[0], acc[1]); st8bf_(kc + 8, acc[2], acc[3]);
; DI void p4_run(const Args& a, LAS unsigned char* lds, unsigned* qctr, const XcdBarrier& fb, unsigned* F, unsigned* F2, unsigned* F4a, unsigned* F4b) {
;     ...
;     while (u < C3) { const int v = (u - C2) % 256; w2_unit(a, lds, v, wave, lane); NEXT_UNIT4(); }
	v_mfma_f32_16x16x32_bf16 v[2:5], v[22:25], v[30:33], v[2:5]
	v_add_u32_e32 v22, v56, v121
	ds_read_b128 v[22:25], v22
	v_rcp_f32_e32 v55, v55
	s_waitcnt lgkmcnt(2)
	v_mfma_f32_16x16x32_bf16 v[2:5], v[6:9], v[26:29], v[2:5]
	v_add_u32_e32 v6, v56, v122
	ds_read_b128 v[6:9], v6
	v_add_u32_e32 v50, s9, v123
	s_waitcnt lgkmcnt(2)
	v_mfma_f32_16x16x32_bf16 v[2:5], v[18:21], v[14:17], v[2:5]
	v_add_u32_e32 v19, v50, v124
	v_pk_mul_f32 v[40:41], v[52:53], v[54:55]
	v_cvt_pk_bf16_f32 v18, v36, v37
	s_waitcnt lgkmcnt(1)
	v_mfma_f32_16x16x32_bf16 v[2:5], v[22:25], v[10:13], v[2:5]
	ds_read_b128 v[22:25], v19
	v_cvt_pk_bf16_f32 v19, v34, v35
	v_cvt_pk_bf16_f32 v20, v38, v39
	v_cvt_pk_bf16_f32 v21, v40, v41
	s_waitcnt lgkmcnt(0)
	v_mfma_f32_16x16x32_bf16 v[22:25], v[22:25], v[58:61], 0
	v_add_u32_e32 v34, v50, v126
	ds_read_b128 v[34:37], v34
	v_add_u32_e32 v54, s9, v141
	v_mfma_f32_16x16x32_bf16 v[2:5], v[6:9], v[18:21], v[2:5]
	v_add_u32_e32 v6, v50, v125
	ds_read_b128 v[6:9], v6
	s_waitcnt lgkmcnt(0)
	v_mfma_f32_16x16x32_bf16 v[6:9], v[6:9], v[46:49], v[22:25]
	s_nop 2
	v_add_u32_e32 v22, v50, v127
	ds_read_b128 v[22:25], v22
	v_cvt_pk_bf16_f32 v2, v2, v3
	v_mfma_f32_16x16x32_bf16 v[6:9], v[34:37], v[42:45], v[6:9]
	v_add_u32_e32 v34, v50, v128
	ds_read_b128 v[34:37], v34
	v_cvt_pk_bf16_f32 v3, v4, v5
	s_waitcnt lgkmcnt(1)
	v_mfma_f32_16x16x32_bf16 v[6:9], v[22:25], v[30:33], v[6:9]
	v_add_u32_e32 v22, v50, v129
	ds_read_b128 v[22:25], v22
	s_waitcnt lgkmcnt(1)
	v_mfma_f32_16x16x32_bf16 v[6:9], v[34:37], v[26:29], v[6:9]
	v_add_u32_e32 v34, v50, v130
	ds_read_b128 v[34:37], v34
	s_waitcnt lgkmcnt(1)
	v_mfma_f32_16x16x32_bf16 v[6:9], v[22:25], v[14:17], v[6:9]
	v_add_u32_e32 v22, v50, v131
	ds_read_b128 v[22:25], v22
	v_add_u32_e32 v50, s9, v132
	s_waitcnt lgkmcnt(1)
	v_mfma_f32_16x16x32_bf16 v[6:9], v[34:37], v[10:13], v[6:9]
	v_add_u32_e32 v34, v50, v133
	ds_read_b128 v[34:37], v34
	v_add_u32_e32 v38, v50, v135
	s_waitcnt lgkmcnt(1)
	v_mfma_f32_16x16x32_bf16 v[6:9], v[22:25], v[18:21], v[6:9]
	v_add_u32_e32 v22, v50, v134
	ds_read_b128 v[22:25], v22
	ds_read_b128 v[38:41], v38
	s_waitcnt lgkmcnt(2)
	v_mfma_f32_16x16x32_bf16 v[34:37], v[34:37], v[58:61], 0
	s_mul_hi_i32 s9, s8, 0x10800
	s_mul_i32 s8, s8, 0x10800
	s_add_u32 s8, s8, s11
	s_waitcnt lgkmcnt(1)
	v_mfma_f32_16x16x32_bf16 v[22:25], v[22:25], v[46:49], v[34:37]
	s_addc_u32 s9, s9, s10
	s_nop 1
	v_add_u32_e32 v34, v50, v136
	ds_read_b128 v[34:37], v34
	s_waitcnt lgkmcnt(1)
	v_mfma_f32_16x16x32_bf16 v[22:25], v[38:41], v[42:45], v[22:25]
	v_add_u32_e32 v38, v50, v137
	ds_read_b128 v[38:41], v38
	v_cvt_pk_bf16_f32 v4, v6, v7
	s_waitcnt lgkmcnt(1)
	v_mfma_f32_16x16x32_bf16 v[22:25], v[34:37], v[30:33], v[22:25]
	v_add_u32_e32 v34, v50, v138
	ds_read_b128 v[34:37], v34
	v_cvt_pk_bf16_f32 v5, v8, v9
	s_waitcnt lgkmcnt(1)
	v_mfma_f32_16x16x32_bf16 v[22:25], v[38:41], v[26:29], v[22:25]
	v_add_u32_e32 v38, v50, v139
	ds_read_b128 v[38:41], v38
	s_waitcnt lgkmcnt(1)
	v_mfma_f32_16x16x32_bf16 v[22:25], v[34:37], v[14:17], v[22:25]
	v_add_u32_e32 v34, v50, v140
	ds_read_b128 v[34:37], v34
	v_add_u32_e32 v50, v54, v144
	s_waitcnt lgkmcnt(1)
	v_mfma_f32_16x16x32_bf16 v[22:25], v[38:41], v[10:13], v[22:25]
	v_add_u32_e32 v38, v54, v142
	ds_read_b128 v[38:41], v38
	ds_read_b128 v[50:53], v50
	s_waitcnt lgkmcnt(2)
	v_mfma_f32_16x16x32_bf16 v[22:25], v[34:37], v[18:21], v[22:25]
	v_add_u32_e32 v34, v54, v143
	ds_read_b128 v[34:37], v34
	s_waitcnt lgkmcnt(2)
	v_mfma_f32_16x16x32_bf16 v[38:41], v[38:41], v[58:61], 0
	s_waitcnt lgkmcnt(0)
	v_mfma_f32_16x16x32_bf16 v[34:37], v[34:37], v[46:49], v[38:41]
	s_nop 5
	v_add_u32_e32 v38, v54, v145
	ds_read_b128 v[38:41], v38
	v_mfma_f32_16x16x32_bf16 v[34:37], v[50:53], v[42:45], v[34:37]
	v_add_u32_e32 v42, v54, v146
	ds_read_b128 v[42:45], v42
	s_waitcnt lgkmcnt(1)
	v_mfma_f32_16x16x32_bf16 v[30:33], v[38:41], v[30:33], v[34:37]
	s_nop 3
	v_add_u32_e32 v34, v54, v147
	ds_read_b128 v[34:37], v34
	s_waitcnt lgkmcnt(1)
	v_mfma_f32_16x16x32_bf16 v[26:29], v[42:45], v[26:29], v[30:33]
	s_nop 2
	v_add_u32_e32 v30, v54, v148
	ds_read_b128 v[30:33], v30
	s_waitcnt lgkmcnt(1)
	v_mfma_f32_16x16x32_bf16 v[14:17], v[34:37], v[14:17], v[26:29]
	s_nop 2
	v_add_u32_e32 v26, v54, v149
	ds_read_b128 v[26:29], v26
	s_waitcnt lgkmcnt(1)
	v_mfma_f32_16x16x32_bf16 v[10:13], v[30:33], v[10:13], v[14:17]
	s_nop 2
	v_mov_b32_e32 v15, s9
	v_or_b32_e32 v14, s8, v1
	s_waitcnt lgkmcnt(0)
	v_mfma_f32_16x16x32_bf16 v[10:13], v[26:29], v[18:21], v[10:13]
	v_lshlrev_b64 v[14:15], 7, v[14:15]
	v_lshl_add_u64 v[14:15], v[108:109], 0, v[14:15]
	global_store_dwordx4 v[14:15], v[2:5], off
	s_nop 1
	v_cvt_pk_bf16_f32 v2, v22, v23
	v_cvt_pk_bf16_f32 v3, v24, v25
	s_nop 0
	v_cvt_pk_bf16_f32 v4, v10, v11
	v_cvt_pk_bf16_f32 v5, v12, v13
	global_store_dwordx4 v[14:15], v[2:5], off offset:16
	s_barrier
	s_and_saveexec_b64 s[10:11], s[0:1]
	s_cbranch_execz .LBB0_1358
	s_mov_b64 s[16:17], exec
	v_mbcnt_lo_u32_b32 v2, s16, 0
	v_mbcnt_hi_u32_b32 v2, s17, v2
	v_cmp_eq_u32_e64 s[8:9], 0, v2
	s_and_saveexec_b64 s[12:13], s[8:9]
	s_cbranch_execz .LBB0_1357
	s_bcnt1_i32_b64 s8, s[16:17]
	v_mov_b32_e32 v3, s8
	global_atomic_add v3, v103, v3, s[26:27] offset:768 sc0
	s_branch .LBB0_1357
